# V pass sweeps token pairs chunk-major (each table slice serves two tokens)
# speedup vs baseline: 1.0129x; 1.0021x over previous
.LBB0_2055:
	s_mul_i32 s42, s64, s48
	v_add_u32_e32 v152, s42, v123
	v_cmp_gt_i32_e32 vcc, s33, v152
	s_and_saveexec_b64 s[42:43], vcc
	s_cbranch_execz .LBB0_2054
	s_and_b32 s44, s64, 1
	s_cbranch_scc1 .Lp10v_odd
	s_lshl_b32 s44, s64, 10
	v_add3_u32 v0, v157, s44, v112
	ds_read_b64 v[154:155], v0 offset:8704
	s_waitcnt lgkmcnt(0)
	v_mov_b32_e32 v24, 0
	s_mov_b32 s65, -16
	s_mov_b32 s66, 7
	v_mov_b32_e32 v131, v129
	v_mov_b32_e32 v25, v24
	v_mov_b32_e32 v26, v24
	v_mov_b32_e32 v27, v24
	v_mov_b32_e32 v40, v24
	v_mov_b32_e32 v41, v24
	v_mov_b32_e32 v42, v24
	v_mov_b32_e32 v43, v24
	v_mov_b32_e32 v36, v24
	v_mov_b32_e32 v37, v24
	v_mov_b32_e32 v38, v24
	v_mov_b32_e32 v39, v24
	v_mov_b32_e32 v4, v24
	v_mov_b32_e32 v5, v24
	v_mov_b32_e32 v6, v24
	v_mov_b32_e32 v7, v24
	v_mov_b32_e32 v32, v24
	v_mov_b32_e32 v33, v24
	v_mov_b32_e32 v34, v24
	v_mov_b32_e32 v35, v24
	v_mov_b32_e32 v28, v24
	v_mov_b32_e32 v29, v24
	v_mov_b32_e32 v30, v24
	v_mov_b32_e32 v31, v24
	v_mov_b32_e32 v20, v24
	v_mov_b32_e32 v21, v24
	v_mov_b32_e32 v22, v24
	v_mov_b32_e32 v23, v24
	v_mov_b32_e32 v0, v24
	v_mov_b32_e32 v1, v24
	v_mov_b32_e32 v2, v24
	v_mov_b32_e32 v3, v24
	s_cmp_lt_u32 s64, 8
	s_cbranch_scc1 .Lp10v_pair
	s_add_i32 s45, s66, -7
	v_readlane_b32 s44, v154, s45
	s_lshl_b32 s44, s44, 10
	s_add_u32 s46, s92, s44
	s_addc_u32 s47, s93, 0
	global_load_dwordx4 v[44:47], v216, s[46:47]
	v_readlane_b32 s44, v155, s45
	s_lshl_b32 s44, s44, 10
	s_add_u32 s46, s92, s44
	s_addc_u32 s47, s93, 0
	global_load_dwordx4 v[48:51], v216, s[46:47]
	s_add_i32 s45, s66, -6
	v_readlane_b32 s44, v154, s45
	s_lshl_b32 s44, s44, 10
	s_add_u32 s46, s92, s44
	s_addc_u32 s47, s93, 0
	global_load_dwordx4 v[52:55], v216, s[46:47]
	v_readlane_b32 s44, v155, s45
	s_lshl_b32 s44, s44, 10
	s_add_u32 s46, s92, s44
	s_addc_u32 s47, s93, 0
	global_load_dwordx4 v[56:59], v216, s[46:47]
	s_add_i32 s45, s66, -5
	v_readlane_b32 s44, v154, s45
	s_lshl_b32 s44, s44, 10
	s_add_u32 s46, s92, s44
	s_addc_u32 s47, s93, 0
	global_load_dwordx4 v[60:63], v216, s[46:47]
	v_readlane_b32 s44, v155, s45
	s_lshl_b32 s44, s44, 10
	s_add_u32 s46, s92, s44
	s_addc_u32 s47, s93, 0
	global_load_dwordx4 v[76:79], v216, s[46:47]
	s_add_i32 s45, s66, -4
	v_readlane_b32 s44, v154, s45
	s_lshl_b32 s44, s44, 10
	s_add_u32 s46, s92, s44
	s_addc_u32 s47, s93, 0
	global_load_dwordx4 v[80:83], v216, s[46:47]
	v_readlane_b32 s44, v155, s45
	s_lshl_b32 s44, s44, 10
	s_add_u32 s46, s92, s44
	s_addc_u32 s47, s93, 0
	global_load_dwordx4 v[84:87], v216, s[46:47]
	s_add_i32 s45, s66, -3
	v_readlane_b32 s44, v154, s45
	s_lshl_b32 s44, s44, 10
	s_add_u32 s46, s92, s44
	s_addc_u32 s47, s93, 0
	global_load_dwordx4 v[88:91], v216, s[46:47]
	v_readlane_b32 s44, v155, s45
	s_lshl_b32 s44, s44, 10
	s_add_u32 s46, s92, s44
	s_addc_u32 s47, s93, 0
	global_load_dwordx4 v[92:95], v216, s[46:47]
	s_add_i32 s45, s66, -2
	v_readlane_b32 s44, v154, s45
	s_lshl_b32 s44, s44, 10
	s_add_u32 s46, s92, s44
	s_addc_u32 s47, s93, 0
	global_load_dwordx4 v[96:99], v216, s[46:47]
	v_readlane_b32 s44, v155, s45
	s_lshl_b32 s44, s44, 10
	s_add_u32 s46, s92, s44
	s_addc_u32 s47, s93, 0
	global_load_dwordx4 v[100:103], v216, s[46:47]
	s_add_i32 s45, s66, -1
	v_readlane_b32 s44, v154, s45
	s_lshl_b32 s44, s44, 10
	s_add_u32 s46, s92, s44
	s_addc_u32 s47, s93, 0
	global_load_dwordx4 v[172:175], v216, s[46:47]
	v_readlane_b32 s44, v155, s45
	s_lshl_b32 s44, s44, 10
	s_add_u32 s46, s92, s44
	s_addc_u32 s47, s93, 0
	global_load_dwordx4 v[176:179], v216, s[46:47]
	s_add_i32 s45, s66, 0
	v_readlane_b32 s44, v154, s45
	s_lshl_b32 s44, s44, 10
	s_add_u32 s46, s92, s44
	s_addc_u32 s47, s93, 0
	global_load_dwordx4 v[180:183], v216, s[46:47]
	v_readlane_b32 s44, v155, s45
	s_lshl_b32 s44, s44, 10
	s_add_u32 s46, s92, s44
	s_addc_u32 s47, s93, 0
	global_load_dwordx4 v[184:187], v216, s[46:47]
	ds_read_b128 v[188:191], v131 offset:0
	ds_read_b128 v[192:195], v131 offset:16
	ds_read_b128 v[240:243], v131 offset:32
	ds_read_b128 v[244:247], v131 offset:48
.Lp10v_loop:
	s_waitcnt vmcnt(15) lgkmcnt(3)
	v_cvt_scalef32_pk_f32_fp4 v[8:9], v44, 1.0
	v_cvt_scalef32_pk_f32_fp4 v[10:11], v44, 1.0 op_sel:[1,0,0]
	v_cvt_scalef32_pk_f32_fp4 v[12:13], v44, 1.0 op_sel:[0,1,0]
	v_cvt_scalef32_pk_f32_fp4 v[14:15], v44, 1.0 op_sel:[1,1,0]
	v_cvt_scalef32_pk_f32_fp4 v[16:17], v45, 1.0
	v_cvt_scalef32_pk_f32_fp4 v[18:19], v45, 1.0 op_sel:[1,0,0]
	v_cvt_scalef32_pk_f32_fp4 v[64:65], v45, 1.0 op_sel:[0,1,0]
	v_cvt_scalef32_pk_f32_fp4 v[66:67], v45, 1.0 op_sel:[1,1,0]
	v_pk_fma_f32 v[24:25], v[8:9], v[188:189], v[24:25] op_sel_hi:[1,0,1]
	v_pk_fma_f32 v[26:27], v[10:11], v[188:189], v[26:27] op_sel_hi:[1,0,1]
	v_pk_fma_f32 v[40:41], v[12:13], v[188:189], v[40:41] op_sel_hi:[1,0,1]
	v_pk_fma_f32 v[42:43], v[14:15], v[188:189], v[42:43] op_sel_hi:[1,0,1]
	v_cvt_scalef32_pk_f32_fp4 v[68:69], v46, 1.0
	v_cvt_scalef32_pk_f32_fp4 v[70:71], v46, 1.0 op_sel:[1,0,0]
	v_cvt_scalef32_pk_f32_fp4 v[72:73], v46, 1.0 op_sel:[0,1,0]
	v_cvt_scalef32_pk_f32_fp4 v[74:75], v46, 1.0 op_sel:[1,1,0]
	v_pk_fma_f32 v[36:37], v[16:17], v[188:189], v[36:37] op_sel_hi:[1,0,1]
	v_pk_fma_f32 v[38:39], v[18:19], v[188:189], v[38:39] op_sel_hi:[1,0,1]
	v_pk_fma_f32 v[4:5], v[64:65], v[188:189], v[4:5] op_sel_hi:[1,0,1]
	v_pk_fma_f32 v[6:7], v[66:67], v[188:189], v[6:7] op_sel_hi:[1,0,1]
	v_cvt_scalef32_pk_f32_fp4 v[8:9], v47, 1.0
	v_cvt_scalef32_pk_f32_fp4 v[10:11], v47, 1.0 op_sel:[1,0,0]
	v_cvt_scalef32_pk_f32_fp4 v[12:13], v47, 1.0 op_sel:[0,1,0]
	v_cvt_scalef32_pk_f32_fp4 v[14:15], v47, 1.0 op_sel:[1,1,0]
	v_pk_fma_f32 v[32:33], v[68:69], v[188:189], v[32:33] op_sel_hi:[1,0,1]
	v_pk_fma_f32 v[34:35], v[70:71], v[188:189], v[34:35] op_sel_hi:[1,0,1]
	v_pk_fma_f32 v[28:29], v[72:73], v[188:189], v[28:29] op_sel_hi:[1,0,1]
	v_pk_fma_f32 v[30:31], v[74:75], v[188:189], v[30:31] op_sel_hi:[1,0,1]
	v_pk_fma_f32 v[20:21], v[8:9], v[188:189], v[20:21] op_sel_hi:[1,0,1]
	v_pk_fma_f32 v[22:23], v[10:11], v[188:189], v[22:23] op_sel_hi:[1,0,1]
	v_pk_fma_f32 v[0:1], v[12:13], v[188:189], v[0:1] op_sel_hi:[1,0,1]
	v_pk_fma_f32 v[2:3], v[14:15], v[188:189], v[2:3] op_sel_hi:[1,0,1]
	s_add_i32 s45, s66, 1
	v_readlane_b32 s44, v154, s45
	s_lshl_b32 s44, s44, 10
	s_add_u32 s46, s92, s44
	s_addc_u32 s47, s93, 0
	global_load_dwordx4 v[44:47], v216, s[46:47]
	s_waitcnt vmcnt(15)
	v_cvt_scalef32_pk_f32_fp4 v[8:9], v48, 1.0
	v_cvt_scalef32_pk_f32_fp4 v[10:11], v48, 1.0 op_sel:[1,0,0]
	v_cvt_scalef32_pk_f32_fp4 v[12:13], v48, 1.0 op_sel:[0,1,0]
	v_cvt_scalef32_pk_f32_fp4 v[14:15], v48, 1.0 op_sel:[1,1,0]
	v_cvt_scalef32_pk_f32_fp4 v[16:17], v49, 1.0
	v_cvt_scalef32_pk_f32_fp4 v[18:19], v49, 1.0 op_sel:[1,0,0]
	v_cvt_scalef32_pk_f32_fp4 v[64:65], v49, 1.0 op_sel:[0,1,0]
	v_cvt_scalef32_pk_f32_fp4 v[66:67], v49, 1.0 op_sel:[1,1,0]
	v_pk_fma_f32 v[24:25], v[8:9], v[188:189], v[24:25] op_sel:[0,1,0]
	v_pk_fma_f32 v[26:27], v[10:11], v[188:189], v[26:27] op_sel:[0,1,0]
	v_pk_fma_f32 v[40:41], v[12:13], v[188:189], v[40:41] op_sel:[0,1,0]
	v_pk_fma_f32 v[42:43], v[14:15], v[188:189], v[42:43] op_sel:[0,1,0]
	v_cvt_scalef32_pk_f32_fp4 v[68:69], v50, 1.0
	v_cvt_scalef32_pk_f32_fp4 v[70:71], v50, 1.0 op_sel:[1,0,0]
	v_cvt_scalef32_pk_f32_fp4 v[72:73], v50, 1.0 op_sel:[0,1,0]
	v_cvt_scalef32_pk_f32_fp4 v[74:75], v50, 1.0 op_sel:[1,1,0]
	v_pk_fma_f32 v[36:37], v[16:17], v[188:189], v[36:37] op_sel:[0,1,0]
	v_pk_fma_f32 v[38:39], v[18:19], v[188:189], v[38:39] op_sel:[0,1,0]
	v_pk_fma_f32 v[4:5], v[64:65], v[188:189], v[4:5] op_sel:[0,1,0]
	v_pk_fma_f32 v[6:7], v[66:67], v[188:189], v[6:7] op_sel:[0,1,0]
	v_cvt_scalef32_pk_f32_fp4 v[8:9], v51, 1.0
	v_cvt_scalef32_pk_f32_fp4 v[10:11], v51, 1.0 op_sel:[1,0,0]
	v_cvt_scalef32_pk_f32_fp4 v[12:13], v51, 1.0 op_sel:[0,1,0]
	v_cvt_scalef32_pk_f32_fp4 v[14:15], v51, 1.0 op_sel:[1,1,0]
	v_pk_fma_f32 v[32:33], v[68:69], v[188:189], v[32:33] op_sel:[0,1,0]
	v_pk_fma_f32 v[34:35], v[70:71], v[188:189], v[34:35] op_sel:[0,1,0]
	v_pk_fma_f32 v[28:29], v[72:73], v[188:189], v[28:29] op_sel:[0,1,0]
	v_pk_fma_f32 v[30:31], v[74:75], v[188:189], v[30:31] op_sel:[0,1,0]
	v_pk_fma_f32 v[20:21], v[8:9], v[188:189], v[20:21] op_sel:[0,1,0]
	v_pk_fma_f32 v[22:23], v[10:11], v[188:189], v[22:23] op_sel:[0,1,0]
	v_pk_fma_f32 v[0:1], v[12:13], v[188:189], v[0:1] op_sel:[0,1,0]
	v_pk_fma_f32 v[2:3], v[14:15], v[188:189], v[2:3] op_sel:[0,1,0]
	v_readlane_b32 s44, v155, s45
	s_lshl_b32 s44, s44, 10
	s_add_u32 s46, s92, s44
	s_addc_u32 s47, s93, 0
	global_load_dwordx4 v[48:51], v216, s[46:47]
	s_waitcnt vmcnt(15)
	v_cvt_scalef32_pk_f32_fp4 v[8:9], v52, 1.0
	v_cvt_scalef32_pk_f32_fp4 v[10:11], v52, 1.0 op_sel:[1,0,0]
	v_cvt_scalef32_pk_f32_fp4 v[12:13], v52, 1.0 op_sel:[0,1,0]
	v_cvt_scalef32_pk_f32_fp4 v[14:15], v52, 1.0 op_sel:[1,1,0]
	v_cvt_scalef32_pk_f32_fp4 v[16:17], v53, 1.0
	v_cvt_scalef32_pk_f32_fp4 v[18:19], v53, 1.0 op_sel:[1,0,0]
	v_cvt_scalef32_pk_f32_fp4 v[64:65], v53, 1.0 op_sel:[0,1,0]
	v_cvt_scalef32_pk_f32_fp4 v[66:67], v53, 1.0 op_sel:[1,1,0]
	v_pk_fma_f32 v[24:25], v[8:9], v[190:191], v[24:25] op_sel_hi:[1,0,1]
	v_pk_fma_f32 v[26:27], v[10:11], v[190:191], v[26:27] op_sel_hi:[1,0,1]
	v_pk_fma_f32 v[40:41], v[12:13], v[190:191], v[40:41] op_sel_hi:[1,0,1]
	v_pk_fma_f32 v[42:43], v[14:15], v[190:191], v[42:43] op_sel_hi:[1,0,1]
	v_cvt_scalef32_pk_f32_fp4 v[68:69], v54, 1.0
	v_cvt_scalef32_pk_f32_fp4 v[70:71], v54, 1.0 op_sel:[1,0,0]
	v_cvt_scalef32_pk_f32_fp4 v[72:73], v54, 1.0 op_sel:[0,1,0]
	v_cvt_scalef32_pk_f32_fp4 v[74:75], v54, 1.0 op_sel:[1,1,0]
	v_pk_fma_f32 v[36:37], v[16:17], v[190:191], v[36:37] op_sel_hi:[1,0,1]
	v_pk_fma_f32 v[38:39], v[18:19], v[190:191], v[38:39] op_sel_hi:[1,0,1]
	v_pk_fma_f32 v[4:5], v[64:65], v[190:191], v[4:5] op_sel_hi:[1,0,1]
	v_pk_fma_f32 v[6:7], v[66:67], v[190:191], v[6:7] op_sel_hi:[1,0,1]
	v_cvt_scalef32_pk_f32_fp4 v[8:9], v55, 1.0
	v_cvt_scalef32_pk_f32_fp4 v[10:11], v55, 1.0 op_sel:[1,0,0]
	v_cvt_scalef32_pk_f32_fp4 v[12:13], v55, 1.0 op_sel:[0,1,0]
	v_cvt_scalef32_pk_f32_fp4 v[14:15], v55, 1.0 op_sel:[1,1,0]
	v_pk_fma_f32 v[32:33], v[68:69], v[190:191], v[32:33] op_sel_hi:[1,0,1]
	v_pk_fma_f32 v[34:35], v[70:71], v[190:191], v[34:35] op_sel_hi:[1,0,1]
	v_pk_fma_f32 v[28:29], v[72:73], v[190:191], v[28:29] op_sel_hi:[1,0,1]
	v_pk_fma_f32 v[30:31], v[74:75], v[190:191], v[30:31] op_sel_hi:[1,0,1]
	v_pk_fma_f32 v[20:21], v[8:9], v[190:191], v[20:21] op_sel_hi:[1,0,1]
	v_pk_fma_f32 v[22:23], v[10:11], v[190:191], v[22:23] op_sel_hi:[1,0,1]
	v_pk_fma_f32 v[0:1], v[12:13], v[190:191], v[0:1] op_sel_hi:[1,0,1]
	v_pk_fma_f32 v[2:3], v[14:15], v[190:191], v[2:3] op_sel_hi:[1,0,1]
	s_add_i32 s45, s66, 2
	v_readlane_b32 s44, v154, s45
	s_lshl_b32 s44, s44, 10
	s_add_u32 s46, s92, s44
	s_addc_u32 s47, s93, 0
	global_load_dwordx4 v[52:55], v216, s[46:47]
	s_waitcnt vmcnt(15)
	v_cvt_scalef32_pk_f32_fp4 v[8:9], v56, 1.0
	v_cvt_scalef32_pk_f32_fp4 v[10:11], v56, 1.0 op_sel:[1,0,0]
	v_cvt_scalef32_pk_f32_fp4 v[12:13], v56, 1.0 op_sel:[0,1,0]
	v_cvt_scalef32_pk_f32_fp4 v[14:15], v56, 1.0 op_sel:[1,1,0]
	v_cvt_scalef32_pk_f32_fp4 v[16:17], v57, 1.0
	v_cvt_scalef32_pk_f32_fp4 v[18:19], v57, 1.0 op_sel:[1,0,0]
	v_cvt_scalef32_pk_f32_fp4 v[64:65], v57, 1.0 op_sel:[0,1,0]
	v_cvt_scalef32_pk_f32_fp4 v[66:67], v57, 1.0 op_sel:[1,1,0]
	v_pk_fma_f32 v[24:25], v[8:9], v[190:191], v[24:25] op_sel:[0,1,0]
	v_pk_fma_f32 v[26:27], v[10:11], v[190:191], v[26:27] op_sel:[0,1,0]
	v_pk_fma_f32 v[40:41], v[12:13], v[190:191], v[40:41] op_sel:[0,1,0]
	v_pk_fma_f32 v[42:43], v[14:15], v[190:191], v[42:43] op_sel:[0,1,0]
	v_cvt_scalef32_pk_f32_fp4 v[68:69], v58, 1.0
	v_cvt_scalef32_pk_f32_fp4 v[70:71], v58, 1.0 op_sel:[1,0,0]
	v_cvt_scalef32_pk_f32_fp4 v[72:73], v58, 1.0 op_sel:[0,1,0]
	v_cvt_scalef32_pk_f32_fp4 v[74:75], v58, 1.0 op_sel:[1,1,0]
	v_pk_fma_f32 v[36:37], v[16:17], v[190:191], v[36:37] op_sel:[0,1,0]
	v_pk_fma_f32 v[38:39], v[18:19], v[190:191], v[38:39] op_sel:[0,1,0]
	v_pk_fma_f32 v[4:5], v[64:65], v[190:191], v[4:5] op_sel:[0,1,0]
	v_pk_fma_f32 v[6:7], v[66:67], v[190:191], v[6:7] op_sel:[0,1,0]
	v_cvt_scalef32_pk_f32_fp4 v[8:9], v59, 1.0
	v_cvt_scalef32_pk_f32_fp4 v[10:11], v59, 1.0 op_sel:[1,0,0]
	v_cvt_scalef32_pk_f32_fp4 v[12:13], v59, 1.0 op_sel:[0,1,0]
	v_cvt_scalef32_pk_f32_fp4 v[14:15], v59, 1.0 op_sel:[1,1,0]
	v_pk_fma_f32 v[32:33], v[68:69], v[190:191], v[32:33] op_sel:[0,1,0]
	v_pk_fma_f32 v[34:35], v[70:71], v[190:191], v[34:35] op_sel:[0,1,0]
	v_pk_fma_f32 v[28:29], v[72:73], v[190:191], v[28:29] op_sel:[0,1,0]
	v_pk_fma_f32 v[30:31], v[74:75], v[190:191], v[30:31] op_sel:[0,1,0]
	v_pk_fma_f32 v[20:21], v[8:9], v[190:191], v[20:21] op_sel:[0,1,0]
	v_pk_fma_f32 v[22:23], v[10:11], v[190:191], v[22:23] op_sel:[0,1,0]
	v_pk_fma_f32 v[0:1], v[12:13], v[190:191], v[0:1] op_sel:[0,1,0]
	v_pk_fma_f32 v[2:3], v[14:15], v[190:191], v[2:3] op_sel:[0,1,0]
	v_readlane_b32 s44, v155, s45
	s_lshl_b32 s44, s44, 10
	s_add_u32 s46, s92, s44
	s_addc_u32 s47, s93, 0
	global_load_dwordx4 v[56:59], v216, s[46:47]
	ds_read_b128 v[188:191], v131 offset:64
	s_waitcnt vmcnt(15) lgkmcnt(3)
	v_cvt_scalef32_pk_f32_fp4 v[8:9], v60, 1.0
	v_cvt_scalef32_pk_f32_fp4 v[10:11], v60, 1.0 op_sel:[1,0,0]
	v_cvt_scalef32_pk_f32_fp4 v[12:13], v60, 1.0 op_sel:[0,1,0]
	v_cvt_scalef32_pk_f32_fp4 v[14:15], v60, 1.0 op_sel:[1,1,0]
	v_cvt_scalef32_pk_f32_fp4 v[16:17], v61, 1.0
	v_cvt_scalef32_pk_f32_fp4 v[18:19], v61, 1.0 op_sel:[1,0,0]
	v_cvt_scalef32_pk_f32_fp4 v[64:65], v61, 1.0 op_sel:[0,1,0]
	v_cvt_scalef32_pk_f32_fp4 v[66:67], v61, 1.0 op_sel:[1,1,0]
	v_pk_fma_f32 v[24:25], v[8:9], v[192:193], v[24:25] op_sel_hi:[1,0,1]
	v_pk_fma_f32 v[26:27], v[10:11], v[192:193], v[26:27] op_sel_hi:[1,0,1]
	v_pk_fma_f32 v[40:41], v[12:13], v[192:193], v[40:41] op_sel_hi:[1,0,1]
	v_pk_fma_f32 v[42:43], v[14:15], v[192:193], v[42:43] op_sel_hi:[1,0,1]
	v_cvt_scalef32_pk_f32_fp4 v[68:69], v62, 1.0
	v_cvt_scalef32_pk_f32_fp4 v[70:71], v62, 1.0 op_sel:[1,0,0]
	v_cvt_scalef32_pk_f32_fp4 v[72:73], v62, 1.0 op_sel:[0,1,0]
	v_cvt_scalef32_pk_f32_fp4 v[74:75], v62, 1.0 op_sel:[1,1,0]
	v_pk_fma_f32 v[36:37], v[16:17], v[192:193], v[36:37] op_sel_hi:[1,0,1]
	v_pk_fma_f32 v[38:39], v[18:19], v[192:193], v[38:39] op_sel_hi:[1,0,1]
	v_pk_fma_f32 v[4:5], v[64:65], v[192:193], v[4:5] op_sel_hi:[1,0,1]
	v_pk_fma_f32 v[6:7], v[66:67], v[192:193], v[6:7] op_sel_hi:[1,0,1]
	v_cvt_scalef32_pk_f32_fp4 v[8:9], v63, 1.0
	v_cvt_scalef32_pk_f32_fp4 v[10:11], v63, 1.0 op_sel:[1,0,0]
	v_cvt_scalef32_pk_f32_fp4 v[12:13], v63, 1.0 op_sel:[0,1,0]
	v_cvt_scalef32_pk_f32_fp4 v[14:15], v63, 1.0 op_sel:[1,1,0]
	v_pk_fma_f32 v[32:33], v[68:69], v[192:193], v[32:33] op_sel_hi:[1,0,1]
	v_pk_fma_f32 v[34:35], v[70:71], v[192:193], v[34:35] op_sel_hi:[1,0,1]
	v_pk_fma_f32 v[28:29], v[72:73], v[192:193], v[28:29] op_sel_hi:[1,0,1]
	v_pk_fma_f32 v[30:31], v[74:75], v[192:193], v[30:31] op_sel_hi:[1,0,1]
	v_pk_fma_f32 v[20:21], v[8:9], v[192:193], v[20:21] op_sel_hi:[1,0,1]
	v_pk_fma_f32 v[22:23], v[10:11], v[192:193], v[22:23] op_sel_hi:[1,0,1]
	v_pk_fma_f32 v[0:1], v[12:13], v[192:193], v[0:1] op_sel_hi:[1,0,1]
	v_pk_fma_f32 v[2:3], v[14:15], v[192:193], v[2:3] op_sel_hi:[1,0,1]
	s_add_i32 s45, s66, 3
	v_readlane_b32 s44, v154, s45
	s_lshl_b32 s44, s44, 10
	s_add_u32 s46, s92, s44
	s_addc_u32 s47, s93, 0
	global_load_dwordx4 v[60:63], v216, s[46:47]
	s_waitcnt vmcnt(15)
	v_cvt_scalef32_pk_f32_fp4 v[8:9], v76, 1.0
	v_cvt_scalef32_pk_f32_fp4 v[10:11], v76, 1.0 op_sel:[1,0,0]
	v_cvt_scalef32_pk_f32_fp4 v[12:13], v76, 1.0 op_sel:[0,1,0]
	v_cvt_scalef32_pk_f32_fp4 v[14:15], v76, 1.0 op_sel:[1,1,0]
	v_cvt_scalef32_pk_f32_fp4 v[16:17], v77, 1.0
	v_cvt_scalef32_pk_f32_fp4 v[18:19], v77, 1.0 op_sel:[1,0,0]
	v_cvt_scalef32_pk_f32_fp4 v[64:65], v77, 1.0 op_sel:[0,1,0]
	v_cvt_scalef32_pk_f32_fp4 v[66:67], v77, 1.0 op_sel:[1,1,0]
	v_pk_fma_f32 v[24:25], v[8:9], v[192:193], v[24:25] op_sel:[0,1,0]
	v_pk_fma_f32 v[26:27], v[10:11], v[192:193], v[26:27] op_sel:[0,1,0]
	v_pk_fma_f32 v[40:41], v[12:13], v[192:193], v[40:41] op_sel:[0,1,0]
	v_pk_fma_f32 v[42:43], v[14:15], v[192:193], v[42:43] op_sel:[0,1,0]
	v_cvt_scalef32_pk_f32_fp4 v[68:69], v78, 1.0
	v_cvt_scalef32_pk_f32_fp4 v[70:71], v78, 1.0 op_sel:[1,0,0]
	v_cvt_scalef32_pk_f32_fp4 v[72:73], v78, 1.0 op_sel:[0,1,0]
	v_cvt_scalef32_pk_f32_fp4 v[74:75], v78, 1.0 op_sel:[1,1,0]
	v_pk_fma_f32 v[36:37], v[16:17], v[192:193], v[36:37] op_sel:[0,1,0]
	v_pk_fma_f32 v[38:39], v[18:19], v[192:193], v[38:39] op_sel:[0,1,0]
	v_pk_fma_f32 v[4:5], v[64:65], v[192:193], v[4:5] op_sel:[0,1,0]
	v_pk_fma_f32 v[6:7], v[66:67], v[192:193], v[6:7] op_sel:[0,1,0]
	v_cvt_scalef32_pk_f32_fp4 v[8:9], v79, 1.0
	v_cvt_scalef32_pk_f32_fp4 v[10:11], v79, 1.0 op_sel:[1,0,0]
	v_cvt_scalef32_pk_f32_fp4 v[12:13], v79, 1.0 op_sel:[0,1,0]
	v_cvt_scalef32_pk_f32_fp4 v[14:15], v79, 1.0 op_sel:[1,1,0]
	v_pk_fma_f32 v[32:33], v[68:69], v[192:193], v[32:33] op_sel:[0,1,0]
	v_pk_fma_f32 v[34:35], v[70:71], v[192:193], v[34:35] op_sel:[0,1,0]
	v_pk_fma_f32 v[28:29], v[72:73], v[192:193], v[28:29] op_sel:[0,1,0]
	v_pk_fma_f32 v[30:31], v[74:75], v[192:193], v[30:31] op_sel:[0,1,0]
	v_pk_fma_f32 v[20:21], v[8:9], v[192:193], v[20:21] op_sel:[0,1,0]
	v_pk_fma_f32 v[22:23], v[10:11], v[192:193], v[22:23] op_sel:[0,1,0]
	v_pk_fma_f32 v[0:1], v[12:13], v[192:193], v[0:1] op_sel:[0,1,0]
	v_pk_fma_f32 v[2:3], v[14:15], v[192:193], v[2:3] op_sel:[0,1,0]
	v_readlane_b32 s44, v155, s45
	s_lshl_b32 s44, s44, 10
	s_add_u32 s46, s92, s44
	s_addc_u32 s47, s93, 0
	global_load_dwordx4 v[76:79], v216, s[46:47]
	s_waitcnt vmcnt(15)
	v_cvt_scalef32_pk_f32_fp4 v[8:9], v80, 1.0
	v_cvt_scalef32_pk_f32_fp4 v[10:11], v80, 1.0 op_sel:[1,0,0]
	v_cvt_scalef32_pk_f32_fp4 v[12:13], v80, 1.0 op_sel:[0,1,0]
	v_cvt_scalef32_pk_f32_fp4 v[14:15], v80, 1.0 op_sel:[1,1,0]
	v_cvt_scalef32_pk_f32_fp4 v[16:17], v81, 1.0
	v_cvt_scalef32_pk_f32_fp4 v[18:19], v81, 1.0 op_sel:[1,0,0]
	v_cvt_scalef32_pk_f32_fp4 v[64:65], v81, 1.0 op_sel:[0,1,0]
	v_cvt_scalef32_pk_f32_fp4 v[66:67], v81, 1.0 op_sel:[1,1,0]
	v_pk_fma_f32 v[24:25], v[8:9], v[194:195], v[24:25] op_sel_hi:[1,0,1]
	v_pk_fma_f32 v[26:27], v[10:11], v[194:195], v[26:27] op_sel_hi:[1,0,1]
	v_pk_fma_f32 v[40:41], v[12:13], v[194:195], v[40:41] op_sel_hi:[1,0,1]
	v_pk_fma_f32 v[42:43], v[14:15], v[194:195], v[42:43] op_sel_hi:[1,0,1]
	v_cvt_scalef32_pk_f32_fp4 v[68:69], v82, 1.0
	v_cvt_scalef32_pk_f32_fp4 v[70:71], v82, 1.0 op_sel:[1,0,0]
	v_cvt_scalef32_pk_f32_fp4 v[72:73], v82, 1.0 op_sel:[0,1,0]
	v_cvt_scalef32_pk_f32_fp4 v[74:75], v82, 1.0 op_sel:[1,1,0]
	v_pk_fma_f32 v[36:37], v[16:17], v[194:195], v[36:37] op_sel_hi:[1,0,1]
	v_pk_fma_f32 v[38:39], v[18:19], v[194:195], v[38:39] op_sel_hi:[1,0,1]
	v_pk_fma_f32 v[4:5], v[64:65], v[194:195], v[4:5] op_sel_hi:[1,0,1]
	v_pk_fma_f32 v[6:7], v[66:67], v[194:195], v[6:7] op_sel_hi:[1,0,1]
	v_cvt_scalef32_pk_f32_fp4 v[8:9], v83, 1.0
	v_cvt_scalef32_pk_f32_fp4 v[10:11], v83, 1.0 op_sel:[1,0,0]
	v_cvt_scalef32_pk_f32_fp4 v[12:13], v83, 1.0 op_sel:[0,1,0]
	v_cvt_scalef32_pk_f32_fp4 v[14:15], v83, 1.0 op_sel:[1,1,0]
	v_pk_fma_f32 v[32:33], v[68:69], v[194:195], v[32:33] op_sel_hi:[1,0,1]
	v_pk_fma_f32 v[34:35], v[70:71], v[194:195], v[34:35] op_sel_hi:[1,0,1]
	v_pk_fma_f32 v[28:29], v[72:73], v[194:195], v[28:29] op_sel_hi:[1,0,1]
	v_pk_fma_f32 v[30:31], v[74:75], v[194:195], v[30:31] op_sel_hi:[1,0,1]
	v_pk_fma_f32 v[20:21], v[8:9], v[194:195], v[20:21] op_sel_hi:[1,0,1]
	v_pk_fma_f32 v[22:23], v[10:11], v[194:195], v[22:23] op_sel_hi:[1,0,1]
	v_pk_fma_f32 v[0:1], v[12:13], v[194:195], v[0:1] op_sel_hi:[1,0,1]
	v_pk_fma_f32 v[2:3], v[14:15], v[194:195], v[2:3] op_sel_hi:[1,0,1]
	s_add_i32 s45, s66, 4
	v_readlane_b32 s44, v154, s45
	s_lshl_b32 s44, s44, 10
	s_add_u32 s46, s92, s44
	s_addc_u32 s47, s93, 0
	global_load_dwordx4 v[80:83], v216, s[46:47]
	s_waitcnt vmcnt(15)
	v_cvt_scalef32_pk_f32_fp4 v[8:9], v84, 1.0
	v_cvt_scalef32_pk_f32_fp4 v[10:11], v84, 1.0 op_sel:[1,0,0]
	v_cvt_scalef32_pk_f32_fp4 v[12:13], v84, 1.0 op_sel:[0,1,0]
	v_cvt_scalef32_pk_f32_fp4 v[14:15], v84, 1.0 op_sel:[1,1,0]
	v_cvt_scalef32_pk_f32_fp4 v[16:17], v85, 1.0
	v_cvt_scalef32_pk_f32_fp4 v[18:19], v85, 1.0 op_sel:[1,0,0]
	v_cvt_scalef32_pk_f32_fp4 v[64:65], v85, 1.0 op_sel:[0,1,0]
	v_cvt_scalef32_pk_f32_fp4 v[66:67], v85, 1.0 op_sel:[1,1,0]
	v_pk_fma_f32 v[24:25], v[8:9], v[194:195], v[24:25] op_sel:[0,1,0]
	v_pk_fma_f32 v[26:27], v[10:11], v[194:195], v[26:27] op_sel:[0,1,0]
	v_pk_fma_f32 v[40:41], v[12:13], v[194:195], v[40:41] op_sel:[0,1,0]
	v_pk_fma_f32 v[42:43], v[14:15], v[194:195], v[42:43] op_sel:[0,1,0]
	v_cvt_scalef32_pk_f32_fp4 v[68:69], v86, 1.0
	v_cvt_scalef32_pk_f32_fp4 v[70:71], v86, 1.0 op_sel:[1,0,0]
	v_cvt_scalef32_pk_f32_fp4 v[72:73], v86, 1.0 op_sel:[0,1,0]
	v_cvt_scalef32_pk_f32_fp4 v[74:75], v86, 1.0 op_sel:[1,1,0]
	v_pk_fma_f32 v[36:37], v[16:17], v[194:195], v[36:37] op_sel:[0,1,0]
	v_pk_fma_f32 v[38:39], v[18:19], v[194:195], v[38:39] op_sel:[0,1,0]
	v_pk_fma_f32 v[4:5], v[64:65], v[194:195], v[4:5] op_sel:[0,1,0]
	v_pk_fma_f32 v[6:7], v[66:67], v[194:195], v[6:7] op_sel:[0,1,0]
	v_cvt_scalef32_pk_f32_fp4 v[8:9], v87, 1.0
	v_cvt_scalef32_pk_f32_fp4 v[10:11], v87, 1.0 op_sel:[1,0,0]
	v_cvt_scalef32_pk_f32_fp4 v[12:13], v87, 1.0 op_sel:[0,1,0]
	v_cvt_scalef32_pk_f32_fp4 v[14:15], v87, 1.0 op_sel:[1,1,0]
	v_pk_fma_f32 v[32:33], v[68:69], v[194:195], v[32:33] op_sel:[0,1,0]
	v_pk_fma_f32 v[34:35], v[70:71], v[194:195], v[34:35] op_sel:[0,1,0]
	v_pk_fma_f32 v[28:29], v[72:73], v[194:195], v[28:29] op_sel:[0,1,0]
	v_pk_fma_f32 v[30:31], v[74:75], v[194:195], v[30:31] op_sel:[0,1,0]
	v_pk_fma_f32 v[20:21], v[8:9], v[194:195], v[20:21] op_sel:[0,1,0]
	v_pk_fma_f32 v[22:23], v[10:11], v[194:195], v[22:23] op_sel:[0,1,0]
	v_pk_fma_f32 v[0:1], v[12:13], v[194:195], v[0:1] op_sel:[0,1,0]
	v_pk_fma_f32 v[2:3], v[14:15], v[194:195], v[2:3] op_sel:[0,1,0]
	v_readlane_b32 s44, v155, s45
	s_lshl_b32 s44, s44, 10
	s_add_u32 s46, s92, s44
	s_addc_u32 s47, s93, 0
	global_load_dwordx4 v[84:87], v216, s[46:47]
	ds_read_b128 v[192:195], v131 offset:80
	s_waitcnt vmcnt(15) lgkmcnt(3)
	v_cvt_scalef32_pk_f32_fp4 v[8:9], v88, 1.0
	v_cvt_scalef32_pk_f32_fp4 v[10:11], v88, 1.0 op_sel:[1,0,0]
	v_cvt_scalef32_pk_f32_fp4 v[12:13], v88, 1.0 op_sel:[0,1,0]
	v_cvt_scalef32_pk_f32_fp4 v[14:15], v88, 1.0 op_sel:[1,1,0]
	v_cvt_scalef32_pk_f32_fp4 v[16:17], v89, 1.0
	v_cvt_scalef32_pk_f32_fp4 v[18:19], v89, 1.0 op_sel:[1,0,0]
	v_cvt_scalef32_pk_f32_fp4 v[64:65], v89, 1.0 op_sel:[0,1,0]
	v_cvt_scalef32_pk_f32_fp4 v[66:67], v89, 1.0 op_sel:[1,1,0]
	v_pk_fma_f32 v[24:25], v[8:9], v[240:241], v[24:25] op_sel_hi:[1,0,1]
	v_pk_fma_f32 v[26:27], v[10:11], v[240:241], v[26:27] op_sel_hi:[1,0,1]
	v_pk_fma_f32 v[40:41], v[12:13], v[240:241], v[40:41] op_sel_hi:[1,0,1]
	v_pk_fma_f32 v[42:43], v[14:15], v[240:241], v[42:43] op_sel_hi:[1,0,1]
	v_cvt_scalef32_pk_f32_fp4 v[68:69], v90, 1.0
	v_cvt_scalef32_pk_f32_fp4 v[70:71], v90, 1.0 op_sel:[1,0,0]
	v_cvt_scalef32_pk_f32_fp4 v[72:73], v90, 1.0 op_sel:[0,1,0]
	v_cvt_scalef32_pk_f32_fp4 v[74:75], v90, 1.0 op_sel:[1,1,0]
	v_pk_fma_f32 v[36:37], v[16:17], v[240:241], v[36:37] op_sel_hi:[1,0,1]
	v_pk_fma_f32 v[38:39], v[18:19], v[240:241], v[38:39] op_sel_hi:[1,0,1]
	v_pk_fma_f32 v[4:5], v[64:65], v[240:241], v[4:5] op_sel_hi:[1,0,1]
	v_pk_fma_f32 v[6:7], v[66:67], v[240:241], v[6:7] op_sel_hi:[1,0,1]
	v_cvt_scalef32_pk_f32_fp4 v[8:9], v91, 1.0
	v_cvt_scalef32_pk_f32_fp4 v[10:11], v91, 1.0 op_sel:[1,0,0]
	v_cvt_scalef32_pk_f32_fp4 v[12:13], v91, 1.0 op_sel:[0,1,0]
	v_cvt_scalef32_pk_f32_fp4 v[14:15], v91, 1.0 op_sel:[1,1,0]
	v_pk_fma_f32 v[32:33], v[68:69], v[240:241], v[32:33] op_sel_hi:[1,0,1]
	v_pk_fma_f32 v[34:35], v[70:71], v[240:241], v[34:35] op_sel_hi:[1,0,1]
	v_pk_fma_f32 v[28:29], v[72:73], v[240:241], v[28:29] op_sel_hi:[1,0,1]
	v_pk_fma_f32 v[30:31], v[74:75], v[240:241], v[30:31] op_sel_hi:[1,0,1]
	v_pk_fma_f32 v[20:21], v[8:9], v[240:241], v[20:21] op_sel_hi:[1,0,1]
	v_pk_fma_f32 v[22:23], v[10:11], v[240:241], v[22:23] op_sel_hi:[1,0,1]
	v_pk_fma_f32 v[0:1], v[12:13], v[240:241], v[0:1] op_sel_hi:[1,0,1]
	v_pk_fma_f32 v[2:3], v[14:15], v[240:241], v[2:3] op_sel_hi:[1,0,1]
	s_add_i32 s45, s66, 5
	v_readlane_b32 s44, v154, s45
	s_lshl_b32 s44, s44, 10
	s_add_u32 s46, s92, s44
	s_addc_u32 s47, s93, 0
	global_load_dwordx4 v[88:91], v216, s[46:47]
	s_waitcnt vmcnt(15)
	v_cvt_scalef32_pk_f32_fp4 v[8:9], v92, 1.0
	v_cvt_scalef32_pk_f32_fp4 v[10:11], v92, 1.0 op_sel:[1,0,0]
	v_cvt_scalef32_pk_f32_fp4 v[12:13], v92, 1.0 op_sel:[0,1,0]
	v_cvt_scalef32_pk_f32_fp4 v[14:15], v92, 1.0 op_sel:[1,1,0]
	v_cvt_scalef32_pk_f32_fp4 v[16:17], v93, 1.0
	v_cvt_scalef32_pk_f32_fp4 v[18:19], v93, 1.0 op_sel:[1,0,0]
	v_cvt_scalef32_pk_f32_fp4 v[64:65], v93, 1.0 op_sel:[0,1,0]
	v_cvt_scalef32_pk_f32_fp4 v[66:67], v93, 1.0 op_sel:[1,1,0]
	v_pk_fma_f32 v[24:25], v[8:9], v[240:241], v[24:25] op_sel:[0,1,0]
	v_pk_fma_f32 v[26:27], v[10:11], v[240:241], v[26:27] op_sel:[0,1,0]
	v_pk_fma_f32 v[40:41], v[12:13], v[240:241], v[40:41] op_sel:[0,1,0]
	v_pk_fma_f32 v[42:43], v[14:15], v[240:241], v[42:43] op_sel:[0,1,0]
	v_cvt_scalef32_pk_f32_fp4 v[68:69], v94, 1.0
	v_cvt_scalef32_pk_f32_fp4 v[70:71], v94, 1.0 op_sel:[1,0,0]
	v_cvt_scalef32_pk_f32_fp4 v[72:73], v94, 1.0 op_sel:[0,1,0]
	v_cvt_scalef32_pk_f32_fp4 v[74:75], v94, 1.0 op_sel:[1,1,0]
	v_pk_fma_f32 v[36:37], v[16:17], v[240:241], v[36:37] op_sel:[0,1,0]
	v_pk_fma_f32 v[38:39], v[18:19], v[240:241], v[38:39] op_sel:[0,1,0]
	v_pk_fma_f32 v[4:5], v[64:65], v[240:241], v[4:5] op_sel:[0,1,0]
	v_pk_fma_f32 v[6:7], v[66:67], v[240:241], v[6:7] op_sel:[0,1,0]
	v_cvt_scalef32_pk_f32_fp4 v[8:9], v95, 1.0
	v_cvt_scalef32_pk_f32_fp4 v[10:11], v95, 1.0 op_sel:[1,0,0]
	v_cvt_scalef32_pk_f32_fp4 v[12:13], v95, 1.0 op_sel:[0,1,0]
	v_cvt_scalef32_pk_f32_fp4 v[14:15], v95, 1.0 op_sel:[1,1,0]
	v_pk_fma_f32 v[32:33], v[68:69], v[240:241], v[32:33] op_sel:[0,1,0]
	v_pk_fma_f32 v[34:35], v[70:71], v[240:241], v[34:35] op_sel:[0,1,0]
	v_pk_fma_f32 v[28:29], v[72:73], v[240:241], v[28:29] op_sel:[0,1,0]
	v_pk_fma_f32 v[30:31], v[74:75], v[240:241], v[30:31] op_sel:[0,1,0]
	v_pk_fma_f32 v[20:21], v[8:9], v[240:241], v[20:21] op_sel:[0,1,0]
	v_pk_fma_f32 v[22:23], v[10:11], v[240:241], v[22:23] op_sel:[0,1,0]
	v_pk_fma_f32 v[0:1], v[12:13], v[240:241], v[0:1] op_sel:[0,1,0]
	v_pk_fma_f32 v[2:3], v[14:15], v[240:241], v[2:3] op_sel:[0,1,0]
	v_readlane_b32 s44, v155, s45
	s_lshl_b32 s44, s44, 10
	s_add_u32 s46, s92, s44
	s_addc_u32 s47, s93, 0
	global_load_dwordx4 v[92:95], v216, s[46:47]
	s_waitcnt vmcnt(15)
	v_cvt_scalef32_pk_f32_fp4 v[8:9], v96, 1.0
	v_cvt_scalef32_pk_f32_fp4 v[10:11], v96, 1.0 op_sel:[1,0,0]
	v_cvt_scalef32_pk_f32_fp4 v[12:13], v96, 1.0 op_sel:[0,1,0]
	v_cvt_scalef32_pk_f32_fp4 v[14:15], v96, 1.0 op_sel:[1,1,0]
	v_cvt_scalef32_pk_f32_fp4 v[16:17], v97, 1.0
	v_cvt_scalef32_pk_f32_fp4 v[18:19], v97, 1.0 op_sel:[1,0,0]
	v_cvt_scalef32_pk_f32_fp4 v[64:65], v97, 1.0 op_sel:[0,1,0]
	v_cvt_scalef32_pk_f32_fp4 v[66:67], v97, 1.0 op_sel:[1,1,0]
	v_pk_fma_f32 v[24:25], v[8:9], v[242:243], v[24:25] op_sel_hi:[1,0,1]
	v_pk_fma_f32 v[26:27], v[10:11], v[242:243], v[26:27] op_sel_hi:[1,0,1]
	v_pk_fma_f32 v[40:41], v[12:13], v[242:243], v[40:41] op_sel_hi:[1,0,1]
	v_pk_fma_f32 v[42:43], v[14:15], v[242:243], v[42:43] op_sel_hi:[1,0,1]
	v_cvt_scalef32_pk_f32_fp4 v[68:69], v98, 1.0
	v_cvt_scalef32_pk_f32_fp4 v[70:71], v98, 1.0 op_sel:[1,0,0]
	v_cvt_scalef32_pk_f32_fp4 v[72:73], v98, 1.0 op_sel:[0,1,0]
	v_cvt_scalef32_pk_f32_fp4 v[74:75], v98, 1.0 op_sel:[1,1,0]
	v_pk_fma_f32 v[36:37], v[16:17], v[242:243], v[36:37] op_sel_hi:[1,0,1]
	v_pk_fma_f32 v[38:39], v[18:19], v[242:243], v[38:39] op_sel_hi:[1,0,1]
	v_pk_fma_f32 v[4:5], v[64:65], v[242:243], v[4:5] op_sel_hi:[1,0,1]
	v_pk_fma_f32 v[6:7], v[66:67], v[242:243], v[6:7] op_sel_hi:[1,0,1]
	v_cvt_scalef32_pk_f32_fp4 v[8:9], v99, 1.0
	v_cvt_scalef32_pk_f32_fp4 v[10:11], v99, 1.0 op_sel:[1,0,0]
	v_cvt_scalef32_pk_f32_fp4 v[12:13], v99, 1.0 op_sel:[0,1,0]
	v_cvt_scalef32_pk_f32_fp4 v[14:15], v99, 1.0 op_sel:[1,1,0]
	v_pk_fma_f32 v[32:33], v[68:69], v[242:243], v[32:33] op_sel_hi:[1,0,1]
	v_pk_fma_f32 v[34:35], v[70:71], v[242:243], v[34:35] op_sel_hi:[1,0,1]
	v_pk_fma_f32 v[28:29], v[72:73], v[242:243], v[28:29] op_sel_hi:[1,0,1]
	v_pk_fma_f32 v[30:31], v[74:75], v[242:243], v[30:31] op_sel_hi:[1,0,1]
	v_pk_fma_f32 v[20:21], v[8:9], v[242:243], v[20:21] op_sel_hi:[1,0,1]
	v_pk_fma_f32 v[22:23], v[10:11], v[242:243], v[22:23] op_sel_hi:[1,0,1]
	v_pk_fma_f32 v[0:1], v[12:13], v[242:243], v[0:1] op_sel_hi:[1,0,1]
	v_pk_fma_f32 v[2:3], v[14:15], v[242:243], v[2:3] op_sel_hi:[1,0,1]
	s_add_i32 s45, s66, 6
	v_readlane_b32 s44, v154, s45
	s_lshl_b32 s44, s44, 10
	s_add_u32 s46, s92, s44
	s_addc_u32 s47, s93, 0
	global_load_dwordx4 v[96:99], v216, s[46:47]
	s_waitcnt vmcnt(15)
	v_cvt_scalef32_pk_f32_fp4 v[8:9], v100, 1.0
	v_cvt_scalef32_pk_f32_fp4 v[10:11], v100, 1.0 op_sel:[1,0,0]
	v_cvt_scalef32_pk_f32_fp4 v[12:13], v100, 1.0 op_sel:[0,1,0]
	v_cvt_scalef32_pk_f32_fp4 v[14:15], v100, 1.0 op_sel:[1,1,0]
	v_cvt_scalef32_pk_f32_fp4 v[16:17], v101, 1.0
	v_cvt_scalef32_pk_f32_fp4 v[18:19], v101, 1.0 op_sel:[1,0,0]
	v_cvt_scalef32_pk_f32_fp4 v[64:65], v101, 1.0 op_sel:[0,1,0]
	v_cvt_scalef32_pk_f32_fp4 v[66:67], v101, 1.0 op_sel:[1,1,0]
	v_pk_fma_f32 v[24:25], v[8:9], v[242:243], v[24:25] op_sel:[0,1,0]
	v_pk_fma_f32 v[26:27], v[10:11], v[242:243], v[26:27] op_sel:[0,1,0]
	v_pk_fma_f32 v[40:41], v[12:13], v[242:243], v[40:41] op_sel:[0,1,0]
	v_pk_fma_f32 v[42:43], v[14:15], v[242:243], v[42:43] op_sel:[0,1,0]
	v_cvt_scalef32_pk_f32_fp4 v[68:69], v102, 1.0
	v_cvt_scalef32_pk_f32_fp4 v[70:71], v102, 1.0 op_sel:[1,0,0]
	v_cvt_scalef32_pk_f32_fp4 v[72:73], v102, 1.0 op_sel:[0,1,0]
	v_cvt_scalef32_pk_f32_fp4 v[74:75], v102, 1.0 op_sel:[1,1,0]
	v_pk_fma_f32 v[36:37], v[16:17], v[242:243], v[36:37] op_sel:[0,1,0]
	v_pk_fma_f32 v[38:39], v[18:19], v[242:243], v[38:39] op_sel:[0,1,0]
	v_pk_fma_f32 v[4:5], v[64:65], v[242:243], v[4:5] op_sel:[0,1,0]
	v_pk_fma_f32 v[6:7], v[66:67], v[242:243], v[6:7] op_sel:[0,1,0]
	v_cvt_scalef32_pk_f32_fp4 v[8:9], v103, 1.0
	v_cvt_scalef32_pk_f32_fp4 v[10:11], v103, 1.0 op_sel:[1,0,0]
	v_cvt_scalef32_pk_f32_fp4 v[12:13], v103, 1.0 op_sel:[0,1,0]
	v_cvt_scalef32_pk_f32_fp4 v[14:15], v103, 1.0 op_sel:[1,1,0]
	v_pk_fma_f32 v[32:33], v[68:69], v[242:243], v[32:33] op_sel:[0,1,0]
	v_pk_fma_f32 v[34:35], v[70:71], v[242:243], v[34:35] op_sel:[0,1,0]
	v_pk_fma_f32 v[28:29], v[72:73], v[242:243], v[28:29] op_sel:[0,1,0]
	v_pk_fma_f32 v[30:31], v[74:75], v[242:243], v[30:31] op_sel:[0,1,0]
	v_pk_fma_f32 v[20:21], v[8:9], v[242:243], v[20:21] op_sel:[0,1,0]
	v_pk_fma_f32 v[22:23], v[10:11], v[242:243], v[22:23] op_sel:[0,1,0]
	v_pk_fma_f32 v[0:1], v[12:13], v[242:243], v[0:1] op_sel:[0,1,0]
	v_pk_fma_f32 v[2:3], v[14:15], v[242:243], v[2:3] op_sel:[0,1,0]
	v_readlane_b32 s44, v155, s45
	s_lshl_b32 s44, s44, 10
	s_add_u32 s46, s92, s44
	s_addc_u32 s47, s93, 0
	global_load_dwordx4 v[100:103], v216, s[46:47]
	ds_read_b128 v[240:243], v131 offset:96
	s_waitcnt vmcnt(15) lgkmcnt(3)
	v_cvt_scalef32_pk_f32_fp4 v[8:9], v172, 1.0
	v_cvt_scalef32_pk_f32_fp4 v[10:11], v172, 1.0 op_sel:[1,0,0]
	v_cvt_scalef32_pk_f32_fp4 v[12:13], v172, 1.0 op_sel:[0,1,0]
	v_cvt_scalef32_pk_f32_fp4 v[14:15], v172, 1.0 op_sel:[1,1,0]
	v_cvt_scalef32_pk_f32_fp4 v[16:17], v173, 1.0
	v_cvt_scalef32_pk_f32_fp4 v[18:19], v173, 1.0 op_sel:[1,0,0]
	v_cvt_scalef32_pk_f32_fp4 v[64:65], v173, 1.0 op_sel:[0,1,0]
	v_cvt_scalef32_pk_f32_fp4 v[66:67], v173, 1.0 op_sel:[1,1,0]
	v_pk_fma_f32 v[24:25], v[8:9], v[244:245], v[24:25] op_sel_hi:[1,0,1]
	v_pk_fma_f32 v[26:27], v[10:11], v[244:245], v[26:27] op_sel_hi:[1,0,1]
	v_pk_fma_f32 v[40:41], v[12:13], v[244:245], v[40:41] op_sel_hi:[1,0,1]
	v_pk_fma_f32 v[42:43], v[14:15], v[244:245], v[42:43] op_sel_hi:[1,0,1]
	v_cvt_scalef32_pk_f32_fp4 v[68:69], v174, 1.0
	v_cvt_scalef32_pk_f32_fp4 v[70:71], v174, 1.0 op_sel:[1,0,0]
	v_cvt_scalef32_pk_f32_fp4 v[72:73], v174, 1.0 op_sel:[0,1,0]
	v_cvt_scalef32_pk_f32_fp4 v[74:75], v174, 1.0 op_sel:[1,1,0]
	v_pk_fma_f32 v[36:37], v[16:17], v[244:245], v[36:37] op_sel_hi:[1,0,1]
	v_pk_fma_f32 v[38:39], v[18:19], v[244:245], v[38:39] op_sel_hi:[1,0,1]
	v_pk_fma_f32 v[4:5], v[64:65], v[244:245], v[4:5] op_sel_hi:[1,0,1]
	v_pk_fma_f32 v[6:7], v[66:67], v[244:245], v[6:7] op_sel_hi:[1,0,1]
	v_cvt_scalef32_pk_f32_fp4 v[8:9], v175, 1.0
	v_cvt_scalef32_pk_f32_fp4 v[10:11], v175, 1.0 op_sel:[1,0,0]
	v_cvt_scalef32_pk_f32_fp4 v[12:13], v175, 1.0 op_sel:[0,1,0]
	v_cvt_scalef32_pk_f32_fp4 v[14:15], v175, 1.0 op_sel:[1,1,0]
	v_pk_fma_f32 v[32:33], v[68:69], v[244:245], v[32:33] op_sel_hi:[1,0,1]
	v_pk_fma_f32 v[34:35], v[70:71], v[244:245], v[34:35] op_sel_hi:[1,0,1]
	v_pk_fma_f32 v[28:29], v[72:73], v[244:245], v[28:29] op_sel_hi:[1,0,1]
	v_pk_fma_f32 v[30:31], v[74:75], v[244:245], v[30:31] op_sel_hi:[1,0,1]
	v_pk_fma_f32 v[20:21], v[8:9], v[244:245], v[20:21] op_sel_hi:[1,0,1]
	v_pk_fma_f32 v[22:23], v[10:11], v[244:245], v[22:23] op_sel_hi:[1,0,1]
	v_pk_fma_f32 v[0:1], v[12:13], v[244:245], v[0:1] op_sel_hi:[1,0,1]
	v_pk_fma_f32 v[2:3], v[14:15], v[244:245], v[2:3] op_sel_hi:[1,0,1]
	s_add_i32 s45, s66, 7
	v_readlane_b32 s44, v154, s45
	s_lshl_b32 s44, s44, 10
	s_add_u32 s46, s92, s44
	s_addc_u32 s47, s93, 0
	global_load_dwordx4 v[172:175], v216, s[46:47]
	s_waitcnt vmcnt(15)
	v_cvt_scalef32_pk_f32_fp4 v[8:9], v176, 1.0
	v_cvt_scalef32_pk_f32_fp4 v[10:11], v176, 1.0 op_sel:[1,0,0]
	v_cvt_scalef32_pk_f32_fp4 v[12:13], v176, 1.0 op_sel:[0,1,0]
	v_cvt_scalef32_pk_f32_fp4 v[14:15], v176, 1.0 op_sel:[1,1,0]
	v_cvt_scalef32_pk_f32_fp4 v[16:17], v177, 1.0
	v_cvt_scalef32_pk_f32_fp4 v[18:19], v177, 1.0 op_sel:[1,0,0]
	v_cvt_scalef32_pk_f32_fp4 v[64:65], v177, 1.0 op_sel:[0,1,0]
	v_cvt_scalef32_pk_f32_fp4 v[66:67], v177, 1.0 op_sel:[1,1,0]
	v_pk_fma_f32 v[24:25], v[8:9], v[244:245], v[24:25] op_sel:[0,1,0]
	v_pk_fma_f32 v[26:27], v[10:11], v[244:245], v[26:27] op_sel:[0,1,0]
	v_pk_fma_f32 v[40:41], v[12:13], v[244:245], v[40:41] op_sel:[0,1,0]
	v_pk_fma_f32 v[42:43], v[14:15], v[244:245], v[42:43] op_sel:[0,1,0]
	v_cvt_scalef32_pk_f32_fp4 v[68:69], v178, 1.0
	v_cvt_scalef32_pk_f32_fp4 v[70:71], v178, 1.0 op_sel:[1,0,0]
	v_cvt_scalef32_pk_f32_fp4 v[72:73], v178, 1.0 op_sel:[0,1,0]
	v_cvt_scalef32_pk_f32_fp4 v[74:75], v178, 1.0 op_sel:[1,1,0]
	v_pk_fma_f32 v[36:37], v[16:17], v[244:245], v[36:37] op_sel:[0,1,0]
	v_pk_fma_f32 v[38:39], v[18:19], v[244:245], v[38:39] op_sel:[0,1,0]
	v_pk_fma_f32 v[4:5], v[64:65], v[244:245], v[4:5] op_sel:[0,1,0]
	v_pk_fma_f32 v[6:7], v[66:67], v[244:245], v[6:7] op_sel:[0,1,0]
	v_cvt_scalef32_pk_f32_fp4 v[8:9], v179, 1.0
	v_cvt_scalef32_pk_f32_fp4 v[10:11], v179, 1.0 op_sel:[1,0,0]
	v_cvt_scalef32_pk_f32_fp4 v[12:13], v179, 1.0 op_sel:[0,1,0]
	v_cvt_scalef32_pk_f32_fp4 v[14:15], v179, 1.0 op_sel:[1,1,0]
	v_pk_fma_f32 v[32:33], v[68:69], v[244:245], v[32:33] op_sel:[0,1,0]
	v_pk_fma_f32 v[34:35], v[70:71], v[244:245], v[34:35] op_sel:[0,1,0]
	v_pk_fma_f32 v[28:29], v[72:73], v[244:245], v[28:29] op_sel:[0,1,0]
	v_pk_fma_f32 v[30:31], v[74:75], v[244:245], v[30:31] op_sel:[0,1,0]
	v_pk_fma_f32 v[20:21], v[8:9], v[244:245], v[20:21] op_sel:[0,1,0]
	v_pk_fma_f32 v[22:23], v[10:11], v[244:245], v[22:23] op_sel:[0,1,0]
	v_pk_fma_f32 v[0:1], v[12:13], v[244:245], v[0:1] op_sel:[0,1,0]
	v_pk_fma_f32 v[2:3], v[14:15], v[244:245], v[2:3] op_sel:[0,1,0]
	v_readlane_b32 s44, v155, s45
	s_lshl_b32 s44, s44, 10
	s_add_u32 s46, s92, s44
	s_addc_u32 s47, s93, 0
	global_load_dwordx4 v[176:179], v216, s[46:47]
	s_waitcnt vmcnt(15)
	v_cvt_scalef32_pk_f32_fp4 v[8:9], v180, 1.0
	v_cvt_scalef32_pk_f32_fp4 v[10:11], v180, 1.0 op_sel:[1,0,0]
	v_cvt_scalef32_pk_f32_fp4 v[12:13], v180, 1.0 op_sel:[0,1,0]
	v_cvt_scalef32_pk_f32_fp4 v[14:15], v180, 1.0 op_sel:[1,1,0]
	v_cvt_scalef32_pk_f32_fp4 v[16:17], v181, 1.0
	v_cvt_scalef32_pk_f32_fp4 v[18:19], v181, 1.0 op_sel:[1,0,0]
	v_cvt_scalef32_pk_f32_fp4 v[64:65], v181, 1.0 op_sel:[0,1,0]
	v_cvt_scalef32_pk_f32_fp4 v[66:67], v181, 1.0 op_sel:[1,1,0]
	v_pk_fma_f32 v[24:25], v[8:9], v[246:247], v[24:25] op_sel_hi:[1,0,1]
	v_pk_fma_f32 v[26:27], v[10:11], v[246:247], v[26:27] op_sel_hi:[1,0,1]
	v_pk_fma_f32 v[40:41], v[12:13], v[246:247], v[40:41] op_sel_hi:[1,0,1]
	v_pk_fma_f32 v[42:43], v[14:15], v[246:247], v[42:43] op_sel_hi:[1,0,1]
	v_cvt_scalef32_pk_f32_fp4 v[68:69], v182, 1.0
	v_cvt_scalef32_pk_f32_fp4 v[70:71], v182, 1.0 op_sel:[1,0,0]
	v_cvt_scalef32_pk_f32_fp4 v[72:73], v182, 1.0 op_sel:[0,1,0]
	v_cvt_scalef32_pk_f32_fp4 v[74:75], v182, 1.0 op_sel:[1,1,0]
	v_pk_fma_f32 v[36:37], v[16:17], v[246:247], v[36:37] op_sel_hi:[1,0,1]
	v_pk_fma_f32 v[38:39], v[18:19], v[246:247], v[38:39] op_sel_hi:[1,0,1]
	v_pk_fma_f32 v[4:5], v[64:65], v[246:247], v[4:5] op_sel_hi:[1,0,1]
	v_pk_fma_f32 v[6:7], v[66:67], v[246:247], v[6:7] op_sel_hi:[1,0,1]
	v_cvt_scalef32_pk_f32_fp4 v[8:9], v183, 1.0
	v_cvt_scalef32_pk_f32_fp4 v[10:11], v183, 1.0 op_sel:[1,0,0]
	v_cvt_scalef32_pk_f32_fp4 v[12:13], v183, 1.0 op_sel:[0,1,0]
	v_cvt_scalef32_pk_f32_fp4 v[14:15], v183, 1.0 op_sel:[1,1,0]
	v_pk_fma_f32 v[32:33], v[68:69], v[246:247], v[32:33] op_sel_hi:[1,0,1]
	v_pk_fma_f32 v[34:35], v[70:71], v[246:247], v[34:35] op_sel_hi:[1,0,1]
	v_pk_fma_f32 v[28:29], v[72:73], v[246:247], v[28:29] op_sel_hi:[1,0,1]
	v_pk_fma_f32 v[30:31], v[74:75], v[246:247], v[30:31] op_sel_hi:[1,0,1]
	v_pk_fma_f32 v[20:21], v[8:9], v[246:247], v[20:21] op_sel_hi:[1,0,1]
	v_pk_fma_f32 v[22:23], v[10:11], v[246:247], v[22:23] op_sel_hi:[1,0,1]
	v_pk_fma_f32 v[0:1], v[12:13], v[246:247], v[0:1] op_sel_hi:[1,0,1]
	v_pk_fma_f32 v[2:3], v[14:15], v[246:247], v[2:3] op_sel_hi:[1,0,1]
	s_add_i32 s45, s66, 8
	v_readlane_b32 s44, v154, s45
	s_lshl_b32 s44, s44, 10
	s_add_u32 s46, s92, s44
	s_addc_u32 s47, s93, 0
	global_load_dwordx4 v[180:183], v216, s[46:47]
	s_waitcnt vmcnt(15)
	v_cvt_scalef32_pk_f32_fp4 v[8:9], v184, 1.0
	v_cvt_scalef32_pk_f32_fp4 v[10:11], v184, 1.0 op_sel:[1,0,0]
	v_cvt_scalef32_pk_f32_fp4 v[12:13], v184, 1.0 op_sel:[0,1,0]
	v_cvt_scalef32_pk_f32_fp4 v[14:15], v184, 1.0 op_sel:[1,1,0]
	v_cvt_scalef32_pk_f32_fp4 v[16:17], v185, 1.0
	v_cvt_scalef32_pk_f32_fp4 v[18:19], v185, 1.0 op_sel:[1,0,0]
	v_cvt_scalef32_pk_f32_fp4 v[64:65], v185, 1.0 op_sel:[0,1,0]
	v_cvt_scalef32_pk_f32_fp4 v[66:67], v185, 1.0 op_sel:[1,1,0]
	v_pk_fma_f32 v[24:25], v[8:9], v[246:247], v[24:25] op_sel:[0,1,0]
	v_pk_fma_f32 v[26:27], v[10:11], v[246:247], v[26:27] op_sel:[0,1,0]
	v_pk_fma_f32 v[40:41], v[12:13], v[246:247], v[40:41] op_sel:[0,1,0]
	v_pk_fma_f32 v[42:43], v[14:15], v[246:247], v[42:43] op_sel:[0,1,0]
	v_cvt_scalef32_pk_f32_fp4 v[68:69], v186, 1.0
	v_cvt_scalef32_pk_f32_fp4 v[70:71], v186, 1.0 op_sel:[1,0,0]
	v_cvt_scalef32_pk_f32_fp4 v[72:73], v186, 1.0 op_sel:[0,1,0]
	v_cvt_scalef32_pk_f32_fp4 v[74:75], v186, 1.0 op_sel:[1,1,0]
	v_pk_fma_f32 v[36:37], v[16:17], v[246:247], v[36:37] op_sel:[0,1,0]
	v_pk_fma_f32 v[38:39], v[18:19], v[246:247], v[38:39] op_sel:[0,1,0]
	v_pk_fma_f32 v[4:5], v[64:65], v[246:247], v[4:5] op_sel:[0,1,0]
	v_pk_fma_f32 v[6:7], v[66:67], v[246:247], v[6:7] op_sel:[0,1,0]
	v_cvt_scalef32_pk_f32_fp4 v[8:9], v187, 1.0
	v_cvt_scalef32_pk_f32_fp4 v[10:11], v187, 1.0 op_sel:[1,0,0]
	v_cvt_scalef32_pk_f32_fp4 v[12:13], v187, 1.0 op_sel:[0,1,0]
	v_cvt_scalef32_pk_f32_fp4 v[14:15], v187, 1.0 op_sel:[1,1,0]
	v_pk_fma_f32 v[32:33], v[68:69], v[246:247], v[32:33] op_sel:[0,1,0]
	v_pk_fma_f32 v[34:35], v[70:71], v[246:247], v[34:35] op_sel:[0,1,0]
	v_pk_fma_f32 v[28:29], v[72:73], v[246:247], v[28:29] op_sel:[0,1,0]
	v_pk_fma_f32 v[30:31], v[74:75], v[246:247], v[30:31] op_sel:[0,1,0]
	v_pk_fma_f32 v[20:21], v[8:9], v[246:247], v[20:21] op_sel:[0,1,0]
	v_pk_fma_f32 v[22:23], v[10:11], v[246:247], v[22:23] op_sel:[0,1,0]
	v_pk_fma_f32 v[0:1], v[12:13], v[246:247], v[0:1] op_sel:[0,1,0]
	v_pk_fma_f32 v[2:3], v[14:15], v[246:247], v[2:3] op_sel:[0,1,0]
	v_readlane_b32 s44, v155, s45
	s_lshl_b32 s44, s44, 10
	s_add_u32 s46, s92, s44
	s_addc_u32 s47, s93, 0
	global_load_dwordx4 v[184:187], v216, s[46:47]
	ds_read_b128 v[244:247], v131 offset:112
	s_add_i32 s65, s65, 16
	s_add_i32 s66, s66, 8
	v_add_u32_e32 v131, 64, v131
	s_cmpk_lt_u32 s65, 0x60
	s_cbranch_scc1 .Lp10v_loop
	s_waitcnt vmcnt(15) lgkmcnt(3)
	v_cvt_scalef32_pk_f32_fp4 v[8:9], v44, 1.0
	v_cvt_scalef32_pk_f32_fp4 v[10:11], v44, 1.0 op_sel:[1,0,0]
	v_cvt_scalef32_pk_f32_fp4 v[12:13], v44, 1.0 op_sel:[0,1,0]
	v_cvt_scalef32_pk_f32_fp4 v[14:15], v44, 1.0 op_sel:[1,1,0]
	v_cvt_scalef32_pk_f32_fp4 v[16:17], v45, 1.0
	v_cvt_scalef32_pk_f32_fp4 v[18:19], v45, 1.0 op_sel:[1,0,0]
	v_cvt_scalef32_pk_f32_fp4 v[64:65], v45, 1.0 op_sel:[0,1,0]
	v_cvt_scalef32_pk_f32_fp4 v[66:67], v45, 1.0 op_sel:[1,1,0]
	v_pk_fma_f32 v[24:25], v[8:9], v[188:189], v[24:25] op_sel_hi:[1,0,1]
	v_pk_fma_f32 v[26:27], v[10:11], v[188:189], v[26:27] op_sel_hi:[1,0,1]
	v_pk_fma_f32 v[40:41], v[12:13], v[188:189], v[40:41] op_sel_hi:[1,0,1]
	v_pk_fma_f32 v[42:43], v[14:15], v[188:189], v[42:43] op_sel_hi:[1,0,1]
	v_cvt_scalef32_pk_f32_fp4 v[68:69], v46, 1.0
	v_cvt_scalef32_pk_f32_fp4 v[70:71], v46, 1.0 op_sel:[1,0,0]
	v_cvt_scalef32_pk_f32_fp4 v[72:73], v46, 1.0 op_sel:[0,1,0]
	v_cvt_scalef32_pk_f32_fp4 v[74:75], v46, 1.0 op_sel:[1,1,0]
	v_pk_fma_f32 v[36:37], v[16:17], v[188:189], v[36:37] op_sel_hi:[1,0,1]
	v_pk_fma_f32 v[38:39], v[18:19], v[188:189], v[38:39] op_sel_hi:[1,0,1]
	v_pk_fma_f32 v[4:5], v[64:65], v[188:189], v[4:5] op_sel_hi:[1,0,1]
	v_pk_fma_f32 v[6:7], v[66:67], v[188:189], v[6:7] op_sel_hi:[1,0,1]
	v_cvt_scalef32_pk_f32_fp4 v[8:9], v47, 1.0
	v_cvt_scalef32_pk_f32_fp4 v[10:11], v47, 1.0 op_sel:[1,0,0]
	v_cvt_scalef32_pk_f32_fp4 v[12:13], v47, 1.0 op_sel:[0,1,0]
	v_cvt_scalef32_pk_f32_fp4 v[14:15], v47, 1.0 op_sel:[1,1,0]
	v_pk_fma_f32 v[32:33], v[68:69], v[188:189], v[32:33] op_sel_hi:[1,0,1]
	v_pk_fma_f32 v[34:35], v[70:71], v[188:189], v[34:35] op_sel_hi:[1,0,1]
	v_pk_fma_f32 v[28:29], v[72:73], v[188:189], v[28:29] op_sel_hi:[1,0,1]
	v_pk_fma_f32 v[30:31], v[74:75], v[188:189], v[30:31] op_sel_hi:[1,0,1]
	v_pk_fma_f32 v[20:21], v[8:9], v[188:189], v[20:21] op_sel_hi:[1,0,1]
	v_pk_fma_f32 v[22:23], v[10:11], v[188:189], v[22:23] op_sel_hi:[1,0,1]
	v_pk_fma_f32 v[0:1], v[12:13], v[188:189], v[0:1] op_sel_hi:[1,0,1]
	v_pk_fma_f32 v[2:3], v[14:15], v[188:189], v[2:3] op_sel_hi:[1,0,1]
	s_waitcnt vmcnt(14)
	v_cvt_scalef32_pk_f32_fp4 v[8:9], v48, 1.0
	v_cvt_scalef32_pk_f32_fp4 v[10:11], v48, 1.0 op_sel:[1,0,0]
	v_cvt_scalef32_pk_f32_fp4 v[12:13], v48, 1.0 op_sel:[0,1,0]
	v_cvt_scalef32_pk_f32_fp4 v[14:15], v48, 1.0 op_sel:[1,1,0]
	v_cvt_scalef32_pk_f32_fp4 v[16:17], v49, 1.0
	v_cvt_scalef32_pk_f32_fp4 v[18:19], v49, 1.0 op_sel:[1,0,0]
	v_cvt_scalef32_pk_f32_fp4 v[64:65], v49, 1.0 op_sel:[0,1,0]
	v_cvt_scalef32_pk_f32_fp4 v[66:67], v49, 1.0 op_sel:[1,1,0]
	v_pk_fma_f32 v[24:25], v[8:9], v[188:189], v[24:25] op_sel:[0,1,0]
	v_pk_fma_f32 v[26:27], v[10:11], v[188:189], v[26:27] op_sel:[0,1,0]
	v_pk_fma_f32 v[40:41], v[12:13], v[188:189], v[40:41] op_sel:[0,1,0]
	v_pk_fma_f32 v[42:43], v[14:15], v[188:189], v[42:43] op_sel:[0,1,0]
	v_cvt_scalef32_pk_f32_fp4 v[68:69], v50, 1.0
	v_cvt_scalef32_pk_f32_fp4 v[70:71], v50, 1.0 op_sel:[1,0,0]
	v_cvt_scalef32_pk_f32_fp4 v[72:73], v50, 1.0 op_sel:[0,1,0]
	v_cvt_scalef32_pk_f32_fp4 v[74:75], v50, 1.0 op_sel:[1,1,0]
	v_pk_fma_f32 v[36:37], v[16:17], v[188:189], v[36:37] op_sel:[0,1,0]
	v_pk_fma_f32 v[38:39], v[18:19], v[188:189], v[38:39] op_sel:[0,1,0]
	v_pk_fma_f32 v[4:5], v[64:65], v[188:189], v[4:5] op_sel:[0,1,0]
	v_pk_fma_f32 v[6:7], v[66:67], v[188:189], v[6:7] op_sel:[0,1,0]
	v_cvt_scalef32_pk_f32_fp4 v[8:9], v51, 1.0
	v_cvt_scalef32_pk_f32_fp4 v[10:11], v51, 1.0 op_sel:[1,0,0]
	v_cvt_scalef32_pk_f32_fp4 v[12:13], v51, 1.0 op_sel:[0,1,0]
	v_cvt_scalef32_pk_f32_fp4 v[14:15], v51, 1.0 op_sel:[1,1,0]
	v_pk_fma_f32 v[32:33], v[68:69], v[188:189], v[32:33] op_sel:[0,1,0]
	v_pk_fma_f32 v[34:35], v[70:71], v[188:189], v[34:35] op_sel:[0,1,0]
	v_pk_fma_f32 v[28:29], v[72:73], v[188:189], v[28:29] op_sel:[0,1,0]
	v_pk_fma_f32 v[30:31], v[74:75], v[188:189], v[30:31] op_sel:[0,1,0]
	v_pk_fma_f32 v[20:21], v[8:9], v[188:189], v[20:21] op_sel:[0,1,0]
	v_pk_fma_f32 v[22:23], v[10:11], v[188:189], v[22:23] op_sel:[0,1,0]
	v_pk_fma_f32 v[0:1], v[12:13], v[188:189], v[0:1] op_sel:[0,1,0]
	v_pk_fma_f32 v[2:3], v[14:15], v[188:189], v[2:3] op_sel:[0,1,0]
	s_waitcnt vmcnt(13)
	v_cvt_scalef32_pk_f32_fp4 v[8:9], v52, 1.0
	v_cvt_scalef32_pk_f32_fp4 v[10:11], v52, 1.0 op_sel:[1,0,0]
	v_cvt_scalef32_pk_f32_fp4 v[12:13], v52, 1.0 op_sel:[0,1,0]
	v_cvt_scalef32_pk_f32_fp4 v[14:15], v52, 1.0 op_sel:[1,1,0]
	v_cvt_scalef32_pk_f32_fp4 v[16:17], v53, 1.0
	v_cvt_scalef32_pk_f32_fp4 v[18:19], v53, 1.0 op_sel:[1,0,0]
	v_cvt_scalef32_pk_f32_fp4 v[64:65], v53, 1.0 op_sel:[0,1,0]
	v_cvt_scalef32_pk_f32_fp4 v[66:67], v53, 1.0 op_sel:[1,1,0]
	v_pk_fma_f32 v[24:25], v[8:9], v[190:191], v[24:25] op_sel_hi:[1,0,1]
	v_pk_fma_f32 v[26:27], v[10:11], v[190:191], v[26:27] op_sel_hi:[1,0,1]
	v_pk_fma_f32 v[40:41], v[12:13], v[190:191], v[40:41] op_sel_hi:[1,0,1]
	v_pk_fma_f32 v[42:43], v[14:15], v[190:191], v[42:43] op_sel_hi:[1,0,1]
	v_cvt_scalef32_pk_f32_fp4 v[68:69], v54, 1.0
	v_cvt_scalef32_pk_f32_fp4 v[70:71], v54, 1.0 op_sel:[1,0,0]
	v_cvt_scalef32_pk_f32_fp4 v[72:73], v54, 1.0 op_sel:[0,1,0]
	v_cvt_scalef32_pk_f32_fp4 v[74:75], v54, 1.0 op_sel:[1,1,0]
	v_pk_fma_f32 v[36:37], v[16:17], v[190:191], v[36:37] op_sel_hi:[1,0,1]
	v_pk_fma_f32 v[38:39], v[18:19], v[190:191], v[38:39] op_sel_hi:[1,0,1]
	v_pk_fma_f32 v[4:5], v[64:65], v[190:191], v[4:5] op_sel_hi:[1,0,1]
	v_pk_fma_f32 v[6:7], v[66:67], v[190:191], v[6:7] op_sel_hi:[1,0,1]
	v_cvt_scalef32_pk_f32_fp4 v[8:9], v55, 1.0
	v_cvt_scalef32_pk_f32_fp4 v[10:11], v55, 1.0 op_sel:[1,0,0]
	v_cvt_scalef32_pk_f32_fp4 v[12:13], v55, 1.0 op_sel:[0,1,0]
	v_cvt_scalef32_pk_f32_fp4 v[14:15], v55, 1.0 op_sel:[1,1,0]
	v_pk_fma_f32 v[32:33], v[68:69], v[190:191], v[32:33] op_sel_hi:[1,0,1]
	v_pk_fma_f32 v[34:35], v[70:71], v[190:191], v[34:35] op_sel_hi:[1,0,1]
	v_pk_fma_f32 v[28:29], v[72:73], v[190:191], v[28:29] op_sel_hi:[1,0,1]
	v_pk_fma_f32 v[30:31], v[74:75], v[190:191], v[30:31] op_sel_hi:[1,0,1]
	v_pk_fma_f32 v[20:21], v[8:9], v[190:191], v[20:21] op_sel_hi:[1,0,1]
	v_pk_fma_f32 v[22:23], v[10:11], v[190:191], v[22:23] op_sel_hi:[1,0,1]
	v_pk_fma_f32 v[0:1], v[12:13], v[190:191], v[0:1] op_sel_hi:[1,0,1]
	v_pk_fma_f32 v[2:3], v[14:15], v[190:191], v[2:3] op_sel_hi:[1,0,1]
	s_waitcnt vmcnt(12)
	v_cvt_scalef32_pk_f32_fp4 v[8:9], v56, 1.0
	v_cvt_scalef32_pk_f32_fp4 v[10:11], v56, 1.0 op_sel:[1,0,0]
	v_cvt_scalef32_pk_f32_fp4 v[12:13], v56, 1.0 op_sel:[0,1,0]
	v_cvt_scalef32_pk_f32_fp4 v[14:15], v56, 1.0 op_sel:[1,1,0]
	v_cvt_scalef32_pk_f32_fp4 v[16:17], v57, 1.0
	v_cvt_scalef32_pk_f32_fp4 v[18:19], v57, 1.0 op_sel:[1,0,0]
	v_cvt_scalef32_pk_f32_fp4 v[64:65], v57, 1.0 op_sel:[0,1,0]
	v_cvt_scalef32_pk_f32_fp4 v[66:67], v57, 1.0 op_sel:[1,1,0]
	v_pk_fma_f32 v[24:25], v[8:9], v[190:191], v[24:25] op_sel:[0,1,0]
	v_pk_fma_f32 v[26:27], v[10:11], v[190:191], v[26:27] op_sel:[0,1,0]
	v_pk_fma_f32 v[40:41], v[12:13], v[190:191], v[40:41] op_sel:[0,1,0]
	v_pk_fma_f32 v[42:43], v[14:15], v[190:191], v[42:43] op_sel:[0,1,0]
	v_cvt_scalef32_pk_f32_fp4 v[68:69], v58, 1.0
	v_cvt_scalef32_pk_f32_fp4 v[70:71], v58, 1.0 op_sel:[1,0,0]
	v_cvt_scalef32_pk_f32_fp4 v[72:73], v58, 1.0 op_sel:[0,1,0]
	v_cvt_scalef32_pk_f32_fp4 v[74:75], v58, 1.0 op_sel:[1,1,0]
	v_pk_fma_f32 v[36:37], v[16:17], v[190:191], v[36:37] op_sel:[0,1,0]
	v_pk_fma_f32 v[38:39], v[18:19], v[190:191], v[38:39] op_sel:[0,1,0]
	v_pk_fma_f32 v[4:5], v[64:65], v[190:191], v[4:5] op_sel:[0,1,0]
	v_pk_fma_f32 v[6:7], v[66:67], v[190:191], v[6:7] op_sel:[0,1,0]
	v_cvt_scalef32_pk_f32_fp4 v[8:9], v59, 1.0
	v_cvt_scalef32_pk_f32_fp4 v[10:11], v59, 1.0 op_sel:[1,0,0]
	v_cvt_scalef32_pk_f32_fp4 v[12:13], v59, 1.0 op_sel:[0,1,0]
	v_cvt_scalef32_pk_f32_fp4 v[14:15], v59, 1.0 op_sel:[1,1,0]
	v_pk_fma_f32 v[32:33], v[68:69], v[190:191], v[32:33] op_sel:[0,1,0]
	v_pk_fma_f32 v[34:35], v[70:71], v[190:191], v[34:35] op_sel:[0,1,0]
	v_pk_fma_f32 v[28:29], v[72:73], v[190:191], v[28:29] op_sel:[0,1,0]
	v_pk_fma_f32 v[30:31], v[74:75], v[190:191], v[30:31] op_sel:[0,1,0]
	v_pk_fma_f32 v[20:21], v[8:9], v[190:191], v[20:21] op_sel:[0,1,0]
	v_pk_fma_f32 v[22:23], v[10:11], v[190:191], v[22:23] op_sel:[0,1,0]
	v_pk_fma_f32 v[0:1], v[12:13], v[190:191], v[0:1] op_sel:[0,1,0]
	v_pk_fma_f32 v[2:3], v[14:15], v[190:191], v[2:3] op_sel:[0,1,0]
	s_waitcnt vmcnt(11) lgkmcnt(2)
	v_cvt_scalef32_pk_f32_fp4 v[8:9], v60, 1.0
	v_cvt_scalef32_pk_f32_fp4 v[10:11], v60, 1.0 op_sel:[1,0,0]
	v_cvt_scalef32_pk_f32_fp4 v[12:13], v60, 1.0 op_sel:[0,1,0]
	v_cvt_scalef32_pk_f32_fp4 v[14:15], v60, 1.0 op_sel:[1,1,0]
	v_cvt_scalef32_pk_f32_fp4 v[16:17], v61, 1.0
	v_cvt_scalef32_pk_f32_fp4 v[18:19], v61, 1.0 op_sel:[1,0,0]
	v_cvt_scalef32_pk_f32_fp4 v[64:65], v61, 1.0 op_sel:[0,1,0]
	v_cvt_scalef32_pk_f32_fp4 v[66:67], v61, 1.0 op_sel:[1,1,0]
	v_pk_fma_f32 v[24:25], v[8:9], v[192:193], v[24:25] op_sel_hi:[1,0,1]
	v_pk_fma_f32 v[26:27], v[10:11], v[192:193], v[26:27] op_sel_hi:[1,0,1]
	v_pk_fma_f32 v[40:41], v[12:13], v[192:193], v[40:41] op_sel_hi:[1,0,1]
	v_pk_fma_f32 v[42:43], v[14:15], v[192:193], v[42:43] op_sel_hi:[1,0,1]
	v_cvt_scalef32_pk_f32_fp4 v[68:69], v62, 1.0
	v_cvt_scalef32_pk_f32_fp4 v[70:71], v62, 1.0 op_sel:[1,0,0]
	v_cvt_scalef32_pk_f32_fp4 v[72:73], v62, 1.0 op_sel:[0,1,0]
	v_cvt_scalef32_pk_f32_fp4 v[74:75], v62, 1.0 op_sel:[1,1,0]
	v_pk_fma_f32 v[36:37], v[16:17], v[192:193], v[36:37] op_sel_hi:[1,0,1]
	v_pk_fma_f32 v[38:39], v[18:19], v[192:193], v[38:39] op_sel_hi:[1,0,1]
	v_pk_fma_f32 v[4:5], v[64:65], v[192:193], v[4:5] op_sel_hi:[1,0,1]
	v_pk_fma_f32 v[6:7], v[66:67], v[192:193], v[6:7] op_sel_hi:[1,0,1]
	v_cvt_scalef32_pk_f32_fp4 v[8:9], v63, 1.0
	v_cvt_scalef32_pk_f32_fp4 v[10:11], v63, 1.0 op_sel:[1,0,0]
	v_cvt_scalef32_pk_f32_fp4 v[12:13], v63, 1.0 op_sel:[0,1,0]
	v_cvt_scalef32_pk_f32_fp4 v[14:15], v63, 1.0 op_sel:[1,1,0]
	v_pk_fma_f32 v[32:33], v[68:69], v[192:193], v[32:33] op_sel_hi:[1,0,1]
	v_pk_fma_f32 v[34:35], v[70:71], v[192:193], v[34:35] op_sel_hi:[1,0,1]
	v_pk_fma_f32 v[28:29], v[72:73], v[192:193], v[28:29] op_sel_hi:[1,0,1]
	v_pk_fma_f32 v[30:31], v[74:75], v[192:193], v[30:31] op_sel_hi:[1,0,1]
	v_pk_fma_f32 v[20:21], v[8:9], v[192:193], v[20:21] op_sel_hi:[1,0,1]
	v_pk_fma_f32 v[22:23], v[10:11], v[192:193], v[22:23] op_sel_hi:[1,0,1]
	v_pk_fma_f32 v[0:1], v[12:13], v[192:193], v[0:1] op_sel_hi:[1,0,1]
	v_pk_fma_f32 v[2:3], v[14:15], v[192:193], v[2:3] op_sel_hi:[1,0,1]
	s_waitcnt vmcnt(10)
	v_cvt_scalef32_pk_f32_fp4 v[8:9], v76, 1.0
	v_cvt_scalef32_pk_f32_fp4 v[10:11], v76, 1.0 op_sel:[1,0,0]
	v_cvt_scalef32_pk_f32_fp4 v[12:13], v76, 1.0 op_sel:[0,1,0]
	v_cvt_scalef32_pk_f32_fp4 v[14:15], v76, 1.0 op_sel:[1,1,0]
	v_cvt_scalef32_pk_f32_fp4 v[16:17], v77, 1.0
	v_cvt_scalef32_pk_f32_fp4 v[18:19], v77, 1.0 op_sel:[1,0,0]
	v_cvt_scalef32_pk_f32_fp4 v[64:65], v77, 1.0 op_sel:[0,1,0]
	v_cvt_scalef32_pk_f32_fp4 v[66:67], v77, 1.0 op_sel:[1,1,0]
	v_pk_fma_f32 v[24:25], v[8:9], v[192:193], v[24:25] op_sel:[0,1,0]
	v_pk_fma_f32 v[26:27], v[10:11], v[192:193], v[26:27] op_sel:[0,1,0]
	v_pk_fma_f32 v[40:41], v[12:13], v[192:193], v[40:41] op_sel:[0,1,0]
	v_pk_fma_f32 v[42:43], v[14:15], v[192:193], v[42:43] op_sel:[0,1,0]
	v_cvt_scalef32_pk_f32_fp4 v[68:69], v78, 1.0
	v_cvt_scalef32_pk_f32_fp4 v[70:71], v78, 1.0 op_sel:[1,0,0]
	v_cvt_scalef32_pk_f32_fp4 v[72:73], v78, 1.0 op_sel:[0,1,0]
	v_cvt_scalef32_pk_f32_fp4 v[74:75], v78, 1.0 op_sel:[1,1,0]
	v_pk_fma_f32 v[36:37], v[16:17], v[192:193], v[36:37] op_sel:[0,1,0]
	v_pk_fma_f32 v[38:39], v[18:19], v[192:193], v[38:39] op_sel:[0,1,0]
	v_pk_fma_f32 v[4:5], v[64:65], v[192:193], v[4:5] op_sel:[0,1,0]
	v_pk_fma_f32 v[6:7], v[66:67], v[192:193], v[6:7] op_sel:[0,1,0]
	v_cvt_scalef32_pk_f32_fp4 v[8:9], v79, 1.0
	v_cvt_scalef32_pk_f32_fp4 v[10:11], v79, 1.0 op_sel:[1,0,0]
	v_cvt_scalef32_pk_f32_fp4 v[12:13], v79, 1.0 op_sel:[0,1,0]
	v_cvt_scalef32_pk_f32_fp4 v[14:15], v79, 1.0 op_sel:[1,1,0]
	v_pk_fma_f32 v[32:33], v[68:69], v[192:193], v[32:33] op_sel:[0,1,0]
	v_pk_fma_f32 v[34:35], v[70:71], v[192:193], v[34:35] op_sel:[0,1,0]
	v_pk_fma_f32 v[28:29], v[72:73], v[192:193], v[28:29] op_sel:[0,1,0]
	v_pk_fma_f32 v[30:31], v[74:75], v[192:193], v[30:31] op_sel:[0,1,0]
	v_pk_fma_f32 v[20:21], v[8:9], v[192:193], v[20:21] op_sel:[0,1,0]
	v_pk_fma_f32 v[22:23], v[10:11], v[192:193], v[22:23] op_sel:[0,1,0]
	v_pk_fma_f32 v[0:1], v[12:13], v[192:193], v[0:1] op_sel:[0,1,0]
	v_pk_fma_f32 v[2:3], v[14:15], v[192:193], v[2:3] op_sel:[0,1,0]
	s_waitcnt vmcnt(9)
	v_cvt_scalef32_pk_f32_fp4 v[8:9], v80, 1.0
	v_cvt_scalef32_pk_f32_fp4 v[10:11], v80, 1.0 op_sel:[1,0,0]
	v_cvt_scalef32_pk_f32_fp4 v[12:13], v80, 1.0 op_sel:[0,1,0]
	v_cvt_scalef32_pk_f32_fp4 v[14:15], v80, 1.0 op_sel:[1,1,0]
	v_cvt_scalef32_pk_f32_fp4 v[16:17], v81, 1.0
	v_cvt_scalef32_pk_f32_fp4 v[18:19], v81, 1.0 op_sel:[1,0,0]
	v_cvt_scalef32_pk_f32_fp4 v[64:65], v81, 1.0 op_sel:[0,1,0]
	v_cvt_scalef32_pk_f32_fp4 v[66:67], v81, 1.0 op_sel:[1,1,0]
	v_pk_fma_f32 v[24:25], v[8:9], v[194:195], v[24:25] op_sel_hi:[1,0,1]
	v_pk_fma_f32 v[26:27], v[10:11], v[194:195], v[26:27] op_sel_hi:[1,0,1]
	v_pk_fma_f32 v[40:41], v[12:13], v[194:195], v[40:41] op_sel_hi:[1,0,1]
	v_pk_fma_f32 v[42:43], v[14:15], v[194:195], v[42:43] op_sel_hi:[1,0,1]
	v_cvt_scalef32_pk_f32_fp4 v[68:69], v82, 1.0
	v_cvt_scalef32_pk_f32_fp4 v[70:71], v82, 1.0 op_sel:[1,0,0]
	v_cvt_scalef32_pk_f32_fp4 v[72:73], v82, 1.0 op_sel:[0,1,0]
	v_cvt_scalef32_pk_f32_fp4 v[74:75], v82, 1.0 op_sel:[1,1,0]
	v_pk_fma_f32 v[36:37], v[16:17], v[194:195], v[36:37] op_sel_hi:[1,0,1]
	v_pk_fma_f32 v[38:39], v[18:19], v[194:195], v[38:39] op_sel_hi:[1,0,1]
	v_pk_fma_f32 v[4:5], v[64:65], v[194:195], v[4:5] op_sel_hi:[1,0,1]
	v_pk_fma_f32 v[6:7], v[66:67], v[194:195], v[6:7] op_sel_hi:[1,0,1]
	v_cvt_scalef32_pk_f32_fp4 v[8:9], v83, 1.0
	v_cvt_scalef32_pk_f32_fp4 v[10:11], v83, 1.0 op_sel:[1,0,0]
	v_cvt_scalef32_pk_f32_fp4 v[12:13], v83, 1.0 op_sel:[0,1,0]
	v_cvt_scalef32_pk_f32_fp4 v[14:15], v83, 1.0 op_sel:[1,1,0]
	v_pk_fma_f32 v[32:33], v[68:69], v[194:195], v[32:33] op_sel_hi:[1,0,1]
	v_pk_fma_f32 v[34:35], v[70:71], v[194:195], v[34:35] op_sel_hi:[1,0,1]
	v_pk_fma_f32 v[28:29], v[72:73], v[194:195], v[28:29] op_sel_hi:[1,0,1]
	v_pk_fma_f32 v[30:31], v[74:75], v[194:195], v[30:31] op_sel_hi:[1,0,1]
	v_pk_fma_f32 v[20:21], v[8:9], v[194:195], v[20:21] op_sel_hi:[1,0,1]
	v_pk_fma_f32 v[22:23], v[10:11], v[194:195], v[22:23] op_sel_hi:[1,0,1]
	v_pk_fma_f32 v[0:1], v[12:13], v[194:195], v[0:1] op_sel_hi:[1,0,1]
	v_pk_fma_f32 v[2:3], v[14:15], v[194:195], v[2:3] op_sel_hi:[1,0,1]
	s_waitcnt vmcnt(8)
	v_cvt_scalef32_pk_f32_fp4 v[8:9], v84, 1.0
	v_cvt_scalef32_pk_f32_fp4 v[10:11], v84, 1.0 op_sel:[1,0,0]
	v_cvt_scalef32_pk_f32_fp4 v[12:13], v84, 1.0 op_sel:[0,1,0]
	v_cvt_scalef32_pk_f32_fp4 v[14:15], v84, 1.0 op_sel:[1,1,0]
	v_cvt_scalef32_pk_f32_fp4 v[16:17], v85, 1.0
	v_cvt_scalef32_pk_f32_fp4 v[18:19], v85, 1.0 op_sel:[1,0,0]
	v_cvt_scalef32_pk_f32_fp4 v[64:65], v85, 1.0 op_sel:[0,1,0]
	v_cvt_scalef32_pk_f32_fp4 v[66:67], v85, 1.0 op_sel:[1,1,0]
	v_pk_fma_f32 v[24:25], v[8:9], v[194:195], v[24:25] op_sel:[0,1,0]
	v_pk_fma_f32 v[26:27], v[10:11], v[194:195], v[26:27] op_sel:[0,1,0]
	v_pk_fma_f32 v[40:41], v[12:13], v[194:195], v[40:41] op_sel:[0,1,0]
	v_pk_fma_f32 v[42:43], v[14:15], v[194:195], v[42:43] op_sel:[0,1,0]
	v_cvt_scalef32_pk_f32_fp4 v[68:69], v86, 1.0
	v_cvt_scalef32_pk_f32_fp4 v[70:71], v86, 1.0 op_sel:[1,0,0]
	v_cvt_scalef32_pk_f32_fp4 v[72:73], v86, 1.0 op_sel:[0,1,0]
	v_cvt_scalef32_pk_f32_fp4 v[74:75], v86, 1.0 op_sel:[1,1,0]
	v_pk_fma_f32 v[36:37], v[16:17], v[194:195], v[36:37] op_sel:[0,1,0]
	v_pk_fma_f32 v[38:39], v[18:19], v[194:195], v[38:39] op_sel:[0,1,0]
	v_pk_fma_f32 v[4:5], v[64:65], v[194:195], v[4:5] op_sel:[0,1,0]
	v_pk_fma_f32 v[6:7], v[66:67], v[194:195], v[6:7] op_sel:[0,1,0]
	v_cvt_scalef32_pk_f32_fp4 v[8:9], v87, 1.0
	v_cvt_scalef32_pk_f32_fp4 v[10:11], v87, 1.0 op_sel:[1,0,0]
	v_cvt_scalef32_pk_f32_fp4 v[12:13], v87, 1.0 op_sel:[0,1,0]
	v_cvt_scalef32_pk_f32_fp4 v[14:15], v87, 1.0 op_sel:[1,1,0]
	v_pk_fma_f32 v[32:33], v[68:69], v[194:195], v[32:33] op_sel:[0,1,0]
	v_pk_fma_f32 v[34:35], v[70:71], v[194:195], v[34:35] op_sel:[0,1,0]
	v_pk_fma_f32 v[28:29], v[72:73], v[194:195], v[28:29] op_sel:[0,1,0]
	v_pk_fma_f32 v[30:31], v[74:75], v[194:195], v[30:31] op_sel:[0,1,0]
	v_pk_fma_f32 v[20:21], v[8:9], v[194:195], v[20:21] op_sel:[0,1,0]
	v_pk_fma_f32 v[22:23], v[10:11], v[194:195], v[22:23] op_sel:[0,1,0]
	v_pk_fma_f32 v[0:1], v[12:13], v[194:195], v[0:1] op_sel:[0,1,0]
	v_pk_fma_f32 v[2:3], v[14:15], v[194:195], v[2:3] op_sel:[0,1,0]
	s_waitcnt vmcnt(7) lgkmcnt(1)
	v_cvt_scalef32_pk_f32_fp4 v[8:9], v88, 1.0
	v_cvt_scalef32_pk_f32_fp4 v[10:11], v88, 1.0 op_sel:[1,0,0]
	v_cvt_scalef32_pk_f32_fp4 v[12:13], v88, 1.0 op_sel:[0,1,0]
	v_cvt_scalef32_pk_f32_fp4 v[14:15], v88, 1.0 op_sel:[1,1,0]
	v_cvt_scalef32_pk_f32_fp4 v[16:17], v89, 1.0
	v_cvt_scalef32_pk_f32_fp4 v[18:19], v89, 1.0 op_sel:[1,0,0]
	v_cvt_scalef32_pk_f32_fp4 v[64:65], v89, 1.0 op_sel:[0,1,0]
	v_cvt_scalef32_pk_f32_fp4 v[66:67], v89, 1.0 op_sel:[1,1,0]
	v_pk_fma_f32 v[24:25], v[8:9], v[240:241], v[24:25] op_sel_hi:[1,0,1]
	v_pk_fma_f32 v[26:27], v[10:11], v[240:241], v[26:27] op_sel_hi:[1,0,1]
	v_pk_fma_f32 v[40:41], v[12:13], v[240:241], v[40:41] op_sel_hi:[1,0,1]
	v_pk_fma_f32 v[42:43], v[14:15], v[240:241], v[42:43] op_sel_hi:[1,0,1]
	v_cvt_scalef32_pk_f32_fp4 v[68:69], v90, 1.0
	v_cvt_scalef32_pk_f32_fp4 v[70:71], v90, 1.0 op_sel:[1,0,0]
	v_cvt_scalef32_pk_f32_fp4 v[72:73], v90, 1.0 op_sel:[0,1,0]
	v_cvt_scalef32_pk_f32_fp4 v[74:75], v90, 1.0 op_sel:[1,1,0]
	v_pk_fma_f32 v[36:37], v[16:17], v[240:241], v[36:37] op_sel_hi:[1,0,1]
	v_pk_fma_f32 v[38:39], v[18:19], v[240:241], v[38:39] op_sel_hi:[1,0,1]
	v_pk_fma_f32 v[4:5], v[64:65], v[240:241], v[4:5] op_sel_hi:[1,0,1]
	v_pk_fma_f32 v[6:7], v[66:67], v[240:241], v[6:7] op_sel_hi:[1,0,1]
	v_cvt_scalef32_pk_f32_fp4 v[8:9], v91, 1.0
	v_cvt_scalef32_pk_f32_fp4 v[10:11], v91, 1.0 op_sel:[1,0,0]
	v_cvt_scalef32_pk_f32_fp4 v[12:13], v91, 1.0 op_sel:[0,1,0]
	v_cvt_scalef32_pk_f32_fp4 v[14:15], v91, 1.0 op_sel:[1,1,0]
	v_pk_fma_f32 v[32:33], v[68:69], v[240:241], v[32:33] op_sel_hi:[1,0,1]
	v_pk_fma_f32 v[34:35], v[70:71], v[240:241], v[34:35] op_sel_hi:[1,0,1]
	v_pk_fma_f32 v[28:29], v[72:73], v[240:241], v[28:29] op_sel_hi:[1,0,1]
	v_pk_fma_f32 v[30:31], v[74:75], v[240:241], v[30:31] op_sel_hi:[1,0,1]
	v_pk_fma_f32 v[20:21], v[8:9], v[240:241], v[20:21] op_sel_hi:[1,0,1]
	v_pk_fma_f32 v[22:23], v[10:11], v[240:241], v[22:23] op_sel_hi:[1,0,1]
	v_pk_fma_f32 v[0:1], v[12:13], v[240:241], v[0:1] op_sel_hi:[1,0,1]
	v_pk_fma_f32 v[2:3], v[14:15], v[240:241], v[2:3] op_sel_hi:[1,0,1]
	s_waitcnt vmcnt(6)
	v_cvt_scalef32_pk_f32_fp4 v[8:9], v92, 1.0
	v_cvt_scalef32_pk_f32_fp4 v[10:11], v92, 1.0 op_sel:[1,0,0]
	v_cvt_scalef32_pk_f32_fp4 v[12:13], v92, 1.0 op_sel:[0,1,0]
	v_cvt_scalef32_pk_f32_fp4 v[14:15], v92, 1.0 op_sel:[1,1,0]
	v_cvt_scalef32_pk_f32_fp4 v[16:17], v93, 1.0
	v_cvt_scalef32_pk_f32_fp4 v[18:19], v93, 1.0 op_sel:[1,0,0]
	v_cvt_scalef32_pk_f32_fp4 v[64:65], v93, 1.0 op_sel:[0,1,0]
	v_cvt_scalef32_pk_f32_fp4 v[66:67], v93, 1.0 op_sel:[1,1,0]
	v_pk_fma_f32 v[24:25], v[8:9], v[240:241], v[24:25] op_sel:[0,1,0]
	v_pk_fma_f32 v[26:27], v[10:11], v[240:241], v[26:27] op_sel:[0,1,0]
	v_pk_fma_f32 v[40:41], v[12:13], v[240:241], v[40:41] op_sel:[0,1,0]
	v_pk_fma_f32 v[42:43], v[14:15], v[240:241], v[42:43] op_sel:[0,1,0]
	v_cvt_scalef32_pk_f32_fp4 v[68:69], v94, 1.0
	v_cvt_scalef32_pk_f32_fp4 v[70:71], v94, 1.0 op_sel:[1,0,0]
	v_cvt_scalef32_pk_f32_fp4 v[72:73], v94, 1.0 op_sel:[0,1,0]
	v_cvt_scalef32_pk_f32_fp4 v[74:75], v94, 1.0 op_sel:[1,1,0]
	v_pk_fma_f32 v[36:37], v[16:17], v[240:241], v[36:37] op_sel:[0,1,0]
	v_pk_fma_f32 v[38:39], v[18:19], v[240:241], v[38:39] op_sel:[0,1,0]
	v_pk_fma_f32 v[4:5], v[64:65], v[240:241], v[4:5] op_sel:[0,1,0]
	v_pk_fma_f32 v[6:7], v[66:67], v[240:241], v[6:7] op_sel:[0,1,0]
	v_cvt_scalef32_pk_f32_fp4 v[8:9], v95, 1.0
	v_cvt_scalef32_pk_f32_fp4 v[10:11], v95, 1.0 op_sel:[1,0,0]
	v_cvt_scalef32_pk_f32_fp4 v[12:13], v95, 1.0 op_sel:[0,1,0]
	v_cvt_scalef32_pk_f32_fp4 v[14:15], v95, 1.0 op_sel:[1,1,0]
	v_pk_fma_f32 v[32:33], v[68:69], v[240:241], v[32:33] op_sel:[0,1,0]
	v_pk_fma_f32 v[34:35], v[70:71], v[240:241], v[34:35] op_sel:[0,1,0]
	v_pk_fma_f32 v[28:29], v[72:73], v[240:241], v[28:29] op_sel:[0,1,0]
	v_pk_fma_f32 v[30:31], v[74:75], v[240:241], v[30:31] op_sel:[0,1,0]
	v_pk_fma_f32 v[20:21], v[8:9], v[240:241], v[20:21] op_sel:[0,1,0]
	v_pk_fma_f32 v[22:23], v[10:11], v[240:241], v[22:23] op_sel:[0,1,0]
	v_pk_fma_f32 v[0:1], v[12:13], v[240:241], v[0:1] op_sel:[0,1,0]
	v_pk_fma_f32 v[2:3], v[14:15], v[240:241], v[2:3] op_sel:[0,1,0]
	s_waitcnt vmcnt(5)
	v_cvt_scalef32_pk_f32_fp4 v[8:9], v96, 1.0
	v_cvt_scalef32_pk_f32_fp4 v[10:11], v96, 1.0 op_sel:[1,0,0]
	v_cvt_scalef32_pk_f32_fp4 v[12:13], v96, 1.0 op_sel:[0,1,0]
	v_cvt_scalef32_pk_f32_fp4 v[14:15], v96, 1.0 op_sel:[1,1,0]
	v_cvt_scalef32_pk_f32_fp4 v[16:17], v97, 1.0
	v_cvt_scalef32_pk_f32_fp4 v[18:19], v97, 1.0 op_sel:[1,0,0]
	v_cvt_scalef32_pk_f32_fp4 v[64:65], v97, 1.0 op_sel:[0,1,0]
	v_cvt_scalef32_pk_f32_fp4 v[66:67], v97, 1.0 op_sel:[1,1,0]
	v_pk_fma_f32 v[24:25], v[8:9], v[242:243], v[24:25] op_sel_hi:[1,0,1]
	v_pk_fma_f32 v[26:27], v[10:11], v[242:243], v[26:27] op_sel_hi:[1,0,1]
	v_pk_fma_f32 v[40:41], v[12:13], v[242:243], v[40:41] op_sel_hi:[1,0,1]
	v_pk_fma_f32 v[42:43], v[14:15], v[242:243], v[42:43] op_sel_hi:[1,0,1]
	v_cvt_scalef32_pk_f32_fp4 v[68:69], v98, 1.0
	v_cvt_scalef32_pk_f32_fp4 v[70:71], v98, 1.0 op_sel:[1,0,0]
	v_cvt_scalef32_pk_f32_fp4 v[72:73], v98, 1.0 op_sel:[0,1,0]
	v_cvt_scalef32_pk_f32_fp4 v[74:75], v98, 1.0 op_sel:[1,1,0]
	v_pk_fma_f32 v[36:37], v[16:17], v[242:243], v[36:37] op_sel_hi:[1,0,1]
	v_pk_fma_f32 v[38:39], v[18:19], v[242:243], v[38:39] op_sel_hi:[1,0,1]
	v_pk_fma_f32 v[4:5], v[64:65], v[242:243], v[4:5] op_sel_hi:[1,0,1]
	v_pk_fma_f32 v[6:7], v[66:67], v[242:243], v[6:7] op_sel_hi:[1,0,1]
	v_cvt_scalef32_pk_f32_fp4 v[8:9], v99, 1.0
	v_cvt_scalef32_pk_f32_fp4 v[10:11], v99, 1.0 op_sel:[1,0,0]
	v_cvt_scalef32_pk_f32_fp4 v[12:13], v99, 1.0 op_sel:[0,1,0]
	v_cvt_scalef32_pk_f32_fp4 v[14:15], v99, 1.0 op_sel:[1,1,0]
	v_pk_fma_f32 v[32:33], v[68:69], v[242:243], v[32:33] op_sel_hi:[1,0,1]
	v_pk_fma_f32 v[34:35], v[70:71], v[242:243], v[34:35] op_sel_hi:[1,0,1]
	v_pk_fma_f32 v[28:29], v[72:73], v[242:243], v[28:29] op_sel_hi:[1,0,1]
	v_pk_fma_f32 v[30:31], v[74:75], v[242:243], v[30:31] op_sel_hi:[1,0,1]
	v_pk_fma_f32 v[20:21], v[8:9], v[242:243], v[20:21] op_sel_hi:[1,0,1]
	v_pk_fma_f32 v[22:23], v[10:11], v[242:243], v[22:23] op_sel_hi:[1,0,1]
	v_pk_fma_f32 v[0:1], v[12:13], v[242:243], v[0:1] op_sel_hi:[1,0,1]
	v_pk_fma_f32 v[2:3], v[14:15], v[242:243], v[2:3] op_sel_hi:[1,0,1]
	s_waitcnt vmcnt(4)
	v_cvt_scalef32_pk_f32_fp4 v[8:9], v100, 1.0
	v_cvt_scalef32_pk_f32_fp4 v[10:11], v100, 1.0 op_sel:[1,0,0]
	v_cvt_scalef32_pk_f32_fp4 v[12:13], v100, 1.0 op_sel:[0,1,0]
	v_cvt_scalef32_pk_f32_fp4 v[14:15], v100, 1.0 op_sel:[1,1,0]
	v_cvt_scalef32_pk_f32_fp4 v[16:17], v101, 1.0
	v_cvt_scalef32_pk_f32_fp4 v[18:19], v101, 1.0 op_sel:[1,0,0]
	v_cvt_scalef32_pk_f32_fp4 v[64:65], v101, 1.0 op_sel:[0,1,0]
	v_cvt_scalef32_pk_f32_fp4 v[66:67], v101, 1.0 op_sel:[1,1,0]
	v_pk_fma_f32 v[24:25], v[8:9], v[242:243], v[24:25] op_sel:[0,1,0]
	v_pk_fma_f32 v[26:27], v[10:11], v[242:243], v[26:27] op_sel:[0,1,0]
	v_pk_fma_f32 v[40:41], v[12:13], v[242:243], v[40:41] op_sel:[0,1,0]
	v_pk_fma_f32 v[42:43], v[14:15], v[242:243], v[42:43] op_sel:[0,1,0]
	v_cvt_scalef32_pk_f32_fp4 v[68:69], v102, 1.0
	v_cvt_scalef32_pk_f32_fp4 v[70:71], v102, 1.0 op_sel:[1,0,0]
	v_cvt_scalef32_pk_f32_fp4 v[72:73], v102, 1.0 op_sel:[0,1,0]
	v_cvt_scalef32_pk_f32_fp4 v[74:75], v102, 1.0 op_sel:[1,1,0]
	v_pk_fma_f32 v[36:37], v[16:17], v[242:243], v[36:37] op_sel:[0,1,0]
	v_pk_fma_f32 v[38:39], v[18:19], v[242:243], v[38:39] op_sel:[0,1,0]
	v_pk_fma_f32 v[4:5], v[64:65], v[242:243], v[4:5] op_sel:[0,1,0]
	v_pk_fma_f32 v[6:7], v[66:67], v[242:243], v[6:7] op_sel:[0,1,0]
	v_cvt_scalef32_pk_f32_fp4 v[8:9], v103, 1.0
	v_cvt_scalef32_pk_f32_fp4 v[10:11], v103, 1.0 op_sel:[1,0,0]
	v_cvt_scalef32_pk_f32_fp4 v[12:13], v103, 1.0 op_sel:[0,1,0]
	v_cvt_scalef32_pk_f32_fp4 v[14:15], v103, 1.0 op_sel:[1,1,0]
	v_pk_fma_f32 v[32:33], v[68:69], v[242:243], v[32:33] op_sel:[0,1,0]
	v_pk_fma_f32 v[34:35], v[70:71], v[242:243], v[34:35] op_sel:[0,1,0]
	v_pk_fma_f32 v[28:29], v[72:73], v[242:243], v[28:29] op_sel:[0,1,0]
	v_pk_fma_f32 v[30:31], v[74:75], v[242:243], v[30:31] op_sel:[0,1,0]
	v_pk_fma_f32 v[20:21], v[8:9], v[242:243], v[20:21] op_sel:[0,1,0]
	v_pk_fma_f32 v[22:23], v[10:11], v[242:243], v[22:23] op_sel:[0,1,0]
	v_pk_fma_f32 v[0:1], v[12:13], v[242:243], v[0:1] op_sel:[0,1,0]
	v_pk_fma_f32 v[2:3], v[14:15], v[242:243], v[2:3] op_sel:[0,1,0]
	s_waitcnt vmcnt(3) lgkmcnt(0)
	v_cvt_scalef32_pk_f32_fp4 v[8:9], v172, 1.0
	v_cvt_scalef32_pk_f32_fp4 v[10:11], v172, 1.0 op_sel:[1,0,0]
	v_cvt_scalef32_pk_f32_fp4 v[12:13], v172, 1.0 op_sel:[0,1,0]
	v_cvt_scalef32_pk_f32_fp4 v[14:15], v172, 1.0 op_sel:[1,1,0]
	v_cvt_scalef32_pk_f32_fp4 v[16:17], v173, 1.0
	v_cvt_scalef32_pk_f32_fp4 v[18:19], v173, 1.0 op_sel:[1,0,0]
	v_cvt_scalef32_pk_f32_fp4 v[64:65], v173, 1.0 op_sel:[0,1,0]
	v_cvt_scalef32_pk_f32_fp4 v[66:67], v173, 1.0 op_sel:[1,1,0]
	v_pk_fma_f32 v[24:25], v[8:9], v[244:245], v[24:25] op_sel_hi:[1,0,1]
	v_pk_fma_f32 v[26:27], v[10:11], v[244:245], v[26:27] op_sel_hi:[1,0,1]
	v_pk_fma_f32 v[40:41], v[12:13], v[244:245], v[40:41] op_sel_hi:[1,0,1]
	v_pk_fma_f32 v[42:43], v[14:15], v[244:245], v[42:43] op_sel_hi:[1,0,1]
	v_cvt_scalef32_pk_f32_fp4 v[68:69], v174, 1.0
	v_cvt_scalef32_pk_f32_fp4 v[70:71], v174, 1.0 op_sel:[1,0,0]
	v_cvt_scalef32_pk_f32_fp4 v[72:73], v174, 1.0 op_sel:[0,1,0]
	v_cvt_scalef32_pk_f32_fp4 v[74:75], v174, 1.0 op_sel:[1,1,0]
	v_pk_fma_f32 v[36:37], v[16:17], v[244:245], v[36:37] op_sel_hi:[1,0,1]
	v_pk_fma_f32 v[38:39], v[18:19], v[244:245], v[38:39] op_sel_hi:[1,0,1]
	v_pk_fma_f32 v[4:5], v[64:65], v[244:245], v[4:5] op_sel_hi:[1,0,1]
	v_pk_fma_f32 v[6:7], v[66:67], v[244:245], v[6:7] op_sel_hi:[1,0,1]
	v_cvt_scalef32_pk_f32_fp4 v[8:9], v175, 1.0
	v_cvt_scalef32_pk_f32_fp4 v[10:11], v175, 1.0 op_sel:[1,0,0]
	v_cvt_scalef32_pk_f32_fp4 v[12:13], v175, 1.0 op_sel:[0,1,0]
	v_cvt_scalef32_pk_f32_fp4 v[14:15], v175, 1.0 op_sel:[1,1,0]
	v_pk_fma_f32 v[32:33], v[68:69], v[244:245], v[32:33] op_sel_hi:[1,0,1]
	v_pk_fma_f32 v[34:35], v[70:71], v[244:245], v[34:35] op_sel_hi:[1,0,1]
	v_pk_fma_f32 v[28:29], v[72:73], v[244:245], v[28:29] op_sel_hi:[1,0,1]
	v_pk_fma_f32 v[30:31], v[74:75], v[244:245], v[30:31] op_sel_hi:[1,0,1]
	v_pk_fma_f32 v[20:21], v[8:9], v[244:245], v[20:21] op_sel_hi:[1,0,1]
	v_pk_fma_f32 v[22:23], v[10:11], v[244:245], v[22:23] op_sel_hi:[1,0,1]
	v_pk_fma_f32 v[0:1], v[12:13], v[244:245], v[0:1] op_sel_hi:[1,0,1]
	v_pk_fma_f32 v[2:3], v[14:15], v[244:245], v[2:3] op_sel_hi:[1,0,1]
	s_waitcnt vmcnt(2)
	v_cvt_scalef32_pk_f32_fp4 v[8:9], v176, 1.0
	v_cvt_scalef32_pk_f32_fp4 v[10:11], v176, 1.0 op_sel:[1,0,0]
	v_cvt_scalef32_pk_f32_fp4 v[12:13], v176, 1.0 op_sel:[0,1,0]
	v_cvt_scalef32_pk_f32_fp4 v[14:15], v176, 1.0 op_sel:[1,1,0]
	v_cvt_scalef32_pk_f32_fp4 v[16:17], v177, 1.0
	v_cvt_scalef32_pk_f32_fp4 v[18:19], v177, 1.0 op_sel:[1,0,0]
	v_cvt_scalef32_pk_f32_fp4 v[64:65], v177, 1.0 op_sel:[0,1,0]
	v_cvt_scalef32_pk_f32_fp4 v[66:67], v177, 1.0 op_sel:[1,1,0]
	v_pk_fma_f32 v[24:25], v[8:9], v[244:245], v[24:25] op_sel:[0,1,0]
	v_pk_fma_f32 v[26:27], v[10:11], v[244:245], v[26:27] op_sel:[0,1,0]
	v_pk_fma_f32 v[40:41], v[12:13], v[244:245], v[40:41] op_sel:[0,1,0]
	v_pk_fma_f32 v[42:43], v[14:15], v[244:245], v[42:43] op_sel:[0,1,0]
	v_cvt_scalef32_pk_f32_fp4 v[68:69], v178, 1.0
	v_cvt_scalef32_pk_f32_fp4 v[70:71], v178, 1.0 op_sel:[1,0,0]
	v_cvt_scalef32_pk_f32_fp4 v[72:73], v178, 1.0 op_sel:[0,1,0]
	v_cvt_scalef32_pk_f32_fp4 v[74:75], v178, 1.0 op_sel:[1,1,0]
	v_pk_fma_f32 v[36:37], v[16:17], v[244:245], v[36:37] op_sel:[0,1,0]
	v_pk_fma_f32 v[38:39], v[18:19], v[244:245], v[38:39] op_sel:[0,1,0]
	v_pk_fma_f32 v[4:5], v[64:65], v[244:245], v[4:5] op_sel:[0,1,0]
	v_pk_fma_f32 v[6:7], v[66:67], v[244:245], v[6:7] op_sel:[0,1,0]
	v_cvt_scalef32_pk_f32_fp4 v[8:9], v179, 1.0
	v_cvt_scalef32_pk_f32_fp4 v[10:11], v179, 1.0 op_sel:[1,0,0]
	v_cvt_scalef32_pk_f32_fp4 v[12:13], v179, 1.0 op_sel:[0,1,0]
	v_cvt_scalef32_pk_f32_fp4 v[14:15], v179, 1.0 op_sel:[1,1,0]
	v_pk_fma_f32 v[32:33], v[68:69], v[244:245], v[32:33] op_sel:[0,1,0]
	v_pk_fma_f32 v[34:35], v[70:71], v[244:245], v[34:35] op_sel:[0,1,0]
	v_pk_fma_f32 v[28:29], v[72:73], v[244:245], v[28:29] op_sel:[0,1,0]
	v_pk_fma_f32 v[30:31], v[74:75], v[244:245], v[30:31] op_sel:[0,1,0]
	v_pk_fma_f32 v[20:21], v[8:9], v[244:245], v[20:21] op_sel:[0,1,0]
	v_pk_fma_f32 v[22:23], v[10:11], v[244:245], v[22:23] op_sel:[0,1,0]
	v_pk_fma_f32 v[0:1], v[12:13], v[244:245], v[0:1] op_sel:[0,1,0]
	v_pk_fma_f32 v[2:3], v[14:15], v[244:245], v[2:3] op_sel:[0,1,0]
	s_waitcnt vmcnt(1)
	v_cvt_scalef32_pk_f32_fp4 v[8:9], v180, 1.0
	v_cvt_scalef32_pk_f32_fp4 v[10:11], v180, 1.0 op_sel:[1,0,0]
	v_cvt_scalef32_pk_f32_fp4 v[12:13], v180, 1.0 op_sel:[0,1,0]
	v_cvt_scalef32_pk_f32_fp4 v[14:15], v180, 1.0 op_sel:[1,1,0]
	v_cvt_scalef32_pk_f32_fp4 v[16:17], v181, 1.0
	v_cvt_scalef32_pk_f32_fp4 v[18:19], v181, 1.0 op_sel:[1,0,0]
	v_cvt_scalef32_pk_f32_fp4 v[64:65], v181, 1.0 op_sel:[0,1,0]
	v_cvt_scalef32_pk_f32_fp4 v[66:67], v181, 1.0 op_sel:[1,1,0]
	v_pk_fma_f32 v[24:25], v[8:9], v[246:247], v[24:25] op_sel_hi:[1,0,1]
	v_pk_fma_f32 v[26:27], v[10:11], v[246:247], v[26:27] op_sel_hi:[1,0,1]
	v_pk_fma_f32 v[40:41], v[12:13], v[246:247], v[40:41] op_sel_hi:[1,0,1]
	v_pk_fma_f32 v[42:43], v[14:15], v[246:247], v[42:43] op_sel_hi:[1,0,1]
	v_cvt_scalef32_pk_f32_fp4 v[68:69], v182, 1.0
	v_cvt_scalef32_pk_f32_fp4 v[70:71], v182, 1.0 op_sel:[1,0,0]
	v_cvt_scalef32_pk_f32_fp4 v[72:73], v182, 1.0 op_sel:[0,1,0]
	v_cvt_scalef32_pk_f32_fp4 v[74:75], v182, 1.0 op_sel:[1,1,0]
	v_pk_fma_f32 v[36:37], v[16:17], v[246:247], v[36:37] op_sel_hi:[1,0,1]
	v_pk_fma_f32 v[38:39], v[18:19], v[246:247], v[38:39] op_sel_hi:[1,0,1]
	v_pk_fma_f32 v[4:5], v[64:65], v[246:247], v[4:5] op_sel_hi:[1,0,1]
	v_pk_fma_f32 v[6:7], v[66:67], v[246:247], v[6:7] op_sel_hi:[1,0,1]
	v_cvt_scalef32_pk_f32_fp4 v[8:9], v183, 1.0
	v_cvt_scalef32_pk_f32_fp4 v[10:11], v183, 1.0 op_sel:[1,0,0]
	v_cvt_scalef32_pk_f32_fp4 v[12:13], v183, 1.0 op_sel:[0,1,0]
	v_cvt_scalef32_pk_f32_fp4 v[14:15], v183, 1.0 op_sel:[1,1,0]
	v_pk_fma_f32 v[32:33], v[68:69], v[246:247], v[32:33] op_sel_hi:[1,0,1]
	v_pk_fma_f32 v[34:35], v[70:71], v[246:247], v[34:35] op_sel_hi:[1,0,1]
	v_pk_fma_f32 v[28:29], v[72:73], v[246:247], v[28:29] op_sel_hi:[1,0,1]
	v_pk_fma_f32 v[30:31], v[74:75], v[246:247], v[30:31] op_sel_hi:[1,0,1]
	v_pk_fma_f32 v[20:21], v[8:9], v[246:247], v[20:21] op_sel_hi:[1,0,1]
	v_pk_fma_f32 v[22:23], v[10:11], v[246:247], v[22:23] op_sel_hi:[1,0,1]
	v_pk_fma_f32 v[0:1], v[12:13], v[246:247], v[0:1] op_sel_hi:[1,0,1]
	v_pk_fma_f32 v[2:3], v[14:15], v[246:247], v[2:3] op_sel_hi:[1,0,1]
	s_waitcnt vmcnt(0)
	v_cvt_scalef32_pk_f32_fp4 v[8:9], v184, 1.0
	v_cvt_scalef32_pk_f32_fp4 v[10:11], v184, 1.0 op_sel:[1,0,0]
	v_cvt_scalef32_pk_f32_fp4 v[12:13], v184, 1.0 op_sel:[0,1,0]
	v_cvt_scalef32_pk_f32_fp4 v[14:15], v184, 1.0 op_sel:[1,1,0]
	v_cvt_scalef32_pk_f32_fp4 v[16:17], v185, 1.0
	v_cvt_scalef32_pk_f32_fp4 v[18:19], v185, 1.0 op_sel:[1,0,0]
	v_cvt_scalef32_pk_f32_fp4 v[64:65], v185, 1.0 op_sel:[0,1,0]
	v_cvt_scalef32_pk_f32_fp4 v[66:67], v185, 1.0 op_sel:[1,1,0]
	v_pk_fma_f32 v[24:25], v[8:9], v[246:247], v[24:25] op_sel:[0,1,0]
	v_pk_fma_f32 v[26:27], v[10:11], v[246:247], v[26:27] op_sel:[0,1,0]
	v_pk_fma_f32 v[40:41], v[12:13], v[246:247], v[40:41] op_sel:[0,1,0]
	v_pk_fma_f32 v[42:43], v[14:15], v[246:247], v[42:43] op_sel:[0,1,0]
	v_cvt_scalef32_pk_f32_fp4 v[68:69], v186, 1.0
	v_cvt_scalef32_pk_f32_fp4 v[70:71], v186, 1.0 op_sel:[1,0,0]
	v_cvt_scalef32_pk_f32_fp4 v[72:73], v186, 1.0 op_sel:[0,1,0]
	v_cvt_scalef32_pk_f32_fp4 v[74:75], v186, 1.0 op_sel:[1,1,0]
	v_pk_fma_f32 v[36:37], v[16:17], v[246:247], v[36:37] op_sel:[0,1,0]
	v_pk_fma_f32 v[38:39], v[18:19], v[246:247], v[38:39] op_sel:[0,1,0]
	v_pk_fma_f32 v[4:5], v[64:65], v[246:247], v[4:5] op_sel:[0,1,0]
	v_pk_fma_f32 v[6:7], v[66:67], v[246:247], v[6:7] op_sel:[0,1,0]
	v_cvt_scalef32_pk_f32_fp4 v[8:9], v187, 1.0
	v_cvt_scalef32_pk_f32_fp4 v[10:11], v187, 1.0 op_sel:[1,0,0]
	v_cvt_scalef32_pk_f32_fp4 v[12:13], v187, 1.0 op_sel:[0,1,0]
	v_cvt_scalef32_pk_f32_fp4 v[14:15], v187, 1.0 op_sel:[1,1,0]
	v_pk_fma_f32 v[32:33], v[68:69], v[246:247], v[32:33] op_sel:[0,1,0]
	v_pk_fma_f32 v[34:35], v[70:71], v[246:247], v[34:35] op_sel:[0,1,0]
	v_pk_fma_f32 v[28:29], v[72:73], v[246:247], v[28:29] op_sel:[0,1,0]
	v_pk_fma_f32 v[30:31], v[74:75], v[246:247], v[30:31] op_sel:[0,1,0]
	v_pk_fma_f32 v[20:21], v[8:9], v[246:247], v[20:21] op_sel:[0,1,0]
	v_pk_fma_f32 v[22:23], v[10:11], v[246:247], v[22:23] op_sel:[0,1,0]
	v_pk_fma_f32 v[0:1], v[12:13], v[246:247], v[0:1] op_sel:[0,1,0]
	v_pk_fma_f32 v[2:3], v[14:15], v[246:247], v[2:3] op_sel:[0,1,0]
	s_branch .Lp10v_epi
.Lp10v_pair:
	s_lshl_b32 s44, s64, 10
	v_add3_u32 v198, v157, s44, v112
	ds_read_b64 v[196:197], v198 offset:9728
	v_mov_b32_e32 v200, 0
	v_mov_b32_e32 v201, 0
	v_mov_b32_e32 v202, 0
	v_mov_b32_e32 v203, 0
	v_mov_b32_e32 v204, 0
	v_mov_b32_e32 v205, 0
	v_mov_b32_e32 v206, 0
	v_mov_b32_e32 v207, 0
	v_mov_b32_e32 v208, 0
	v_mov_b32_e32 v209, 0
	v_mov_b32_e32 v210, 0
	v_mov_b32_e32 v211, 0
	v_mov_b32_e32 v212, 0
	v_mov_b32_e32 v213, 0
	v_mov_b32_e32 v214, 0
	v_mov_b32_e32 v215, 0
	v_mov_b32_e32 v218, 0
	v_mov_b32_e32 v219, 0
	v_mov_b32_e32 v220, 0
	v_mov_b32_e32 v221, 0
	v_mov_b32_e32 v222, 0
	v_mov_b32_e32 v223, 0
	v_mov_b32_e32 v224, 0
	v_mov_b32_e32 v225, 0
	v_mov_b32_e32 v226, 0
	v_mov_b32_e32 v227, 0
	v_mov_b32_e32 v228, 0
	v_mov_b32_e32 v229, 0
	v_mov_b32_e32 v230, 0
	v_mov_b32_e32 v231, 0
	v_mov_b32_e32 v232, 0
	v_mov_b32_e32 v233, 0
	v_add_u32_e32 v198, 0x400, v131
	s_waitcnt lgkmcnt(0)
	s_add_i32 s45, s66, -7
	v_readlane_b32 s44, v154, s45
	s_lshl_b32 s44, s44, 10
	s_add_u32 s46, s92, s44
	s_addc_u32 s47, s93, 0
	global_load_dwordx4 v[44:47], v216, s[46:47]
	v_readlane_b32 s44, v155, s45
	s_lshl_b32 s44, s44, 10
	s_add_u32 s46, s92, s44
	s_addc_u32 s47, s93, 0
	global_load_dwordx4 v[48:51], v216, s[46:47]
	s_add_i32 s45, s66, -6
	v_readlane_b32 s44, v154, s45
	s_lshl_b32 s44, s44, 10
	s_add_u32 s46, s92, s44
	s_addc_u32 s47, s93, 0
	global_load_dwordx4 v[52:55], v216, s[46:47]
	v_readlane_b32 s44, v155, s45
	s_lshl_b32 s44, s44, 10
	s_add_u32 s46, s92, s44
	s_addc_u32 s47, s93, 0
	global_load_dwordx4 v[56:59], v216, s[46:47]
	s_add_i32 s45, s66, -5
	v_readlane_b32 s44, v154, s45
	s_lshl_b32 s44, s44, 10
	s_add_u32 s46, s92, s44
	s_addc_u32 s47, s93, 0
	global_load_dwordx4 v[60:63], v216, s[46:47]
	v_readlane_b32 s44, v155, s45
	s_lshl_b32 s44, s44, 10
	s_add_u32 s46, s92, s44
	s_addc_u32 s47, s93, 0
	global_load_dwordx4 v[76:79], v216, s[46:47]
	s_add_i32 s45, s66, -4
	v_readlane_b32 s44, v154, s45
	s_lshl_b32 s44, s44, 10
	s_add_u32 s46, s92, s44
	s_addc_u32 s47, s93, 0
	global_load_dwordx4 v[80:83], v216, s[46:47]
	v_readlane_b32 s44, v155, s45
	s_lshl_b32 s44, s44, 10
	s_add_u32 s46, s92, s44
	s_addc_u32 s47, s93, 0
	global_load_dwordx4 v[84:87], v216, s[46:47]
	s_add_i32 s45, s66, -3
	v_readlane_b32 s44, v154, s45
	s_lshl_b32 s44, s44, 10
	s_add_u32 s46, s92, s44
	s_addc_u32 s47, s93, 0
	global_load_dwordx4 v[88:91], v216, s[46:47]
	v_readlane_b32 s44, v155, s45
	s_lshl_b32 s44, s44, 10
	s_add_u32 s46, s92, s44
	s_addc_u32 s47, s93, 0
	global_load_dwordx4 v[92:95], v216, s[46:47]
	s_add_i32 s45, s66, -2
	v_readlane_b32 s44, v154, s45
	s_lshl_b32 s44, s44, 10
	s_add_u32 s46, s92, s44
	s_addc_u32 s47, s93, 0
	global_load_dwordx4 v[96:99], v216, s[46:47]
	v_readlane_b32 s44, v155, s45
	s_lshl_b32 s44, s44, 10
	s_add_u32 s46, s92, s44
	s_addc_u32 s47, s93, 0
	global_load_dwordx4 v[100:103], v216, s[46:47]
	s_add_i32 s45, s66, -1
	v_readlane_b32 s44, v154, s45
	s_lshl_b32 s44, s44, 10
	s_add_u32 s46, s92, s44
	s_addc_u32 s47, s93, 0
	global_load_dwordx4 v[172:175], v216, s[46:47]
	v_readlane_b32 s44, v155, s45
	s_lshl_b32 s44, s44, 10
	s_add_u32 s46, s92, s44
	s_addc_u32 s47, s93, 0
	global_load_dwordx4 v[176:179], v216, s[46:47]
	s_add_i32 s45, s66, 0
	v_readlane_b32 s44, v154, s45
	s_lshl_b32 s44, s44, 10
	s_add_u32 s46, s92, s44
	s_addc_u32 s47, s93, 0
	global_load_dwordx4 v[180:183], v216, s[46:47]
	v_readlane_b32 s44, v155, s45
	s_lshl_b32 s44, s44, 10
	s_add_u32 s46, s92, s44
	s_addc_u32 s47, s93, 0
	global_load_dwordx4 v[184:187], v216, s[46:47]
	ds_read_b128 v[188:191], v131 offset:0
	ds_read_b128 v[192:195], v131 offset:16
	ds_read_b128 v[240:243], v131 offset:32
	ds_read_b128 v[244:247], v131 offset:48
.Lp10vp_loop:
	s_waitcnt vmcnt(15) lgkmcnt(3)
	v_cvt_scalef32_pk_f32_fp4 v[8:9], v44, 1.0
	v_cvt_scalef32_pk_f32_fp4 v[10:11], v44, 1.0 op_sel:[1,0,0]
	v_cvt_scalef32_pk_f32_fp4 v[12:13], v44, 1.0 op_sel:[0,1,0]
	v_cvt_scalef32_pk_f32_fp4 v[14:15], v44, 1.0 op_sel:[1,1,0]
	v_cvt_scalef32_pk_f32_fp4 v[16:17], v45, 1.0
	v_cvt_scalef32_pk_f32_fp4 v[18:19], v45, 1.0 op_sel:[1,0,0]
	v_cvt_scalef32_pk_f32_fp4 v[64:65], v45, 1.0 op_sel:[0,1,0]
	v_cvt_scalef32_pk_f32_fp4 v[66:67], v45, 1.0 op_sel:[1,1,0]
	v_pk_fma_f32 v[24:25], v[8:9], v[188:189], v[24:25] op_sel_hi:[1,0,1]
	v_pk_fma_f32 v[26:27], v[10:11], v[188:189], v[26:27] op_sel_hi:[1,0,1]
	v_pk_fma_f32 v[40:41], v[12:13], v[188:189], v[40:41] op_sel_hi:[1,0,1]
	v_pk_fma_f32 v[42:43], v[14:15], v[188:189], v[42:43] op_sel_hi:[1,0,1]
	v_cvt_scalef32_pk_f32_fp4 v[68:69], v46, 1.0
	v_cvt_scalef32_pk_f32_fp4 v[70:71], v46, 1.0 op_sel:[1,0,0]
	v_cvt_scalef32_pk_f32_fp4 v[72:73], v46, 1.0 op_sel:[0,1,0]
	v_cvt_scalef32_pk_f32_fp4 v[74:75], v46, 1.0 op_sel:[1,1,0]
	v_pk_fma_f32 v[36:37], v[16:17], v[188:189], v[36:37] op_sel_hi:[1,0,1]
	v_pk_fma_f32 v[38:39], v[18:19], v[188:189], v[38:39] op_sel_hi:[1,0,1]
	v_pk_fma_f32 v[4:5], v[64:65], v[188:189], v[4:5] op_sel_hi:[1,0,1]
	v_pk_fma_f32 v[6:7], v[66:67], v[188:189], v[6:7] op_sel_hi:[1,0,1]
	v_cvt_scalef32_pk_f32_fp4 v[8:9], v47, 1.0
	v_cvt_scalef32_pk_f32_fp4 v[10:11], v47, 1.0 op_sel:[1,0,0]
	v_cvt_scalef32_pk_f32_fp4 v[12:13], v47, 1.0 op_sel:[0,1,0]
	v_cvt_scalef32_pk_f32_fp4 v[14:15], v47, 1.0 op_sel:[1,1,0]
	v_pk_fma_f32 v[32:33], v[68:69], v[188:189], v[32:33] op_sel_hi:[1,0,1]
	v_pk_fma_f32 v[34:35], v[70:71], v[188:189], v[34:35] op_sel_hi:[1,0,1]
	v_pk_fma_f32 v[28:29], v[72:73], v[188:189], v[28:29] op_sel_hi:[1,0,1]
	v_pk_fma_f32 v[30:31], v[74:75], v[188:189], v[30:31] op_sel_hi:[1,0,1]
	v_pk_fma_f32 v[20:21], v[8:9], v[188:189], v[20:21] op_sel_hi:[1,0,1]
	v_pk_fma_f32 v[22:23], v[10:11], v[188:189], v[22:23] op_sel_hi:[1,0,1]
	v_pk_fma_f32 v[0:1], v[12:13], v[188:189], v[0:1] op_sel_hi:[1,0,1]
	v_pk_fma_f32 v[2:3], v[14:15], v[188:189], v[2:3] op_sel_hi:[1,0,1]
	s_add_i32 s45, s66, -7
	v_readlane_b32 s44, v196, s45
	s_lshl_b32 s44, s44, 10
	s_add_u32 s46, s92, s44
	s_addc_u32 s47, s93, 0
	global_load_dwordx4 v[44:47], v216, s[46:47]
	s_waitcnt vmcnt(15)
	v_cvt_scalef32_pk_f32_fp4 v[8:9], v48, 1.0
	v_cvt_scalef32_pk_f32_fp4 v[10:11], v48, 1.0 op_sel:[1,0,0]
	v_cvt_scalef32_pk_f32_fp4 v[12:13], v48, 1.0 op_sel:[0,1,0]
	v_cvt_scalef32_pk_f32_fp4 v[14:15], v48, 1.0 op_sel:[1,1,0]
	v_cvt_scalef32_pk_f32_fp4 v[16:17], v49, 1.0
	v_cvt_scalef32_pk_f32_fp4 v[18:19], v49, 1.0 op_sel:[1,0,0]
	v_cvt_scalef32_pk_f32_fp4 v[64:65], v49, 1.0 op_sel:[0,1,0]
	v_cvt_scalef32_pk_f32_fp4 v[66:67], v49, 1.0 op_sel:[1,1,0]
	v_pk_fma_f32 v[24:25], v[8:9], v[188:189], v[24:25] op_sel:[0,1,0]
	v_pk_fma_f32 v[26:27], v[10:11], v[188:189], v[26:27] op_sel:[0,1,0]
	v_pk_fma_f32 v[40:41], v[12:13], v[188:189], v[40:41] op_sel:[0,1,0]
	v_pk_fma_f32 v[42:43], v[14:15], v[188:189], v[42:43] op_sel:[0,1,0]
	v_cvt_scalef32_pk_f32_fp4 v[68:69], v50, 1.0
	v_cvt_scalef32_pk_f32_fp4 v[70:71], v50, 1.0 op_sel:[1,0,0]
	v_cvt_scalef32_pk_f32_fp4 v[72:73], v50, 1.0 op_sel:[0,1,0]
	v_cvt_scalef32_pk_f32_fp4 v[74:75], v50, 1.0 op_sel:[1,1,0]
	v_pk_fma_f32 v[36:37], v[16:17], v[188:189], v[36:37] op_sel:[0,1,0]
	v_pk_fma_f32 v[38:39], v[18:19], v[188:189], v[38:39] op_sel:[0,1,0]
	v_pk_fma_f32 v[4:5], v[64:65], v[188:189], v[4:5] op_sel:[0,1,0]
	v_pk_fma_f32 v[6:7], v[66:67], v[188:189], v[6:7] op_sel:[0,1,0]
	v_cvt_scalef32_pk_f32_fp4 v[8:9], v51, 1.0
	v_cvt_scalef32_pk_f32_fp4 v[10:11], v51, 1.0 op_sel:[1,0,0]
	v_cvt_scalef32_pk_f32_fp4 v[12:13], v51, 1.0 op_sel:[0,1,0]
	v_cvt_scalef32_pk_f32_fp4 v[14:15], v51, 1.0 op_sel:[1,1,0]
	v_pk_fma_f32 v[32:33], v[68:69], v[188:189], v[32:33] op_sel:[0,1,0]
	v_pk_fma_f32 v[34:35], v[70:71], v[188:189], v[34:35] op_sel:[0,1,0]
	v_pk_fma_f32 v[28:29], v[72:73], v[188:189], v[28:29] op_sel:[0,1,0]
	v_pk_fma_f32 v[30:31], v[74:75], v[188:189], v[30:31] op_sel:[0,1,0]
	v_pk_fma_f32 v[20:21], v[8:9], v[188:189], v[20:21] op_sel:[0,1,0]
	v_pk_fma_f32 v[22:23], v[10:11], v[188:189], v[22:23] op_sel:[0,1,0]
	v_pk_fma_f32 v[0:1], v[12:13], v[188:189], v[0:1] op_sel:[0,1,0]
	v_pk_fma_f32 v[2:3], v[14:15], v[188:189], v[2:3] op_sel:[0,1,0]
	v_readlane_b32 s44, v197, s45
	s_lshl_b32 s44, s44, 10
	s_add_u32 s46, s92, s44
	s_addc_u32 s47, s93, 0
	global_load_dwordx4 v[48:51], v216, s[46:47]
	s_waitcnt vmcnt(15)
	v_cvt_scalef32_pk_f32_fp4 v[8:9], v52, 1.0
	v_cvt_scalef32_pk_f32_fp4 v[10:11], v52, 1.0 op_sel:[1,0,0]
	v_cvt_scalef32_pk_f32_fp4 v[12:13], v52, 1.0 op_sel:[0,1,0]
	v_cvt_scalef32_pk_f32_fp4 v[14:15], v52, 1.0 op_sel:[1,1,0]
	v_cvt_scalef32_pk_f32_fp4 v[16:17], v53, 1.0
	v_cvt_scalef32_pk_f32_fp4 v[18:19], v53, 1.0 op_sel:[1,0,0]
	v_cvt_scalef32_pk_f32_fp4 v[64:65], v53, 1.0 op_sel:[0,1,0]
	v_cvt_scalef32_pk_f32_fp4 v[66:67], v53, 1.0 op_sel:[1,1,0]
	v_pk_fma_f32 v[24:25], v[8:9], v[190:191], v[24:25] op_sel_hi:[1,0,1]
	v_pk_fma_f32 v[26:27], v[10:11], v[190:191], v[26:27] op_sel_hi:[1,0,1]
	v_pk_fma_f32 v[40:41], v[12:13], v[190:191], v[40:41] op_sel_hi:[1,0,1]
	v_pk_fma_f32 v[42:43], v[14:15], v[190:191], v[42:43] op_sel_hi:[1,0,1]
	v_cvt_scalef32_pk_f32_fp4 v[68:69], v54, 1.0
	v_cvt_scalef32_pk_f32_fp4 v[70:71], v54, 1.0 op_sel:[1,0,0]
	v_cvt_scalef32_pk_f32_fp4 v[72:73], v54, 1.0 op_sel:[0,1,0]
	v_cvt_scalef32_pk_f32_fp4 v[74:75], v54, 1.0 op_sel:[1,1,0]
	v_pk_fma_f32 v[36:37], v[16:17], v[190:191], v[36:37] op_sel_hi:[1,0,1]
	v_pk_fma_f32 v[38:39], v[18:19], v[190:191], v[38:39] op_sel_hi:[1,0,1]
	v_pk_fma_f32 v[4:5], v[64:65], v[190:191], v[4:5] op_sel_hi:[1,0,1]
	v_pk_fma_f32 v[6:7], v[66:67], v[190:191], v[6:7] op_sel_hi:[1,0,1]
	v_cvt_scalef32_pk_f32_fp4 v[8:9], v55, 1.0
	v_cvt_scalef32_pk_f32_fp4 v[10:11], v55, 1.0 op_sel:[1,0,0]
	v_cvt_scalef32_pk_f32_fp4 v[12:13], v55, 1.0 op_sel:[0,1,0]
	v_cvt_scalef32_pk_f32_fp4 v[14:15], v55, 1.0 op_sel:[1,1,0]
	v_pk_fma_f32 v[32:33], v[68:69], v[190:191], v[32:33] op_sel_hi:[1,0,1]
	v_pk_fma_f32 v[34:35], v[70:71], v[190:191], v[34:35] op_sel_hi:[1,0,1]
	v_pk_fma_f32 v[28:29], v[72:73], v[190:191], v[28:29] op_sel_hi:[1,0,1]
	v_pk_fma_f32 v[30:31], v[74:75], v[190:191], v[30:31] op_sel_hi:[1,0,1]
	v_pk_fma_f32 v[20:21], v[8:9], v[190:191], v[20:21] op_sel_hi:[1,0,1]
	v_pk_fma_f32 v[22:23], v[10:11], v[190:191], v[22:23] op_sel_hi:[1,0,1]
	v_pk_fma_f32 v[0:1], v[12:13], v[190:191], v[0:1] op_sel_hi:[1,0,1]
	v_pk_fma_f32 v[2:3], v[14:15], v[190:191], v[2:3] op_sel_hi:[1,0,1]
	s_add_i32 s45, s66, -6
	v_readlane_b32 s44, v196, s45
	s_lshl_b32 s44, s44, 10
	s_add_u32 s46, s92, s44
	s_addc_u32 s47, s93, 0
	global_load_dwordx4 v[52:55], v216, s[46:47]
	s_waitcnt vmcnt(15)
	v_cvt_scalef32_pk_f32_fp4 v[8:9], v56, 1.0
	v_cvt_scalef32_pk_f32_fp4 v[10:11], v56, 1.0 op_sel:[1,0,0]
	v_cvt_scalef32_pk_f32_fp4 v[12:13], v56, 1.0 op_sel:[0,1,0]
	v_cvt_scalef32_pk_f32_fp4 v[14:15], v56, 1.0 op_sel:[1,1,0]
	v_cvt_scalef32_pk_f32_fp4 v[16:17], v57, 1.0
	v_cvt_scalef32_pk_f32_fp4 v[18:19], v57, 1.0 op_sel:[1,0,0]
	v_cvt_scalef32_pk_f32_fp4 v[64:65], v57, 1.0 op_sel:[0,1,0]
	v_cvt_scalef32_pk_f32_fp4 v[66:67], v57, 1.0 op_sel:[1,1,0]
	v_pk_fma_f32 v[24:25], v[8:9], v[190:191], v[24:25] op_sel:[0,1,0]
	v_pk_fma_f32 v[26:27], v[10:11], v[190:191], v[26:27] op_sel:[0,1,0]
	v_pk_fma_f32 v[40:41], v[12:13], v[190:191], v[40:41] op_sel:[0,1,0]
	v_pk_fma_f32 v[42:43], v[14:15], v[190:191], v[42:43] op_sel:[0,1,0]
	v_cvt_scalef32_pk_f32_fp4 v[68:69], v58, 1.0
	v_cvt_scalef32_pk_f32_fp4 v[70:71], v58, 1.0 op_sel:[1,0,0]
	v_cvt_scalef32_pk_f32_fp4 v[72:73], v58, 1.0 op_sel:[0,1,0]
	v_cvt_scalef32_pk_f32_fp4 v[74:75], v58, 1.0 op_sel:[1,1,0]
	v_pk_fma_f32 v[36:37], v[16:17], v[190:191], v[36:37] op_sel:[0,1,0]
	v_pk_fma_f32 v[38:39], v[18:19], v[190:191], v[38:39] op_sel:[0,1,0]
	v_pk_fma_f32 v[4:5], v[64:65], v[190:191], v[4:5] op_sel:[0,1,0]
	v_pk_fma_f32 v[6:7], v[66:67], v[190:191], v[6:7] op_sel:[0,1,0]
	v_cvt_scalef32_pk_f32_fp4 v[8:9], v59, 1.0
	v_cvt_scalef32_pk_f32_fp4 v[10:11], v59, 1.0 op_sel:[1,0,0]
	v_cvt_scalef32_pk_f32_fp4 v[12:13], v59, 1.0 op_sel:[0,1,0]
	v_cvt_scalef32_pk_f32_fp4 v[14:15], v59, 1.0 op_sel:[1,1,0]
	v_pk_fma_f32 v[32:33], v[68:69], v[190:191], v[32:33] op_sel:[0,1,0]
	v_pk_fma_f32 v[34:35], v[70:71], v[190:191], v[34:35] op_sel:[0,1,0]
	v_pk_fma_f32 v[28:29], v[72:73], v[190:191], v[28:29] op_sel:[0,1,0]
	v_pk_fma_f32 v[30:31], v[74:75], v[190:191], v[30:31] op_sel:[0,1,0]
	v_pk_fma_f32 v[20:21], v[8:9], v[190:191], v[20:21] op_sel:[0,1,0]
	v_pk_fma_f32 v[22:23], v[10:11], v[190:191], v[22:23] op_sel:[0,1,0]
	v_pk_fma_f32 v[0:1], v[12:13], v[190:191], v[0:1] op_sel:[0,1,0]
	v_pk_fma_f32 v[2:3], v[14:15], v[190:191], v[2:3] op_sel:[0,1,0]
	v_readlane_b32 s44, v197, s45
	s_lshl_b32 s44, s44, 10
	s_add_u32 s46, s92, s44
	s_addc_u32 s47, s93, 0
	global_load_dwordx4 v[56:59], v216, s[46:47]
	ds_read_b128 v[188:191], v198 offset:0
	s_waitcnt vmcnt(15) lgkmcnt(3)
	v_cvt_scalef32_pk_f32_fp4 v[8:9], v60, 1.0
	v_cvt_scalef32_pk_f32_fp4 v[10:11], v60, 1.0 op_sel:[1,0,0]
	v_cvt_scalef32_pk_f32_fp4 v[12:13], v60, 1.0 op_sel:[0,1,0]
	v_cvt_scalef32_pk_f32_fp4 v[14:15], v60, 1.0 op_sel:[1,1,0]
	v_cvt_scalef32_pk_f32_fp4 v[16:17], v61, 1.0
	v_cvt_scalef32_pk_f32_fp4 v[18:19], v61, 1.0 op_sel:[1,0,0]
	v_cvt_scalef32_pk_f32_fp4 v[64:65], v61, 1.0 op_sel:[0,1,0]
	v_cvt_scalef32_pk_f32_fp4 v[66:67], v61, 1.0 op_sel:[1,1,0]
	v_pk_fma_f32 v[24:25], v[8:9], v[192:193], v[24:25] op_sel_hi:[1,0,1]
	v_pk_fma_f32 v[26:27], v[10:11], v[192:193], v[26:27] op_sel_hi:[1,0,1]
	v_pk_fma_f32 v[40:41], v[12:13], v[192:193], v[40:41] op_sel_hi:[1,0,1]
	v_pk_fma_f32 v[42:43], v[14:15], v[192:193], v[42:43] op_sel_hi:[1,0,1]
	v_cvt_scalef32_pk_f32_fp4 v[68:69], v62, 1.0
	v_cvt_scalef32_pk_f32_fp4 v[70:71], v62, 1.0 op_sel:[1,0,0]
	v_cvt_scalef32_pk_f32_fp4 v[72:73], v62, 1.0 op_sel:[0,1,0]
	v_cvt_scalef32_pk_f32_fp4 v[74:75], v62, 1.0 op_sel:[1,1,0]
	v_pk_fma_f32 v[36:37], v[16:17], v[192:193], v[36:37] op_sel_hi:[1,0,1]
	v_pk_fma_f32 v[38:39], v[18:19], v[192:193], v[38:39] op_sel_hi:[1,0,1]
	v_pk_fma_f32 v[4:5], v[64:65], v[192:193], v[4:5] op_sel_hi:[1,0,1]
	v_pk_fma_f32 v[6:7], v[66:67], v[192:193], v[6:7] op_sel_hi:[1,0,1]
	v_cvt_scalef32_pk_f32_fp4 v[8:9], v63, 1.0
	v_cvt_scalef32_pk_f32_fp4 v[10:11], v63, 1.0 op_sel:[1,0,0]
	v_cvt_scalef32_pk_f32_fp4 v[12:13], v63, 1.0 op_sel:[0,1,0]
	v_cvt_scalef32_pk_f32_fp4 v[14:15], v63, 1.0 op_sel:[1,1,0]
	v_pk_fma_f32 v[32:33], v[68:69], v[192:193], v[32:33] op_sel_hi:[1,0,1]
	v_pk_fma_f32 v[34:35], v[70:71], v[192:193], v[34:35] op_sel_hi:[1,0,1]
	v_pk_fma_f32 v[28:29], v[72:73], v[192:193], v[28:29] op_sel_hi:[1,0,1]
	v_pk_fma_f32 v[30:31], v[74:75], v[192:193], v[30:31] op_sel_hi:[1,0,1]
	v_pk_fma_f32 v[20:21], v[8:9], v[192:193], v[20:21] op_sel_hi:[1,0,1]
	v_pk_fma_f32 v[22:23], v[10:11], v[192:193], v[22:23] op_sel_hi:[1,0,1]
	v_pk_fma_f32 v[0:1], v[12:13], v[192:193], v[0:1] op_sel_hi:[1,0,1]
	v_pk_fma_f32 v[2:3], v[14:15], v[192:193], v[2:3] op_sel_hi:[1,0,1]
	s_add_i32 s45, s66, -5
	v_readlane_b32 s44, v196, s45
	s_lshl_b32 s44, s44, 10
	s_add_u32 s46, s92, s44
	s_addc_u32 s47, s93, 0
	global_load_dwordx4 v[60:63], v216, s[46:47]
	s_waitcnt vmcnt(15)
	v_cvt_scalef32_pk_f32_fp4 v[8:9], v76, 1.0
	v_cvt_scalef32_pk_f32_fp4 v[10:11], v76, 1.0 op_sel:[1,0,0]
	v_cvt_scalef32_pk_f32_fp4 v[12:13], v76, 1.0 op_sel:[0,1,0]
	v_cvt_scalef32_pk_f32_fp4 v[14:15], v76, 1.0 op_sel:[1,1,0]
	v_cvt_scalef32_pk_f32_fp4 v[16:17], v77, 1.0
	v_cvt_scalef32_pk_f32_fp4 v[18:19], v77, 1.0 op_sel:[1,0,0]
	v_cvt_scalef32_pk_f32_fp4 v[64:65], v77, 1.0 op_sel:[0,1,0]
	v_cvt_scalef32_pk_f32_fp4 v[66:67], v77, 1.0 op_sel:[1,1,0]
	v_pk_fma_f32 v[24:25], v[8:9], v[192:193], v[24:25] op_sel:[0,1,0]
	v_pk_fma_f32 v[26:27], v[10:11], v[192:193], v[26:27] op_sel:[0,1,0]
	v_pk_fma_f32 v[40:41], v[12:13], v[192:193], v[40:41] op_sel:[0,1,0]
	v_pk_fma_f32 v[42:43], v[14:15], v[192:193], v[42:43] op_sel:[0,1,0]
	v_cvt_scalef32_pk_f32_fp4 v[68:69], v78, 1.0
	v_cvt_scalef32_pk_f32_fp4 v[70:71], v78, 1.0 op_sel:[1,0,0]
	v_cvt_scalef32_pk_f32_fp4 v[72:73], v78, 1.0 op_sel:[0,1,0]
	v_cvt_scalef32_pk_f32_fp4 v[74:75], v78, 1.0 op_sel:[1,1,0]
	v_pk_fma_f32 v[36:37], v[16:17], v[192:193], v[36:37] op_sel:[0,1,0]
	v_pk_fma_f32 v[38:39], v[18:19], v[192:193], v[38:39] op_sel:[0,1,0]
	v_pk_fma_f32 v[4:5], v[64:65], v[192:193], v[4:5] op_sel:[0,1,0]
	v_pk_fma_f32 v[6:7], v[66:67], v[192:193], v[6:7] op_sel:[0,1,0]
	v_cvt_scalef32_pk_f32_fp4 v[8:9], v79, 1.0
	v_cvt_scalef32_pk_f32_fp4 v[10:11], v79, 1.0 op_sel:[1,0,0]
	v_cvt_scalef32_pk_f32_fp4 v[12:13], v79, 1.0 op_sel:[0,1,0]
	v_cvt_scalef32_pk_f32_fp4 v[14:15], v79, 1.0 op_sel:[1,1,0]
	v_pk_fma_f32 v[32:33], v[68:69], v[192:193], v[32:33] op_sel:[0,1,0]
	v_pk_fma_f32 v[34:35], v[70:71], v[192:193], v[34:35] op_sel:[0,1,0]
	v_pk_fma_f32 v[28:29], v[72:73], v[192:193], v[28:29] op_sel:[0,1,0]
	v_pk_fma_f32 v[30:31], v[74:75], v[192:193], v[30:31] op_sel:[0,1,0]
	v_pk_fma_f32 v[20:21], v[8:9], v[192:193], v[20:21] op_sel:[0,1,0]
	v_pk_fma_f32 v[22:23], v[10:11], v[192:193], v[22:23] op_sel:[0,1,0]
	v_pk_fma_f32 v[0:1], v[12:13], v[192:193], v[0:1] op_sel:[0,1,0]
	v_pk_fma_f32 v[2:3], v[14:15], v[192:193], v[2:3] op_sel:[0,1,0]
	v_readlane_b32 s44, v197, s45
	s_lshl_b32 s44, s44, 10
	s_add_u32 s46, s92, s44
	s_addc_u32 s47, s93, 0
	global_load_dwordx4 v[76:79], v216, s[46:47]
	s_waitcnt vmcnt(15)
	v_cvt_scalef32_pk_f32_fp4 v[8:9], v80, 1.0
	v_cvt_scalef32_pk_f32_fp4 v[10:11], v80, 1.0 op_sel:[1,0,0]
	v_cvt_scalef32_pk_f32_fp4 v[12:13], v80, 1.0 op_sel:[0,1,0]
	v_cvt_scalef32_pk_f32_fp4 v[14:15], v80, 1.0 op_sel:[1,1,0]
	v_cvt_scalef32_pk_f32_fp4 v[16:17], v81, 1.0
	v_cvt_scalef32_pk_f32_fp4 v[18:19], v81, 1.0 op_sel:[1,0,0]
	v_cvt_scalef32_pk_f32_fp4 v[64:65], v81, 1.0 op_sel:[0,1,0]
	v_cvt_scalef32_pk_f32_fp4 v[66:67], v81, 1.0 op_sel:[1,1,0]
	v_pk_fma_f32 v[24:25], v[8:9], v[194:195], v[24:25] op_sel_hi:[1,0,1]
	v_pk_fma_f32 v[26:27], v[10:11], v[194:195], v[26:27] op_sel_hi:[1,0,1]
	v_pk_fma_f32 v[40:41], v[12:13], v[194:195], v[40:41] op_sel_hi:[1,0,1]
	v_pk_fma_f32 v[42:43], v[14:15], v[194:195], v[42:43] op_sel_hi:[1,0,1]
	v_cvt_scalef32_pk_f32_fp4 v[68:69], v82, 1.0
	v_cvt_scalef32_pk_f32_fp4 v[70:71], v82, 1.0 op_sel:[1,0,0]
	v_cvt_scalef32_pk_f32_fp4 v[72:73], v82, 1.0 op_sel:[0,1,0]
	v_cvt_scalef32_pk_f32_fp4 v[74:75], v82, 1.0 op_sel:[1,1,0]
	v_pk_fma_f32 v[36:37], v[16:17], v[194:195], v[36:37] op_sel_hi:[1,0,1]
	v_pk_fma_f32 v[38:39], v[18:19], v[194:195], v[38:39] op_sel_hi:[1,0,1]
	v_pk_fma_f32 v[4:5], v[64:65], v[194:195], v[4:5] op_sel_hi:[1,0,1]
	v_pk_fma_f32 v[6:7], v[66:67], v[194:195], v[6:7] op_sel_hi:[1,0,1]
	v_cvt_scalef32_pk_f32_fp4 v[8:9], v83, 1.0
	v_cvt_scalef32_pk_f32_fp4 v[10:11], v83, 1.0 op_sel:[1,0,0]
	v_cvt_scalef32_pk_f32_fp4 v[12:13], v83, 1.0 op_sel:[0,1,0]
	v_cvt_scalef32_pk_f32_fp4 v[14:15], v83, 1.0 op_sel:[1,1,0]
	v_pk_fma_f32 v[32:33], v[68:69], v[194:195], v[32:33] op_sel_hi:[1,0,1]
	v_pk_fma_f32 v[34:35], v[70:71], v[194:195], v[34:35] op_sel_hi:[1,0,1]
	v_pk_fma_f32 v[28:29], v[72:73], v[194:195], v[28:29] op_sel_hi:[1,0,1]
	v_pk_fma_f32 v[30:31], v[74:75], v[194:195], v[30:31] op_sel_hi:[1,0,1]
	v_pk_fma_f32 v[20:21], v[8:9], v[194:195], v[20:21] op_sel_hi:[1,0,1]
	v_pk_fma_f32 v[22:23], v[10:11], v[194:195], v[22:23] op_sel_hi:[1,0,1]
	v_pk_fma_f32 v[0:1], v[12:13], v[194:195], v[0:1] op_sel_hi:[1,0,1]
	v_pk_fma_f32 v[2:3], v[14:15], v[194:195], v[2:3] op_sel_hi:[1,0,1]
	s_add_i32 s45, s66, -4
	v_readlane_b32 s44, v196, s45
	s_lshl_b32 s44, s44, 10
	s_add_u32 s46, s92, s44
	s_addc_u32 s47, s93, 0
	global_load_dwordx4 v[80:83], v216, s[46:47]
	s_waitcnt vmcnt(15)
	v_cvt_scalef32_pk_f32_fp4 v[8:9], v84, 1.0
	v_cvt_scalef32_pk_f32_fp4 v[10:11], v84, 1.0 op_sel:[1,0,0]
	v_cvt_scalef32_pk_f32_fp4 v[12:13], v84, 1.0 op_sel:[0,1,0]
	v_cvt_scalef32_pk_f32_fp4 v[14:15], v84, 1.0 op_sel:[1,1,0]
	v_cvt_scalef32_pk_f32_fp4 v[16:17], v85, 1.0
	v_cvt_scalef32_pk_f32_fp4 v[18:19], v85, 1.0 op_sel:[1,0,0]
	v_cvt_scalef32_pk_f32_fp4 v[64:65], v85, 1.0 op_sel:[0,1,0]
	v_cvt_scalef32_pk_f32_fp4 v[66:67], v85, 1.0 op_sel:[1,1,0]
	v_pk_fma_f32 v[24:25], v[8:9], v[194:195], v[24:25] op_sel:[0,1,0]
	v_pk_fma_f32 v[26:27], v[10:11], v[194:195], v[26:27] op_sel:[0,1,0]
	v_pk_fma_f32 v[40:41], v[12:13], v[194:195], v[40:41] op_sel:[0,1,0]
	v_pk_fma_f32 v[42:43], v[14:15], v[194:195], v[42:43] op_sel:[0,1,0]
	v_cvt_scalef32_pk_f32_fp4 v[68:69], v86, 1.0
	v_cvt_scalef32_pk_f32_fp4 v[70:71], v86, 1.0 op_sel:[1,0,0]
	v_cvt_scalef32_pk_f32_fp4 v[72:73], v86, 1.0 op_sel:[0,1,0]
	v_cvt_scalef32_pk_f32_fp4 v[74:75], v86, 1.0 op_sel:[1,1,0]
	v_pk_fma_f32 v[36:37], v[16:17], v[194:195], v[36:37] op_sel:[0,1,0]
	v_pk_fma_f32 v[38:39], v[18:19], v[194:195], v[38:39] op_sel:[0,1,0]
	v_pk_fma_f32 v[4:5], v[64:65], v[194:195], v[4:5] op_sel:[0,1,0]
	v_pk_fma_f32 v[6:7], v[66:67], v[194:195], v[6:7] op_sel:[0,1,0]
	v_cvt_scalef32_pk_f32_fp4 v[8:9], v87, 1.0
	v_cvt_scalef32_pk_f32_fp4 v[10:11], v87, 1.0 op_sel:[1,0,0]
	v_cvt_scalef32_pk_f32_fp4 v[12:13], v87, 1.0 op_sel:[0,1,0]
	v_cvt_scalef32_pk_f32_fp4 v[14:15], v87, 1.0 op_sel:[1,1,0]
	v_pk_fma_f32 v[32:33], v[68:69], v[194:195], v[32:33] op_sel:[0,1,0]
	v_pk_fma_f32 v[34:35], v[70:71], v[194:195], v[34:35] op_sel:[0,1,0]
	v_pk_fma_f32 v[28:29], v[72:73], v[194:195], v[28:29] op_sel:[0,1,0]
	v_pk_fma_f32 v[30:31], v[74:75], v[194:195], v[30:31] op_sel:[0,1,0]
	v_pk_fma_f32 v[20:21], v[8:9], v[194:195], v[20:21] op_sel:[0,1,0]
	v_pk_fma_f32 v[22:23], v[10:11], v[194:195], v[22:23] op_sel:[0,1,0]
	v_pk_fma_f32 v[0:1], v[12:13], v[194:195], v[0:1] op_sel:[0,1,0]
	v_pk_fma_f32 v[2:3], v[14:15], v[194:195], v[2:3] op_sel:[0,1,0]
	v_readlane_b32 s44, v197, s45
	s_lshl_b32 s44, s44, 10
	s_add_u32 s46, s92, s44
	s_addc_u32 s47, s93, 0
	global_load_dwordx4 v[84:87], v216, s[46:47]
	ds_read_b128 v[192:195], v198 offset:16
	s_waitcnt vmcnt(15) lgkmcnt(3)
	v_cvt_scalef32_pk_f32_fp4 v[8:9], v88, 1.0
	v_cvt_scalef32_pk_f32_fp4 v[10:11], v88, 1.0 op_sel:[1,0,0]
	v_cvt_scalef32_pk_f32_fp4 v[12:13], v88, 1.0 op_sel:[0,1,0]
	v_cvt_scalef32_pk_f32_fp4 v[14:15], v88, 1.0 op_sel:[1,1,0]
	v_cvt_scalef32_pk_f32_fp4 v[16:17], v89, 1.0
	v_cvt_scalef32_pk_f32_fp4 v[18:19], v89, 1.0 op_sel:[1,0,0]
	v_cvt_scalef32_pk_f32_fp4 v[64:65], v89, 1.0 op_sel:[0,1,0]
	v_cvt_scalef32_pk_f32_fp4 v[66:67], v89, 1.0 op_sel:[1,1,0]
	v_pk_fma_f32 v[24:25], v[8:9], v[240:241], v[24:25] op_sel_hi:[1,0,1]
	v_pk_fma_f32 v[26:27], v[10:11], v[240:241], v[26:27] op_sel_hi:[1,0,1]
	v_pk_fma_f32 v[40:41], v[12:13], v[240:241], v[40:41] op_sel_hi:[1,0,1]
	v_pk_fma_f32 v[42:43], v[14:15], v[240:241], v[42:43] op_sel_hi:[1,0,1]
	v_cvt_scalef32_pk_f32_fp4 v[68:69], v90, 1.0
	v_cvt_scalef32_pk_f32_fp4 v[70:71], v90, 1.0 op_sel:[1,0,0]
	v_cvt_scalef32_pk_f32_fp4 v[72:73], v90, 1.0 op_sel:[0,1,0]
	v_cvt_scalef32_pk_f32_fp4 v[74:75], v90, 1.0 op_sel:[1,1,0]
	v_pk_fma_f32 v[36:37], v[16:17], v[240:241], v[36:37] op_sel_hi:[1,0,1]
	v_pk_fma_f32 v[38:39], v[18:19], v[240:241], v[38:39] op_sel_hi:[1,0,1]
	v_pk_fma_f32 v[4:5], v[64:65], v[240:241], v[4:5] op_sel_hi:[1,0,1]
	v_pk_fma_f32 v[6:7], v[66:67], v[240:241], v[6:7] op_sel_hi:[1,0,1]
	v_cvt_scalef32_pk_f32_fp4 v[8:9], v91, 1.0
	v_cvt_scalef32_pk_f32_fp4 v[10:11], v91, 1.0 op_sel:[1,0,0]
	v_cvt_scalef32_pk_f32_fp4 v[12:13], v91, 1.0 op_sel:[0,1,0]
	v_cvt_scalef32_pk_f32_fp4 v[14:15], v91, 1.0 op_sel:[1,1,0]
	v_pk_fma_f32 v[32:33], v[68:69], v[240:241], v[32:33] op_sel_hi:[1,0,1]
	v_pk_fma_f32 v[34:35], v[70:71], v[240:241], v[34:35] op_sel_hi:[1,0,1]
	v_pk_fma_f32 v[28:29], v[72:73], v[240:241], v[28:29] op_sel_hi:[1,0,1]
	v_pk_fma_f32 v[30:31], v[74:75], v[240:241], v[30:31] op_sel_hi:[1,0,1]
	v_pk_fma_f32 v[20:21], v[8:9], v[240:241], v[20:21] op_sel_hi:[1,0,1]
	v_pk_fma_f32 v[22:23], v[10:11], v[240:241], v[22:23] op_sel_hi:[1,0,1]
	v_pk_fma_f32 v[0:1], v[12:13], v[240:241], v[0:1] op_sel_hi:[1,0,1]
	v_pk_fma_f32 v[2:3], v[14:15], v[240:241], v[2:3] op_sel_hi:[1,0,1]
	s_add_i32 s45, s66, -3
	v_readlane_b32 s44, v196, s45
	s_lshl_b32 s44, s44, 10
	s_add_u32 s46, s92, s44
	s_addc_u32 s47, s93, 0
	global_load_dwordx4 v[88:91], v216, s[46:47]
	s_waitcnt vmcnt(15)
	v_cvt_scalef32_pk_f32_fp4 v[8:9], v92, 1.0
	v_cvt_scalef32_pk_f32_fp4 v[10:11], v92, 1.0 op_sel:[1,0,0]
	v_cvt_scalef32_pk_f32_fp4 v[12:13], v92, 1.0 op_sel:[0,1,0]
	v_cvt_scalef32_pk_f32_fp4 v[14:15], v92, 1.0 op_sel:[1,1,0]
	v_cvt_scalef32_pk_f32_fp4 v[16:17], v93, 1.0
	v_cvt_scalef32_pk_f32_fp4 v[18:19], v93, 1.0 op_sel:[1,0,0]
	v_cvt_scalef32_pk_f32_fp4 v[64:65], v93, 1.0 op_sel:[0,1,0]
	v_cvt_scalef32_pk_f32_fp4 v[66:67], v93, 1.0 op_sel:[1,1,0]
	v_pk_fma_f32 v[24:25], v[8:9], v[240:241], v[24:25] op_sel:[0,1,0]
	v_pk_fma_f32 v[26:27], v[10:11], v[240:241], v[26:27] op_sel:[0,1,0]
	v_pk_fma_f32 v[40:41], v[12:13], v[240:241], v[40:41] op_sel:[0,1,0]
	v_pk_fma_f32 v[42:43], v[14:15], v[240:241], v[42:43] op_sel:[0,1,0]
	v_cvt_scalef32_pk_f32_fp4 v[68:69], v94, 1.0
	v_cvt_scalef32_pk_f32_fp4 v[70:71], v94, 1.0 op_sel:[1,0,0]
	v_cvt_scalef32_pk_f32_fp4 v[72:73], v94, 1.0 op_sel:[0,1,0]
	v_cvt_scalef32_pk_f32_fp4 v[74:75], v94, 1.0 op_sel:[1,1,0]
	v_pk_fma_f32 v[36:37], v[16:17], v[240:241], v[36:37] op_sel:[0,1,0]
	v_pk_fma_f32 v[38:39], v[18:19], v[240:241], v[38:39] op_sel:[0,1,0]
	v_pk_fma_f32 v[4:5], v[64:65], v[240:241], v[4:5] op_sel:[0,1,0]
	v_pk_fma_f32 v[6:7], v[66:67], v[240:241], v[6:7] op_sel:[0,1,0]
	v_cvt_scalef32_pk_f32_fp4 v[8:9], v95, 1.0
	v_cvt_scalef32_pk_f32_fp4 v[10:11], v95, 1.0 op_sel:[1,0,0]
	v_cvt_scalef32_pk_f32_fp4 v[12:13], v95, 1.0 op_sel:[0,1,0]
	v_cvt_scalef32_pk_f32_fp4 v[14:15], v95, 1.0 op_sel:[1,1,0]
	v_pk_fma_f32 v[32:33], v[68:69], v[240:241], v[32:33] op_sel:[0,1,0]
	v_pk_fma_f32 v[34:35], v[70:71], v[240:241], v[34:35] op_sel:[0,1,0]
	v_pk_fma_f32 v[28:29], v[72:73], v[240:241], v[28:29] op_sel:[0,1,0]
	v_pk_fma_f32 v[30:31], v[74:75], v[240:241], v[30:31] op_sel:[0,1,0]
	v_pk_fma_f32 v[20:21], v[8:9], v[240:241], v[20:21] op_sel:[0,1,0]
	v_pk_fma_f32 v[22:23], v[10:11], v[240:241], v[22:23] op_sel:[0,1,0]
	v_pk_fma_f32 v[0:1], v[12:13], v[240:241], v[0:1] op_sel:[0,1,0]
	v_pk_fma_f32 v[2:3], v[14:15], v[240:241], v[2:3] op_sel:[0,1,0]
	v_readlane_b32 s44, v197, s45
	s_lshl_b32 s44, s44, 10
	s_add_u32 s46, s92, s44
	s_addc_u32 s47, s93, 0
	global_load_dwordx4 v[92:95], v216, s[46:47]
	s_waitcnt vmcnt(15)
	v_cvt_scalef32_pk_f32_fp4 v[8:9], v96, 1.0
	v_cvt_scalef32_pk_f32_fp4 v[10:11], v96, 1.0 op_sel:[1,0,0]
	v_cvt_scalef32_pk_f32_fp4 v[12:13], v96, 1.0 op_sel:[0,1,0]
	v_cvt_scalef32_pk_f32_fp4 v[14:15], v96, 1.0 op_sel:[1,1,0]
	v_cvt_scalef32_pk_f32_fp4 v[16:17], v97, 1.0
	v_cvt_scalef32_pk_f32_fp4 v[18:19], v97, 1.0 op_sel:[1,0,0]
	v_cvt_scalef32_pk_f32_fp4 v[64:65], v97, 1.0 op_sel:[0,1,0]
	v_cvt_scalef32_pk_f32_fp4 v[66:67], v97, 1.0 op_sel:[1,1,0]
	v_pk_fma_f32 v[24:25], v[8:9], v[242:243], v[24:25] op_sel_hi:[1,0,1]
	v_pk_fma_f32 v[26:27], v[10:11], v[242:243], v[26:27] op_sel_hi:[1,0,1]
	v_pk_fma_f32 v[40:41], v[12:13], v[242:243], v[40:41] op_sel_hi:[1,0,1]
	v_pk_fma_f32 v[42:43], v[14:15], v[242:243], v[42:43] op_sel_hi:[1,0,1]
	v_cvt_scalef32_pk_f32_fp4 v[68:69], v98, 1.0
	v_cvt_scalef32_pk_f32_fp4 v[70:71], v98, 1.0 op_sel:[1,0,0]
	v_cvt_scalef32_pk_f32_fp4 v[72:73], v98, 1.0 op_sel:[0,1,0]
	v_cvt_scalef32_pk_f32_fp4 v[74:75], v98, 1.0 op_sel:[1,1,0]
	v_pk_fma_f32 v[36:37], v[16:17], v[242:243], v[36:37] op_sel_hi:[1,0,1]
	v_pk_fma_f32 v[38:39], v[18:19], v[242:243], v[38:39] op_sel_hi:[1,0,1]
	v_pk_fma_f32 v[4:5], v[64:65], v[242:243], v[4:5] op_sel_hi:[1,0,1]
	v_pk_fma_f32 v[6:7], v[66:67], v[242:243], v[6:7] op_sel_hi:[1,0,1]
	v_cvt_scalef32_pk_f32_fp4 v[8:9], v99, 1.0
	v_cvt_scalef32_pk_f32_fp4 v[10:11], v99, 1.0 op_sel:[1,0,0]
	v_cvt_scalef32_pk_f32_fp4 v[12:13], v99, 1.0 op_sel:[0,1,0]
	v_cvt_scalef32_pk_f32_fp4 v[14:15], v99, 1.0 op_sel:[1,1,0]
	v_pk_fma_f32 v[32:33], v[68:69], v[242:243], v[32:33] op_sel_hi:[1,0,1]
	v_pk_fma_f32 v[34:35], v[70:71], v[242:243], v[34:35] op_sel_hi:[1,0,1]
	v_pk_fma_f32 v[28:29], v[72:73], v[242:243], v[28:29] op_sel_hi:[1,0,1]
	v_pk_fma_f32 v[30:31], v[74:75], v[242:243], v[30:31] op_sel_hi:[1,0,1]
	v_pk_fma_f32 v[20:21], v[8:9], v[242:243], v[20:21] op_sel_hi:[1,0,1]
	v_pk_fma_f32 v[22:23], v[10:11], v[242:243], v[22:23] op_sel_hi:[1,0,1]
	v_pk_fma_f32 v[0:1], v[12:13], v[242:243], v[0:1] op_sel_hi:[1,0,1]
	v_pk_fma_f32 v[2:3], v[14:15], v[242:243], v[2:3] op_sel_hi:[1,0,1]
	s_add_i32 s45, s66, -2
	v_readlane_b32 s44, v196, s45
	s_lshl_b32 s44, s44, 10
	s_add_u32 s46, s92, s44
	s_addc_u32 s47, s93, 0
	global_load_dwordx4 v[96:99], v216, s[46:47]
	s_waitcnt vmcnt(15)
	v_cvt_scalef32_pk_f32_fp4 v[8:9], v100, 1.0
	v_cvt_scalef32_pk_f32_fp4 v[10:11], v100, 1.0 op_sel:[1,0,0]
	v_cvt_scalef32_pk_f32_fp4 v[12:13], v100, 1.0 op_sel:[0,1,0]
	v_cvt_scalef32_pk_f32_fp4 v[14:15], v100, 1.0 op_sel:[1,1,0]
	v_cvt_scalef32_pk_f32_fp4 v[16:17], v101, 1.0
	v_cvt_scalef32_pk_f32_fp4 v[18:19], v101, 1.0 op_sel:[1,0,0]
	v_cvt_scalef32_pk_f32_fp4 v[64:65], v101, 1.0 op_sel:[0,1,0]
	v_cvt_scalef32_pk_f32_fp4 v[66:67], v101, 1.0 op_sel:[1,1,0]
	v_pk_fma_f32 v[24:25], v[8:9], v[242:243], v[24:25] op_sel:[0,1,0]
	v_pk_fma_f32 v[26:27], v[10:11], v[242:243], v[26:27] op_sel:[0,1,0]
	v_pk_fma_f32 v[40:41], v[12:13], v[242:243], v[40:41] op_sel:[0,1,0]
	v_pk_fma_f32 v[42:43], v[14:15], v[242:243], v[42:43] op_sel:[0,1,0]
	v_cvt_scalef32_pk_f32_fp4 v[68:69], v102, 1.0
	v_cvt_scalef32_pk_f32_fp4 v[70:71], v102, 1.0 op_sel:[1,0,0]
	v_cvt_scalef32_pk_f32_fp4 v[72:73], v102, 1.0 op_sel:[0,1,0]
	v_cvt_scalef32_pk_f32_fp4 v[74:75], v102, 1.0 op_sel:[1,1,0]
	v_pk_fma_f32 v[36:37], v[16:17], v[242:243], v[36:37] op_sel:[0,1,0]
	v_pk_fma_f32 v[38:39], v[18:19], v[242:243], v[38:39] op_sel:[0,1,0]
	v_pk_fma_f32 v[4:5], v[64:65], v[242:243], v[4:5] op_sel:[0,1,0]
	v_pk_fma_f32 v[6:7], v[66:67], v[242:243], v[6:7] op_sel:[0,1,0]
	v_cvt_scalef32_pk_f32_fp4 v[8:9], v103, 1.0
	v_cvt_scalef32_pk_f32_fp4 v[10:11], v103, 1.0 op_sel:[1,0,0]
	v_cvt_scalef32_pk_f32_fp4 v[12:13], v103, 1.0 op_sel:[0,1,0]
	v_cvt_scalef32_pk_f32_fp4 v[14:15], v103, 1.0 op_sel:[1,1,0]
	v_pk_fma_f32 v[32:33], v[68:69], v[242:243], v[32:33] op_sel:[0,1,0]
	v_pk_fma_f32 v[34:35], v[70:71], v[242:243], v[34:35] op_sel:[0,1,0]
	v_pk_fma_f32 v[28:29], v[72:73], v[242:243], v[28:29] op_sel:[0,1,0]
	v_pk_fma_f32 v[30:31], v[74:75], v[242:243], v[30:31] op_sel:[0,1,0]
	v_pk_fma_f32 v[20:21], v[8:9], v[242:243], v[20:21] op_sel:[0,1,0]
	v_pk_fma_f32 v[22:23], v[10:11], v[242:243], v[22:23] op_sel:[0,1,0]
	v_pk_fma_f32 v[0:1], v[12:13], v[242:243], v[0:1] op_sel:[0,1,0]
	v_pk_fma_f32 v[2:3], v[14:15], v[242:243], v[2:3] op_sel:[0,1,0]
	v_readlane_b32 s44, v197, s45
	s_lshl_b32 s44, s44, 10
	s_add_u32 s46, s92, s44
	s_addc_u32 s47, s93, 0
	global_load_dwordx4 v[100:103], v216, s[46:47]
	ds_read_b128 v[240:243], v198 offset:32
	s_waitcnt vmcnt(15) lgkmcnt(3)
	v_cvt_scalef32_pk_f32_fp4 v[8:9], v172, 1.0
	v_cvt_scalef32_pk_f32_fp4 v[10:11], v172, 1.0 op_sel:[1,0,0]
	v_cvt_scalef32_pk_f32_fp4 v[12:13], v172, 1.0 op_sel:[0,1,0]
	v_cvt_scalef32_pk_f32_fp4 v[14:15], v172, 1.0 op_sel:[1,1,0]
	v_cvt_scalef32_pk_f32_fp4 v[16:17], v173, 1.0
	v_cvt_scalef32_pk_f32_fp4 v[18:19], v173, 1.0 op_sel:[1,0,0]
	v_cvt_scalef32_pk_f32_fp4 v[64:65], v173, 1.0 op_sel:[0,1,0]
	v_cvt_scalef32_pk_f32_fp4 v[66:67], v173, 1.0 op_sel:[1,1,0]
	v_pk_fma_f32 v[24:25], v[8:9], v[244:245], v[24:25] op_sel_hi:[1,0,1]
	v_pk_fma_f32 v[26:27], v[10:11], v[244:245], v[26:27] op_sel_hi:[1,0,1]
	v_pk_fma_f32 v[40:41], v[12:13], v[244:245], v[40:41] op_sel_hi:[1,0,1]
	v_pk_fma_f32 v[42:43], v[14:15], v[244:245], v[42:43] op_sel_hi:[1,0,1]
	v_cvt_scalef32_pk_f32_fp4 v[68:69], v174, 1.0
	v_cvt_scalef32_pk_f32_fp4 v[70:71], v174, 1.0 op_sel:[1,0,0]
	v_cvt_scalef32_pk_f32_fp4 v[72:73], v174, 1.0 op_sel:[0,1,0]
	v_cvt_scalef32_pk_f32_fp4 v[74:75], v174, 1.0 op_sel:[1,1,0]
	v_pk_fma_f32 v[36:37], v[16:17], v[244:245], v[36:37] op_sel_hi:[1,0,1]
	v_pk_fma_f32 v[38:39], v[18:19], v[244:245], v[38:39] op_sel_hi:[1,0,1]
	v_pk_fma_f32 v[4:5], v[64:65], v[244:245], v[4:5] op_sel_hi:[1,0,1]
	v_pk_fma_f32 v[6:7], v[66:67], v[244:245], v[6:7] op_sel_hi:[1,0,1]
	v_cvt_scalef32_pk_f32_fp4 v[8:9], v175, 1.0
	v_cvt_scalef32_pk_f32_fp4 v[10:11], v175, 1.0 op_sel:[1,0,0]
	v_cvt_scalef32_pk_f32_fp4 v[12:13], v175, 1.0 op_sel:[0,1,0]
	v_cvt_scalef32_pk_f32_fp4 v[14:15], v175, 1.0 op_sel:[1,1,0]
	v_pk_fma_f32 v[32:33], v[68:69], v[244:245], v[32:33] op_sel_hi:[1,0,1]
	v_pk_fma_f32 v[34:35], v[70:71], v[244:245], v[34:35] op_sel_hi:[1,0,1]
	v_pk_fma_f32 v[28:29], v[72:73], v[244:245], v[28:29] op_sel_hi:[1,0,1]
	v_pk_fma_f32 v[30:31], v[74:75], v[244:245], v[30:31] op_sel_hi:[1,0,1]
	v_pk_fma_f32 v[20:21], v[8:9], v[244:245], v[20:21] op_sel_hi:[1,0,1]
	v_pk_fma_f32 v[22:23], v[10:11], v[244:245], v[22:23] op_sel_hi:[1,0,1]
	v_pk_fma_f32 v[0:1], v[12:13], v[244:245], v[0:1] op_sel_hi:[1,0,1]
	v_pk_fma_f32 v[2:3], v[14:15], v[244:245], v[2:3] op_sel_hi:[1,0,1]
	s_add_i32 s45, s66, -1
	v_readlane_b32 s44, v196, s45
	s_lshl_b32 s44, s44, 10
	s_add_u32 s46, s92, s44
	s_addc_u32 s47, s93, 0
	global_load_dwordx4 v[172:175], v216, s[46:47]
	s_waitcnt vmcnt(15)
	v_cvt_scalef32_pk_f32_fp4 v[8:9], v176, 1.0
	v_cvt_scalef32_pk_f32_fp4 v[10:11], v176, 1.0 op_sel:[1,0,0]
	v_cvt_scalef32_pk_f32_fp4 v[12:13], v176, 1.0 op_sel:[0,1,0]
	v_cvt_scalef32_pk_f32_fp4 v[14:15], v176, 1.0 op_sel:[1,1,0]
	v_cvt_scalef32_pk_f32_fp4 v[16:17], v177, 1.0
	v_cvt_scalef32_pk_f32_fp4 v[18:19], v177, 1.0 op_sel:[1,0,0]
	v_cvt_scalef32_pk_f32_fp4 v[64:65], v177, 1.0 op_sel:[0,1,0]
	v_cvt_scalef32_pk_f32_fp4 v[66:67], v177, 1.0 op_sel:[1,1,0]
	v_pk_fma_f32 v[24:25], v[8:9], v[244:245], v[24:25] op_sel:[0,1,0]
	v_pk_fma_f32 v[26:27], v[10:11], v[244:245], v[26:27] op_sel:[0,1,0]
	v_pk_fma_f32 v[40:41], v[12:13], v[244:245], v[40:41] op_sel:[0,1,0]
	v_pk_fma_f32 v[42:43], v[14:15], v[244:245], v[42:43] op_sel:[0,1,0]
	v_cvt_scalef32_pk_f32_fp4 v[68:69], v178, 1.0
	v_cvt_scalef32_pk_f32_fp4 v[70:71], v178, 1.0 op_sel:[1,0,0]
	v_cvt_scalef32_pk_f32_fp4 v[72:73], v178, 1.0 op_sel:[0,1,0]
	v_cvt_scalef32_pk_f32_fp4 v[74:75], v178, 1.0 op_sel:[1,1,0]
	v_pk_fma_f32 v[36:37], v[16:17], v[244:245], v[36:37] op_sel:[0,1,0]
	v_pk_fma_f32 v[38:39], v[18:19], v[244:245], v[38:39] op_sel:[0,1,0]
	v_pk_fma_f32 v[4:5], v[64:65], v[244:245], v[4:5] op_sel:[0,1,0]
	v_pk_fma_f32 v[6:7], v[66:67], v[244:245], v[6:7] op_sel:[0,1,0]
	v_cvt_scalef32_pk_f32_fp4 v[8:9], v179, 1.0
	v_cvt_scalef32_pk_f32_fp4 v[10:11], v179, 1.0 op_sel:[1,0,0]
	v_cvt_scalef32_pk_f32_fp4 v[12:13], v179, 1.0 op_sel:[0,1,0]
	v_cvt_scalef32_pk_f32_fp4 v[14:15], v179, 1.0 op_sel:[1,1,0]
	v_pk_fma_f32 v[32:33], v[68:69], v[244:245], v[32:33] op_sel:[0,1,0]
	v_pk_fma_f32 v[34:35], v[70:71], v[244:245], v[34:35] op_sel:[0,1,0]
	v_pk_fma_f32 v[28:29], v[72:73], v[244:245], v[28:29] op_sel:[0,1,0]
	v_pk_fma_f32 v[30:31], v[74:75], v[244:245], v[30:31] op_sel:[0,1,0]
	v_pk_fma_f32 v[20:21], v[8:9], v[244:245], v[20:21] op_sel:[0,1,0]
	v_pk_fma_f32 v[22:23], v[10:11], v[244:245], v[22:23] op_sel:[0,1,0]
	v_pk_fma_f32 v[0:1], v[12:13], v[244:245], v[0:1] op_sel:[0,1,0]
	v_pk_fma_f32 v[2:3], v[14:15], v[244:245], v[2:3] op_sel:[0,1,0]
	v_readlane_b32 s44, v197, s45
	s_lshl_b32 s44, s44, 10
	s_add_u32 s46, s92, s44
	s_addc_u32 s47, s93, 0
	global_load_dwordx4 v[176:179], v216, s[46:47]
	s_waitcnt vmcnt(15)
	v_cvt_scalef32_pk_f32_fp4 v[8:9], v180, 1.0
	v_cvt_scalef32_pk_f32_fp4 v[10:11], v180, 1.0 op_sel:[1,0,0]
	v_cvt_scalef32_pk_f32_fp4 v[12:13], v180, 1.0 op_sel:[0,1,0]
	v_cvt_scalef32_pk_f32_fp4 v[14:15], v180, 1.0 op_sel:[1,1,0]
	v_cvt_scalef32_pk_f32_fp4 v[16:17], v181, 1.0
	v_cvt_scalef32_pk_f32_fp4 v[18:19], v181, 1.0 op_sel:[1,0,0]
	v_cvt_scalef32_pk_f32_fp4 v[64:65], v181, 1.0 op_sel:[0,1,0]
	v_cvt_scalef32_pk_f32_fp4 v[66:67], v181, 1.0 op_sel:[1,1,0]
	v_pk_fma_f32 v[24:25], v[8:9], v[246:247], v[24:25] op_sel_hi:[1,0,1]
	v_pk_fma_f32 v[26:27], v[10:11], v[246:247], v[26:27] op_sel_hi:[1,0,1]
	v_pk_fma_f32 v[40:41], v[12:13], v[246:247], v[40:41] op_sel_hi:[1,0,1]
	v_pk_fma_f32 v[42:43], v[14:15], v[246:247], v[42:43] op_sel_hi:[1,0,1]
	v_cvt_scalef32_pk_f32_fp4 v[68:69], v182, 1.0
	v_cvt_scalef32_pk_f32_fp4 v[70:71], v182, 1.0 op_sel:[1,0,0]
	v_cvt_scalef32_pk_f32_fp4 v[72:73], v182, 1.0 op_sel:[0,1,0]
	v_cvt_scalef32_pk_f32_fp4 v[74:75], v182, 1.0 op_sel:[1,1,0]
	v_pk_fma_f32 v[36:37], v[16:17], v[246:247], v[36:37] op_sel_hi:[1,0,1]
	v_pk_fma_f32 v[38:39], v[18:19], v[246:247], v[38:39] op_sel_hi:[1,0,1]
	v_pk_fma_f32 v[4:5], v[64:65], v[246:247], v[4:5] op_sel_hi:[1,0,1]
	v_pk_fma_f32 v[6:7], v[66:67], v[246:247], v[6:7] op_sel_hi:[1,0,1]
	v_cvt_scalef32_pk_f32_fp4 v[8:9], v183, 1.0
	v_cvt_scalef32_pk_f32_fp4 v[10:11], v183, 1.0 op_sel:[1,0,0]
	v_cvt_scalef32_pk_f32_fp4 v[12:13], v183, 1.0 op_sel:[0,1,0]
	v_cvt_scalef32_pk_f32_fp4 v[14:15], v183, 1.0 op_sel:[1,1,0]
	v_pk_fma_f32 v[32:33], v[68:69], v[246:247], v[32:33] op_sel_hi:[1,0,1]
	v_pk_fma_f32 v[34:35], v[70:71], v[246:247], v[34:35] op_sel_hi:[1,0,1]
	v_pk_fma_f32 v[28:29], v[72:73], v[246:247], v[28:29] op_sel_hi:[1,0,1]
	v_pk_fma_f32 v[30:31], v[74:75], v[246:247], v[30:31] op_sel_hi:[1,0,1]
	v_pk_fma_f32 v[20:21], v[8:9], v[246:247], v[20:21] op_sel_hi:[1,0,1]
	v_pk_fma_f32 v[22:23], v[10:11], v[246:247], v[22:23] op_sel_hi:[1,0,1]
	v_pk_fma_f32 v[0:1], v[12:13], v[246:247], v[0:1] op_sel_hi:[1,0,1]
	v_pk_fma_f32 v[2:3], v[14:15], v[246:247], v[2:3] op_sel_hi:[1,0,1]
	s_add_i32 s45, s66, 0
	v_readlane_b32 s44, v196, s45
	s_lshl_b32 s44, s44, 10
	s_add_u32 s46, s92, s44
	s_addc_u32 s47, s93, 0
	global_load_dwordx4 v[180:183], v216, s[46:47]
	s_waitcnt vmcnt(15)
	v_cvt_scalef32_pk_f32_fp4 v[8:9], v184, 1.0
	v_cvt_scalef32_pk_f32_fp4 v[10:11], v184, 1.0 op_sel:[1,0,0]
	v_cvt_scalef32_pk_f32_fp4 v[12:13], v184, 1.0 op_sel:[0,1,0]
	v_cvt_scalef32_pk_f32_fp4 v[14:15], v184, 1.0 op_sel:[1,1,0]
	v_cvt_scalef32_pk_f32_fp4 v[16:17], v185, 1.0
	v_cvt_scalef32_pk_f32_fp4 v[18:19], v185, 1.0 op_sel:[1,0,0]
	v_cvt_scalef32_pk_f32_fp4 v[64:65], v185, 1.0 op_sel:[0,1,0]
	v_cvt_scalef32_pk_f32_fp4 v[66:67], v185, 1.0 op_sel:[1,1,0]
	v_pk_fma_f32 v[24:25], v[8:9], v[246:247], v[24:25] op_sel:[0,1,0]
	v_pk_fma_f32 v[26:27], v[10:11], v[246:247], v[26:27] op_sel:[0,1,0]
	v_pk_fma_f32 v[40:41], v[12:13], v[246:247], v[40:41] op_sel:[0,1,0]
	v_pk_fma_f32 v[42:43], v[14:15], v[246:247], v[42:43] op_sel:[0,1,0]
	v_cvt_scalef32_pk_f32_fp4 v[68:69], v186, 1.0
	v_cvt_scalef32_pk_f32_fp4 v[70:71], v186, 1.0 op_sel:[1,0,0]
	v_cvt_scalef32_pk_f32_fp4 v[72:73], v186, 1.0 op_sel:[0,1,0]
	v_cvt_scalef32_pk_f32_fp4 v[74:75], v186, 1.0 op_sel:[1,1,0]
	v_pk_fma_f32 v[36:37], v[16:17], v[246:247], v[36:37] op_sel:[0,1,0]
	v_pk_fma_f32 v[38:39], v[18:19], v[246:247], v[38:39] op_sel:[0,1,0]
	v_pk_fma_f32 v[4:5], v[64:65], v[246:247], v[4:5] op_sel:[0,1,0]
	v_pk_fma_f32 v[6:7], v[66:67], v[246:247], v[6:7] op_sel:[0,1,0]
	v_cvt_scalef32_pk_f32_fp4 v[8:9], v187, 1.0
	v_cvt_scalef32_pk_f32_fp4 v[10:11], v187, 1.0 op_sel:[1,0,0]
	v_cvt_scalef32_pk_f32_fp4 v[12:13], v187, 1.0 op_sel:[0,1,0]
	v_cvt_scalef32_pk_f32_fp4 v[14:15], v187, 1.0 op_sel:[1,1,0]
	v_pk_fma_f32 v[32:33], v[68:69], v[246:247], v[32:33] op_sel:[0,1,0]
	v_pk_fma_f32 v[34:35], v[70:71], v[246:247], v[34:35] op_sel:[0,1,0]
	v_pk_fma_f32 v[28:29], v[72:73], v[246:247], v[28:29] op_sel:[0,1,0]
	v_pk_fma_f32 v[30:31], v[74:75], v[246:247], v[30:31] op_sel:[0,1,0]
	v_pk_fma_f32 v[20:21], v[8:9], v[246:247], v[20:21] op_sel:[0,1,0]
	v_pk_fma_f32 v[22:23], v[10:11], v[246:247], v[22:23] op_sel:[0,1,0]
	v_pk_fma_f32 v[0:1], v[12:13], v[246:247], v[0:1] op_sel:[0,1,0]
	v_pk_fma_f32 v[2:3], v[14:15], v[246:247], v[2:3] op_sel:[0,1,0]
	v_readlane_b32 s44, v197, s45
	s_lshl_b32 s44, s44, 10
	s_add_u32 s46, s92, s44
	s_addc_u32 s47, s93, 0
	global_load_dwordx4 v[184:187], v216, s[46:47]
	ds_read_b128 v[244:247], v198 offset:48
	s_waitcnt vmcnt(15) lgkmcnt(3)
	v_cvt_scalef32_pk_f32_fp4 v[8:9], v44, 1.0
	v_cvt_scalef32_pk_f32_fp4 v[10:11], v44, 1.0 op_sel:[1,0,0]
	v_cvt_scalef32_pk_f32_fp4 v[12:13], v44, 1.0 op_sel:[0,1,0]
	v_cvt_scalef32_pk_f32_fp4 v[14:15], v44, 1.0 op_sel:[1,1,0]
	v_cvt_scalef32_pk_f32_fp4 v[16:17], v45, 1.0
	v_cvt_scalef32_pk_f32_fp4 v[18:19], v45, 1.0 op_sel:[1,0,0]
	v_cvt_scalef32_pk_f32_fp4 v[64:65], v45, 1.0 op_sel:[0,1,0]
	v_cvt_scalef32_pk_f32_fp4 v[66:67], v45, 1.0 op_sel:[1,1,0]
	v_pk_fma_f32 v[200:201], v[8:9], v[188:189], v[200:201] op_sel_hi:[1,0,1]
	v_pk_fma_f32 v[202:203], v[10:11], v[188:189], v[202:203] op_sel_hi:[1,0,1]
	v_pk_fma_f32 v[204:205], v[12:13], v[188:189], v[204:205] op_sel_hi:[1,0,1]
	v_pk_fma_f32 v[206:207], v[14:15], v[188:189], v[206:207] op_sel_hi:[1,0,1]
	v_cvt_scalef32_pk_f32_fp4 v[68:69], v46, 1.0
	v_cvt_scalef32_pk_f32_fp4 v[70:71], v46, 1.0 op_sel:[1,0,0]
	v_cvt_scalef32_pk_f32_fp4 v[72:73], v46, 1.0 op_sel:[0,1,0]
	v_cvt_scalef32_pk_f32_fp4 v[74:75], v46, 1.0 op_sel:[1,1,0]
	v_pk_fma_f32 v[208:209], v[16:17], v[188:189], v[208:209] op_sel_hi:[1,0,1]
	v_pk_fma_f32 v[210:211], v[18:19], v[188:189], v[210:211] op_sel_hi:[1,0,1]
	v_pk_fma_f32 v[212:213], v[64:65], v[188:189], v[212:213] op_sel_hi:[1,0,1]
	v_pk_fma_f32 v[214:215], v[66:67], v[188:189], v[214:215] op_sel_hi:[1,0,1]
	v_cvt_scalef32_pk_f32_fp4 v[8:9], v47, 1.0
	v_cvt_scalef32_pk_f32_fp4 v[10:11], v47, 1.0 op_sel:[1,0,0]
	v_cvt_scalef32_pk_f32_fp4 v[12:13], v47, 1.0 op_sel:[0,1,0]
	v_cvt_scalef32_pk_f32_fp4 v[14:15], v47, 1.0 op_sel:[1,1,0]
	v_pk_fma_f32 v[218:219], v[68:69], v[188:189], v[218:219] op_sel_hi:[1,0,1]
	v_pk_fma_f32 v[220:221], v[70:71], v[188:189], v[220:221] op_sel_hi:[1,0,1]
	v_pk_fma_f32 v[222:223], v[72:73], v[188:189], v[222:223] op_sel_hi:[1,0,1]
	v_pk_fma_f32 v[224:225], v[74:75], v[188:189], v[224:225] op_sel_hi:[1,0,1]
	v_pk_fma_f32 v[226:227], v[8:9], v[188:189], v[226:227] op_sel_hi:[1,0,1]
	v_pk_fma_f32 v[228:229], v[10:11], v[188:189], v[228:229] op_sel_hi:[1,0,1]
	v_pk_fma_f32 v[230:231], v[12:13], v[188:189], v[230:231] op_sel_hi:[1,0,1]
	v_pk_fma_f32 v[232:233], v[14:15], v[188:189], v[232:233] op_sel_hi:[1,0,1]
	s_add_i32 s45, s66, 1
	v_readlane_b32 s44, v154, s45
	s_lshl_b32 s44, s44, 10
	s_add_u32 s46, s92, s44
	s_addc_u32 s47, s93, 0
	global_load_dwordx4 v[44:47], v216, s[46:47]
	s_waitcnt vmcnt(15)
	v_cvt_scalef32_pk_f32_fp4 v[8:9], v48, 1.0
	v_cvt_scalef32_pk_f32_fp4 v[10:11], v48, 1.0 op_sel:[1,0,0]
	v_cvt_scalef32_pk_f32_fp4 v[12:13], v48, 1.0 op_sel:[0,1,0]
	v_cvt_scalef32_pk_f32_fp4 v[14:15], v48, 1.0 op_sel:[1,1,0]
	v_cvt_scalef32_pk_f32_fp4 v[16:17], v49, 1.0
	v_cvt_scalef32_pk_f32_fp4 v[18:19], v49, 1.0 op_sel:[1,0,0]
	v_cvt_scalef32_pk_f32_fp4 v[64:65], v49, 1.0 op_sel:[0,1,0]
	v_cvt_scalef32_pk_f32_fp4 v[66:67], v49, 1.0 op_sel:[1,1,0]
	v_pk_fma_f32 v[200:201], v[8:9], v[188:189], v[200:201] op_sel:[0,1,0]
	v_pk_fma_f32 v[202:203], v[10:11], v[188:189], v[202:203] op_sel:[0,1,0]
	v_pk_fma_f32 v[204:205], v[12:13], v[188:189], v[204:205] op_sel:[0,1,0]
	v_pk_fma_f32 v[206:207], v[14:15], v[188:189], v[206:207] op_sel:[0,1,0]
	v_cvt_scalef32_pk_f32_fp4 v[68:69], v50, 1.0
	v_cvt_scalef32_pk_f32_fp4 v[70:71], v50, 1.0 op_sel:[1,0,0]
	v_cvt_scalef32_pk_f32_fp4 v[72:73], v50, 1.0 op_sel:[0,1,0]
	v_cvt_scalef32_pk_f32_fp4 v[74:75], v50, 1.0 op_sel:[1,1,0]
	v_pk_fma_f32 v[208:209], v[16:17], v[188:189], v[208:209] op_sel:[0,1,0]
	v_pk_fma_f32 v[210:211], v[18:19], v[188:189], v[210:211] op_sel:[0,1,0]
	v_pk_fma_f32 v[212:213], v[64:65], v[188:189], v[212:213] op_sel:[0,1,0]
	v_pk_fma_f32 v[214:215], v[66:67], v[188:189], v[214:215] op_sel:[0,1,0]
	v_cvt_scalef32_pk_f32_fp4 v[8:9], v51, 1.0
	v_cvt_scalef32_pk_f32_fp4 v[10:11], v51, 1.0 op_sel:[1,0,0]
	v_cvt_scalef32_pk_f32_fp4 v[12:13], v51, 1.0 op_sel:[0,1,0]
	v_cvt_scalef32_pk_f32_fp4 v[14:15], v51, 1.0 op_sel:[1,1,0]
	v_pk_fma_f32 v[218:219], v[68:69], v[188:189], v[218:219] op_sel:[0,1,0]
	v_pk_fma_f32 v[220:221], v[70:71], v[188:189], v[220:221] op_sel:[0,1,0]
	v_pk_fma_f32 v[222:223], v[72:73], v[188:189], v[222:223] op_sel:[0,1,0]
	v_pk_fma_f32 v[224:225], v[74:75], v[188:189], v[224:225] op_sel:[0,1,0]
	v_pk_fma_f32 v[226:227], v[8:9], v[188:189], v[226:227] op_sel:[0,1,0]
	v_pk_fma_f32 v[228:229], v[10:11], v[188:189], v[228:229] op_sel:[0,1,0]
	v_pk_fma_f32 v[230:231], v[12:13], v[188:189], v[230:231] op_sel:[0,1,0]
	v_pk_fma_f32 v[232:233], v[14:15], v[188:189], v[232:233] op_sel:[0,1,0]
	v_readlane_b32 s44, v155, s45
	s_lshl_b32 s44, s44, 10
	s_add_u32 s46, s92, s44
	s_addc_u32 s47, s93, 0
	global_load_dwordx4 v[48:51], v216, s[46:47]
	s_waitcnt vmcnt(15)
	v_cvt_scalef32_pk_f32_fp4 v[8:9], v52, 1.0
	v_cvt_scalef32_pk_f32_fp4 v[10:11], v52, 1.0 op_sel:[1,0,0]
	v_cvt_scalef32_pk_f32_fp4 v[12:13], v52, 1.0 op_sel:[0,1,0]
	v_cvt_scalef32_pk_f32_fp4 v[14:15], v52, 1.0 op_sel:[1,1,0]
	v_cvt_scalef32_pk_f32_fp4 v[16:17], v53, 1.0
	v_cvt_scalef32_pk_f32_fp4 v[18:19], v53, 1.0 op_sel:[1,0,0]
	v_cvt_scalef32_pk_f32_fp4 v[64:65], v53, 1.0 op_sel:[0,1,0]
	v_cvt_scalef32_pk_f32_fp4 v[66:67], v53, 1.0 op_sel:[1,1,0]
	v_pk_fma_f32 v[200:201], v[8:9], v[190:191], v[200:201] op_sel_hi:[1,0,1]
	v_pk_fma_f32 v[202:203], v[10:11], v[190:191], v[202:203] op_sel_hi:[1,0,1]
	v_pk_fma_f32 v[204:205], v[12:13], v[190:191], v[204:205] op_sel_hi:[1,0,1]
	v_pk_fma_f32 v[206:207], v[14:15], v[190:191], v[206:207] op_sel_hi:[1,0,1]
	v_cvt_scalef32_pk_f32_fp4 v[68:69], v54, 1.0
	v_cvt_scalef32_pk_f32_fp4 v[70:71], v54, 1.0 op_sel:[1,0,0]
	v_cvt_scalef32_pk_f32_fp4 v[72:73], v54, 1.0 op_sel:[0,1,0]
	v_cvt_scalef32_pk_f32_fp4 v[74:75], v54, 1.0 op_sel:[1,1,0]
	v_pk_fma_f32 v[208:209], v[16:17], v[190:191], v[208:209] op_sel_hi:[1,0,1]
	v_pk_fma_f32 v[210:211], v[18:19], v[190:191], v[210:211] op_sel_hi:[1,0,1]
	v_pk_fma_f32 v[212:213], v[64:65], v[190:191], v[212:213] op_sel_hi:[1,0,1]
	v_pk_fma_f32 v[214:215], v[66:67], v[190:191], v[214:215] op_sel_hi:[1,0,1]
	v_cvt_scalef32_pk_f32_fp4 v[8:9], v55, 1.0
	v_cvt_scalef32_pk_f32_fp4 v[10:11], v55, 1.0 op_sel:[1,0,0]
	v_cvt_scalef32_pk_f32_fp4 v[12:13], v55, 1.0 op_sel:[0,1,0]
	v_cvt_scalef32_pk_f32_fp4 v[14:15], v55, 1.0 op_sel:[1,1,0]
	v_pk_fma_f32 v[218:219], v[68:69], v[190:191], v[218:219] op_sel_hi:[1,0,1]
	v_pk_fma_f32 v[220:221], v[70:71], v[190:191], v[220:221] op_sel_hi:[1,0,1]
	v_pk_fma_f32 v[222:223], v[72:73], v[190:191], v[222:223] op_sel_hi:[1,0,1]
	v_pk_fma_f32 v[224:225], v[74:75], v[190:191], v[224:225] op_sel_hi:[1,0,1]
	v_pk_fma_f32 v[226:227], v[8:9], v[190:191], v[226:227] op_sel_hi:[1,0,1]
	v_pk_fma_f32 v[228:229], v[10:11], v[190:191], v[228:229] op_sel_hi:[1,0,1]
	v_pk_fma_f32 v[230:231], v[12:13], v[190:191], v[230:231] op_sel_hi:[1,0,1]
	v_pk_fma_f32 v[232:233], v[14:15], v[190:191], v[232:233] op_sel_hi:[1,0,1]
	s_add_i32 s45, s66, 2
	v_readlane_b32 s44, v154, s45
	s_lshl_b32 s44, s44, 10
	s_add_u32 s46, s92, s44
	s_addc_u32 s47, s93, 0
	global_load_dwordx4 v[52:55], v216, s[46:47]
	s_waitcnt vmcnt(15)
	v_cvt_scalef32_pk_f32_fp4 v[8:9], v56, 1.0
	v_cvt_scalef32_pk_f32_fp4 v[10:11], v56, 1.0 op_sel:[1,0,0]
	v_cvt_scalef32_pk_f32_fp4 v[12:13], v56, 1.0 op_sel:[0,1,0]
	v_cvt_scalef32_pk_f32_fp4 v[14:15], v56, 1.0 op_sel:[1,1,0]
	v_cvt_scalef32_pk_f32_fp4 v[16:17], v57, 1.0
	v_cvt_scalef32_pk_f32_fp4 v[18:19], v57, 1.0 op_sel:[1,0,0]
	v_cvt_scalef32_pk_f32_fp4 v[64:65], v57, 1.0 op_sel:[0,1,0]
	v_cvt_scalef32_pk_f32_fp4 v[66:67], v57, 1.0 op_sel:[1,1,0]
	v_pk_fma_f32 v[200:201], v[8:9], v[190:191], v[200:201] op_sel:[0,1,0]
	v_pk_fma_f32 v[202:203], v[10:11], v[190:191], v[202:203] op_sel:[0,1,0]
	v_pk_fma_f32 v[204:205], v[12:13], v[190:191], v[204:205] op_sel:[0,1,0]
	v_pk_fma_f32 v[206:207], v[14:15], v[190:191], v[206:207] op_sel:[0,1,0]
	v_cvt_scalef32_pk_f32_fp4 v[68:69], v58, 1.0
	v_cvt_scalef32_pk_f32_fp4 v[70:71], v58, 1.0 op_sel:[1,0,0]
	v_cvt_scalef32_pk_f32_fp4 v[72:73], v58, 1.0 op_sel:[0,1,0]
	v_cvt_scalef32_pk_f32_fp4 v[74:75], v58, 1.0 op_sel:[1,1,0]
	v_pk_fma_f32 v[208:209], v[16:17], v[190:191], v[208:209] op_sel:[0,1,0]
	v_pk_fma_f32 v[210:211], v[18:19], v[190:191], v[210:211] op_sel:[0,1,0]
	v_pk_fma_f32 v[212:213], v[64:65], v[190:191], v[212:213] op_sel:[0,1,0]
	v_pk_fma_f32 v[214:215], v[66:67], v[190:191], v[214:215] op_sel:[0,1,0]
	v_cvt_scalef32_pk_f32_fp4 v[8:9], v59, 1.0
	v_cvt_scalef32_pk_f32_fp4 v[10:11], v59, 1.0 op_sel:[1,0,0]
	v_cvt_scalef32_pk_f32_fp4 v[12:13], v59, 1.0 op_sel:[0,1,0]
	v_cvt_scalef32_pk_f32_fp4 v[14:15], v59, 1.0 op_sel:[1,1,0]
	v_pk_fma_f32 v[218:219], v[68:69], v[190:191], v[218:219] op_sel:[0,1,0]
	v_pk_fma_f32 v[220:221], v[70:71], v[190:191], v[220:221] op_sel:[0,1,0]
	v_pk_fma_f32 v[222:223], v[72:73], v[190:191], v[222:223] op_sel:[0,1,0]
	v_pk_fma_f32 v[224:225], v[74:75], v[190:191], v[224:225] op_sel:[0,1,0]
	v_pk_fma_f32 v[226:227], v[8:9], v[190:191], v[226:227] op_sel:[0,1,0]
	v_pk_fma_f32 v[228:229], v[10:11], v[190:191], v[228:229] op_sel:[0,1,0]
	v_pk_fma_f32 v[230:231], v[12:13], v[190:191], v[230:231] op_sel:[0,1,0]
	v_pk_fma_f32 v[232:233], v[14:15], v[190:191], v[232:233] op_sel:[0,1,0]
	v_readlane_b32 s44, v155, s45
	s_lshl_b32 s44, s44, 10
	s_add_u32 s46, s92, s44
	s_addc_u32 s47, s93, 0
	global_load_dwordx4 v[56:59], v216, s[46:47]
	ds_read_b128 v[188:191], v131 offset:64
	s_waitcnt vmcnt(15) lgkmcnt(3)
	v_cvt_scalef32_pk_f32_fp4 v[8:9], v60, 1.0
	v_cvt_scalef32_pk_f32_fp4 v[10:11], v60, 1.0 op_sel:[1,0,0]
	v_cvt_scalef32_pk_f32_fp4 v[12:13], v60, 1.0 op_sel:[0,1,0]
	v_cvt_scalef32_pk_f32_fp4 v[14:15], v60, 1.0 op_sel:[1,1,0]
	v_cvt_scalef32_pk_f32_fp4 v[16:17], v61, 1.0
	v_cvt_scalef32_pk_f32_fp4 v[18:19], v61, 1.0 op_sel:[1,0,0]
	v_cvt_scalef32_pk_f32_fp4 v[64:65], v61, 1.0 op_sel:[0,1,0]
	v_cvt_scalef32_pk_f32_fp4 v[66:67], v61, 1.0 op_sel:[1,1,0]
	v_pk_fma_f32 v[200:201], v[8:9], v[192:193], v[200:201] op_sel_hi:[1,0,1]
	v_pk_fma_f32 v[202:203], v[10:11], v[192:193], v[202:203] op_sel_hi:[1,0,1]
	v_pk_fma_f32 v[204:205], v[12:13], v[192:193], v[204:205] op_sel_hi:[1,0,1]
	v_pk_fma_f32 v[206:207], v[14:15], v[192:193], v[206:207] op_sel_hi:[1,0,1]
	v_cvt_scalef32_pk_f32_fp4 v[68:69], v62, 1.0
	v_cvt_scalef32_pk_f32_fp4 v[70:71], v62, 1.0 op_sel:[1,0,0]
	v_cvt_scalef32_pk_f32_fp4 v[72:73], v62, 1.0 op_sel:[0,1,0]
	v_cvt_scalef32_pk_f32_fp4 v[74:75], v62, 1.0 op_sel:[1,1,0]
	v_pk_fma_f32 v[208:209], v[16:17], v[192:193], v[208:209] op_sel_hi:[1,0,1]
	v_pk_fma_f32 v[210:211], v[18:19], v[192:193], v[210:211] op_sel_hi:[1,0,1]
	v_pk_fma_f32 v[212:213], v[64:65], v[192:193], v[212:213] op_sel_hi:[1,0,1]
	v_pk_fma_f32 v[214:215], v[66:67], v[192:193], v[214:215] op_sel_hi:[1,0,1]
	v_cvt_scalef32_pk_f32_fp4 v[8:9], v63, 1.0
	v_cvt_scalef32_pk_f32_fp4 v[10:11], v63, 1.0 op_sel:[1,0,0]
	v_cvt_scalef32_pk_f32_fp4 v[12:13], v63, 1.0 op_sel:[0,1,0]
	v_cvt_scalef32_pk_f32_fp4 v[14:15], v63, 1.0 op_sel:[1,1,0]
	v_pk_fma_f32 v[218:219], v[68:69], v[192:193], v[218:219] op_sel_hi:[1,0,1]
	v_pk_fma_f32 v[220:221], v[70:71], v[192:193], v[220:221] op_sel_hi:[1,0,1]
	v_pk_fma_f32 v[222:223], v[72:73], v[192:193], v[222:223] op_sel_hi:[1,0,1]
	v_pk_fma_f32 v[224:225], v[74:75], v[192:193], v[224:225] op_sel_hi:[1,0,1]
	v_pk_fma_f32 v[226:227], v[8:9], v[192:193], v[226:227] op_sel_hi:[1,0,1]
	v_pk_fma_f32 v[228:229], v[10:11], v[192:193], v[228:229] op_sel_hi:[1,0,1]
	v_pk_fma_f32 v[230:231], v[12:13], v[192:193], v[230:231] op_sel_hi:[1,0,1]
	v_pk_fma_f32 v[232:233], v[14:15], v[192:193], v[232:233] op_sel_hi:[1,0,1]
	s_add_i32 s45, s66, 3
	v_readlane_b32 s44, v154, s45
	s_lshl_b32 s44, s44, 10
	s_add_u32 s46, s92, s44
	s_addc_u32 s47, s93, 0
	global_load_dwordx4 v[60:63], v216, s[46:47]
	s_waitcnt vmcnt(15)
	v_cvt_scalef32_pk_f32_fp4 v[8:9], v76, 1.0
	v_cvt_scalef32_pk_f32_fp4 v[10:11], v76, 1.0 op_sel:[1,0,0]
	v_cvt_scalef32_pk_f32_fp4 v[12:13], v76, 1.0 op_sel:[0,1,0]
	v_cvt_scalef32_pk_f32_fp4 v[14:15], v76, 1.0 op_sel:[1,1,0]
	v_cvt_scalef32_pk_f32_fp4 v[16:17], v77, 1.0
	v_cvt_scalef32_pk_f32_fp4 v[18:19], v77, 1.0 op_sel:[1,0,0]
	v_cvt_scalef32_pk_f32_fp4 v[64:65], v77, 1.0 op_sel:[0,1,0]
	v_cvt_scalef32_pk_f32_fp4 v[66:67], v77, 1.0 op_sel:[1,1,0]
	v_pk_fma_f32 v[200:201], v[8:9], v[192:193], v[200:201] op_sel:[0,1,0]
	v_pk_fma_f32 v[202:203], v[10:11], v[192:193], v[202:203] op_sel:[0,1,0]
	v_pk_fma_f32 v[204:205], v[12:13], v[192:193], v[204:205] op_sel:[0,1,0]
	v_pk_fma_f32 v[206:207], v[14:15], v[192:193], v[206:207] op_sel:[0,1,0]
	v_cvt_scalef32_pk_f32_fp4 v[68:69], v78, 1.0
	v_cvt_scalef32_pk_f32_fp4 v[70:71], v78, 1.0 op_sel:[1,0,0]
	v_cvt_scalef32_pk_f32_fp4 v[72:73], v78, 1.0 op_sel:[0,1,0]
	v_cvt_scalef32_pk_f32_fp4 v[74:75], v78, 1.0 op_sel:[1,1,0]
	v_pk_fma_f32 v[208:209], v[16:17], v[192:193], v[208:209] op_sel:[0,1,0]
	v_pk_fma_f32 v[210:211], v[18:19], v[192:193], v[210:211] op_sel:[0,1,0]
	v_pk_fma_f32 v[212:213], v[64:65], v[192:193], v[212:213] op_sel:[0,1,0]
	v_pk_fma_f32 v[214:215], v[66:67], v[192:193], v[214:215] op_sel:[0,1,0]
	v_cvt_scalef32_pk_f32_fp4 v[8:9], v79, 1.0
	v_cvt_scalef32_pk_f32_fp4 v[10:11], v79, 1.0 op_sel:[1,0,0]
	v_cvt_scalef32_pk_f32_fp4 v[12:13], v79, 1.0 op_sel:[0,1,0]
	v_cvt_scalef32_pk_f32_fp4 v[14:15], v79, 1.0 op_sel:[1,1,0]
	v_pk_fma_f32 v[218:219], v[68:69], v[192:193], v[218:219] op_sel:[0,1,0]
	v_pk_fma_f32 v[220:221], v[70:71], v[192:193], v[220:221] op_sel:[0,1,0]
	v_pk_fma_f32 v[222:223], v[72:73], v[192:193], v[222:223] op_sel:[0,1,0]
	v_pk_fma_f32 v[224:225], v[74:75], v[192:193], v[224:225] op_sel:[0,1,0]
	v_pk_fma_f32 v[226:227], v[8:9], v[192:193], v[226:227] op_sel:[0,1,0]
	v_pk_fma_f32 v[228:229], v[10:11], v[192:193], v[228:229] op_sel:[0,1,0]
	v_pk_fma_f32 v[230:231], v[12:13], v[192:193], v[230:231] op_sel:[0,1,0]
	v_pk_fma_f32 v[232:233], v[14:15], v[192:193], v[232:233] op_sel:[0,1,0]
	v_readlane_b32 s44, v155, s45
	s_lshl_b32 s44, s44, 10
	s_add_u32 s46, s92, s44
	s_addc_u32 s47, s93, 0
	global_load_dwordx4 v[76:79], v216, s[46:47]
	s_waitcnt vmcnt(15)
	v_cvt_scalef32_pk_f32_fp4 v[8:9], v80, 1.0
	v_cvt_scalef32_pk_f32_fp4 v[10:11], v80, 1.0 op_sel:[1,0,0]
	v_cvt_scalef32_pk_f32_fp4 v[12:13], v80, 1.0 op_sel:[0,1,0]
	v_cvt_scalef32_pk_f32_fp4 v[14:15], v80, 1.0 op_sel:[1,1,0]
	v_cvt_scalef32_pk_f32_fp4 v[16:17], v81, 1.0
	v_cvt_scalef32_pk_f32_fp4 v[18:19], v81, 1.0 op_sel:[1,0,0]
	v_cvt_scalef32_pk_f32_fp4 v[64:65], v81, 1.0 op_sel:[0,1,0]
	v_cvt_scalef32_pk_f32_fp4 v[66:67], v81, 1.0 op_sel:[1,1,0]
	v_pk_fma_f32 v[200:201], v[8:9], v[194:195], v[200:201] op_sel_hi:[1,0,1]
	v_pk_fma_f32 v[202:203], v[10:11], v[194:195], v[202:203] op_sel_hi:[1,0,1]
	v_pk_fma_f32 v[204:205], v[12:13], v[194:195], v[204:205] op_sel_hi:[1,0,1]
	v_pk_fma_f32 v[206:207], v[14:15], v[194:195], v[206:207] op_sel_hi:[1,0,1]
	v_cvt_scalef32_pk_f32_fp4 v[68:69], v82, 1.0
	v_cvt_scalef32_pk_f32_fp4 v[70:71], v82, 1.0 op_sel:[1,0,0]
	v_cvt_scalef32_pk_f32_fp4 v[72:73], v82, 1.0 op_sel:[0,1,0]
	v_cvt_scalef32_pk_f32_fp4 v[74:75], v82, 1.0 op_sel:[1,1,0]
	v_pk_fma_f32 v[208:209], v[16:17], v[194:195], v[208:209] op_sel_hi:[1,0,1]
	v_pk_fma_f32 v[210:211], v[18:19], v[194:195], v[210:211] op_sel_hi:[1,0,1]
	v_pk_fma_f32 v[212:213], v[64:65], v[194:195], v[212:213] op_sel_hi:[1,0,1]
	v_pk_fma_f32 v[214:215], v[66:67], v[194:195], v[214:215] op_sel_hi:[1,0,1]
	v_cvt_scalef32_pk_f32_fp4 v[8:9], v83, 1.0
	v_cvt_scalef32_pk_f32_fp4 v[10:11], v83, 1.0 op_sel:[1,0,0]
	v_cvt_scalef32_pk_f32_fp4 v[12:13], v83, 1.0 op_sel:[0,1,0]
	v_cvt_scalef32_pk_f32_fp4 v[14:15], v83, 1.0 op_sel:[1,1,0]
	v_pk_fma_f32 v[218:219], v[68:69], v[194:195], v[218:219] op_sel_hi:[1,0,1]
	v_pk_fma_f32 v[220:221], v[70:71], v[194:195], v[220:221] op_sel_hi:[1,0,1]
	v_pk_fma_f32 v[222:223], v[72:73], v[194:195], v[222:223] op_sel_hi:[1,0,1]
	v_pk_fma_f32 v[224:225], v[74:75], v[194:195], v[224:225] op_sel_hi:[1,0,1]
	v_pk_fma_f32 v[226:227], v[8:9], v[194:195], v[226:227] op_sel_hi:[1,0,1]
	v_pk_fma_f32 v[228:229], v[10:11], v[194:195], v[228:229] op_sel_hi:[1,0,1]
	v_pk_fma_f32 v[230:231], v[12:13], v[194:195], v[230:231] op_sel_hi:[1,0,1]
	v_pk_fma_f32 v[232:233], v[14:15], v[194:195], v[232:233] op_sel_hi:[1,0,1]
	s_add_i32 s45, s66, 4
	v_readlane_b32 s44, v154, s45
	s_lshl_b32 s44, s44, 10
	s_add_u32 s46, s92, s44
	s_addc_u32 s47, s93, 0
	global_load_dwordx4 v[80:83], v216, s[46:47]
	s_waitcnt vmcnt(15)
	v_cvt_scalef32_pk_f32_fp4 v[8:9], v84, 1.0
	v_cvt_scalef32_pk_f32_fp4 v[10:11], v84, 1.0 op_sel:[1,0,0]
	v_cvt_scalef32_pk_f32_fp4 v[12:13], v84, 1.0 op_sel:[0,1,0]
	v_cvt_scalef32_pk_f32_fp4 v[14:15], v84, 1.0 op_sel:[1,1,0]
	v_cvt_scalef32_pk_f32_fp4 v[16:17], v85, 1.0
	v_cvt_scalef32_pk_f32_fp4 v[18:19], v85, 1.0 op_sel:[1,0,0]
	v_cvt_scalef32_pk_f32_fp4 v[64:65], v85, 1.0 op_sel:[0,1,0]
	v_cvt_scalef32_pk_f32_fp4 v[66:67], v85, 1.0 op_sel:[1,1,0]
	v_pk_fma_f32 v[200:201], v[8:9], v[194:195], v[200:201] op_sel:[0,1,0]
	v_pk_fma_f32 v[202:203], v[10:11], v[194:195], v[202:203] op_sel:[0,1,0]
	v_pk_fma_f32 v[204:205], v[12:13], v[194:195], v[204:205] op_sel:[0,1,0]
	v_pk_fma_f32 v[206:207], v[14:15], v[194:195], v[206:207] op_sel:[0,1,0]
	v_cvt_scalef32_pk_f32_fp4 v[68:69], v86, 1.0
	v_cvt_scalef32_pk_f32_fp4 v[70:71], v86, 1.0 op_sel:[1,0,0]
	v_cvt_scalef32_pk_f32_fp4 v[72:73], v86, 1.0 op_sel:[0,1,0]
	v_cvt_scalef32_pk_f32_fp4 v[74:75], v86, 1.0 op_sel:[1,1,0]
	v_pk_fma_f32 v[208:209], v[16:17], v[194:195], v[208:209] op_sel:[0,1,0]
	v_pk_fma_f32 v[210:211], v[18:19], v[194:195], v[210:211] op_sel:[0,1,0]
	v_pk_fma_f32 v[212:213], v[64:65], v[194:195], v[212:213] op_sel:[0,1,0]
	v_pk_fma_f32 v[214:215], v[66:67], v[194:195], v[214:215] op_sel:[0,1,0]
	v_cvt_scalef32_pk_f32_fp4 v[8:9], v87, 1.0
	v_cvt_scalef32_pk_f32_fp4 v[10:11], v87, 1.0 op_sel:[1,0,0]
	v_cvt_scalef32_pk_f32_fp4 v[12:13], v87, 1.0 op_sel:[0,1,0]
	v_cvt_scalef32_pk_f32_fp4 v[14:15], v87, 1.0 op_sel:[1,1,0]
	v_pk_fma_f32 v[218:219], v[68:69], v[194:195], v[218:219] op_sel:[0,1,0]
	v_pk_fma_f32 v[220:221], v[70:71], v[194:195], v[220:221] op_sel:[0,1,0]
	v_pk_fma_f32 v[222:223], v[72:73], v[194:195], v[222:223] op_sel:[0,1,0]
	v_pk_fma_f32 v[224:225], v[74:75], v[194:195], v[224:225] op_sel:[0,1,0]
	v_pk_fma_f32 v[226:227], v[8:9], v[194:195], v[226:227] op_sel:[0,1,0]
	v_pk_fma_f32 v[228:229], v[10:11], v[194:195], v[228:229] op_sel:[0,1,0]
	v_pk_fma_f32 v[230:231], v[12:13], v[194:195], v[230:231] op_sel:[0,1,0]
	v_pk_fma_f32 v[232:233], v[14:15], v[194:195], v[232:233] op_sel:[0,1,0]
	v_readlane_b32 s44, v155, s45
	s_lshl_b32 s44, s44, 10
	s_add_u32 s46, s92, s44
	s_addc_u32 s47, s93, 0
	global_load_dwordx4 v[84:87], v216, s[46:47]
	ds_read_b128 v[192:195], v131 offset:80
	s_waitcnt vmcnt(15) lgkmcnt(3)
	v_cvt_scalef32_pk_f32_fp4 v[8:9], v88, 1.0
	v_cvt_scalef32_pk_f32_fp4 v[10:11], v88, 1.0 op_sel:[1,0,0]
	v_cvt_scalef32_pk_f32_fp4 v[12:13], v88, 1.0 op_sel:[0,1,0]
	v_cvt_scalef32_pk_f32_fp4 v[14:15], v88, 1.0 op_sel:[1,1,0]
	v_cvt_scalef32_pk_f32_fp4 v[16:17], v89, 1.0
	v_cvt_scalef32_pk_f32_fp4 v[18:19], v89, 1.0 op_sel:[1,0,0]
	v_cvt_scalef32_pk_f32_fp4 v[64:65], v89, 1.0 op_sel:[0,1,0]
	v_cvt_scalef32_pk_f32_fp4 v[66:67], v89, 1.0 op_sel:[1,1,0]
	v_pk_fma_f32 v[200:201], v[8:9], v[240:241], v[200:201] op_sel_hi:[1,0,1]
	v_pk_fma_f32 v[202:203], v[10:11], v[240:241], v[202:203] op_sel_hi:[1,0,1]
	v_pk_fma_f32 v[204:205], v[12:13], v[240:241], v[204:205] op_sel_hi:[1,0,1]
	v_pk_fma_f32 v[206:207], v[14:15], v[240:241], v[206:207] op_sel_hi:[1,0,1]
	v_cvt_scalef32_pk_f32_fp4 v[68:69], v90, 1.0
	v_cvt_scalef32_pk_f32_fp4 v[70:71], v90, 1.0 op_sel:[1,0,0]
	v_cvt_scalef32_pk_f32_fp4 v[72:73], v90, 1.0 op_sel:[0,1,0]
	v_cvt_scalef32_pk_f32_fp4 v[74:75], v90, 1.0 op_sel:[1,1,0]
	v_pk_fma_f32 v[208:209], v[16:17], v[240:241], v[208:209] op_sel_hi:[1,0,1]
	v_pk_fma_f32 v[210:211], v[18:19], v[240:241], v[210:211] op_sel_hi:[1,0,1]
	v_pk_fma_f32 v[212:213], v[64:65], v[240:241], v[212:213] op_sel_hi:[1,0,1]
	v_pk_fma_f32 v[214:215], v[66:67], v[240:241], v[214:215] op_sel_hi:[1,0,1]
	v_cvt_scalef32_pk_f32_fp4 v[8:9], v91, 1.0
	v_cvt_scalef32_pk_f32_fp4 v[10:11], v91, 1.0 op_sel:[1,0,0]
	v_cvt_scalef32_pk_f32_fp4 v[12:13], v91, 1.0 op_sel:[0,1,0]
	v_cvt_scalef32_pk_f32_fp4 v[14:15], v91, 1.0 op_sel:[1,1,0]
	v_pk_fma_f32 v[218:219], v[68:69], v[240:241], v[218:219] op_sel_hi:[1,0,1]
	v_pk_fma_f32 v[220:221], v[70:71], v[240:241], v[220:221] op_sel_hi:[1,0,1]
	v_pk_fma_f32 v[222:223], v[72:73], v[240:241], v[222:223] op_sel_hi:[1,0,1]
	v_pk_fma_f32 v[224:225], v[74:75], v[240:241], v[224:225] op_sel_hi:[1,0,1]
	v_pk_fma_f32 v[226:227], v[8:9], v[240:241], v[226:227] op_sel_hi:[1,0,1]
	v_pk_fma_f32 v[228:229], v[10:11], v[240:241], v[228:229] op_sel_hi:[1,0,1]
	v_pk_fma_f32 v[230:231], v[12:13], v[240:241], v[230:231] op_sel_hi:[1,0,1]
	v_pk_fma_f32 v[232:233], v[14:15], v[240:241], v[232:233] op_sel_hi:[1,0,1]
	s_add_i32 s45, s66, 5
	v_readlane_b32 s44, v154, s45
	s_lshl_b32 s44, s44, 10
	s_add_u32 s46, s92, s44
	s_addc_u32 s47, s93, 0
	global_load_dwordx4 v[88:91], v216, s[46:47]
	s_waitcnt vmcnt(15)
	v_cvt_scalef32_pk_f32_fp4 v[8:9], v92, 1.0
	v_cvt_scalef32_pk_f32_fp4 v[10:11], v92, 1.0 op_sel:[1,0,0]
	v_cvt_scalef32_pk_f32_fp4 v[12:13], v92, 1.0 op_sel:[0,1,0]
	v_cvt_scalef32_pk_f32_fp4 v[14:15], v92, 1.0 op_sel:[1,1,0]
	v_cvt_scalef32_pk_f32_fp4 v[16:17], v93, 1.0
	v_cvt_scalef32_pk_f32_fp4 v[18:19], v93, 1.0 op_sel:[1,0,0]
	v_cvt_scalef32_pk_f32_fp4 v[64:65], v93, 1.0 op_sel:[0,1,0]
	v_cvt_scalef32_pk_f32_fp4 v[66:67], v93, 1.0 op_sel:[1,1,0]
	v_pk_fma_f32 v[200:201], v[8:9], v[240:241], v[200:201] op_sel:[0,1,0]
	v_pk_fma_f32 v[202:203], v[10:11], v[240:241], v[202:203] op_sel:[0,1,0]
	v_pk_fma_f32 v[204:205], v[12:13], v[240:241], v[204:205] op_sel:[0,1,0]
	v_pk_fma_f32 v[206:207], v[14:15], v[240:241], v[206:207] op_sel:[0,1,0]
	v_cvt_scalef32_pk_f32_fp4 v[68:69], v94, 1.0
	v_cvt_scalef32_pk_f32_fp4 v[70:71], v94, 1.0 op_sel:[1,0,0]
	v_cvt_scalef32_pk_f32_fp4 v[72:73], v94, 1.0 op_sel:[0,1,0]
	v_cvt_scalef32_pk_f32_fp4 v[74:75], v94, 1.0 op_sel:[1,1,0]
	v_pk_fma_f32 v[208:209], v[16:17], v[240:241], v[208:209] op_sel:[0,1,0]
	v_pk_fma_f32 v[210:211], v[18:19], v[240:241], v[210:211] op_sel:[0,1,0]
	v_pk_fma_f32 v[212:213], v[64:65], v[240:241], v[212:213] op_sel:[0,1,0]
	v_pk_fma_f32 v[214:215], v[66:67], v[240:241], v[214:215] op_sel:[0,1,0]
	v_cvt_scalef32_pk_f32_fp4 v[8:9], v95, 1.0
	v_cvt_scalef32_pk_f32_fp4 v[10:11], v95, 1.0 op_sel:[1,0,0]
	v_cvt_scalef32_pk_f32_fp4 v[12:13], v95, 1.0 op_sel:[0,1,0]
	v_cvt_scalef32_pk_f32_fp4 v[14:15], v95, 1.0 op_sel:[1,1,0]
	v_pk_fma_f32 v[218:219], v[68:69], v[240:241], v[218:219] op_sel:[0,1,0]
	v_pk_fma_f32 v[220:221], v[70:71], v[240:241], v[220:221] op_sel:[0,1,0]
	v_pk_fma_f32 v[222:223], v[72:73], v[240:241], v[222:223] op_sel:[0,1,0]
	v_pk_fma_f32 v[224:225], v[74:75], v[240:241], v[224:225] op_sel:[0,1,0]
	v_pk_fma_f32 v[226:227], v[8:9], v[240:241], v[226:227] op_sel:[0,1,0]
	v_pk_fma_f32 v[228:229], v[10:11], v[240:241], v[228:229] op_sel:[0,1,0]
	v_pk_fma_f32 v[230:231], v[12:13], v[240:241], v[230:231] op_sel:[0,1,0]
	v_pk_fma_f32 v[232:233], v[14:15], v[240:241], v[232:233] op_sel:[0,1,0]
	v_readlane_b32 s44, v155, s45
	s_lshl_b32 s44, s44, 10
	s_add_u32 s46, s92, s44
	s_addc_u32 s47, s93, 0
	global_load_dwordx4 v[92:95], v216, s[46:47]
	s_waitcnt vmcnt(15)
	v_cvt_scalef32_pk_f32_fp4 v[8:9], v96, 1.0
	v_cvt_scalef32_pk_f32_fp4 v[10:11], v96, 1.0 op_sel:[1,0,0]
	v_cvt_scalef32_pk_f32_fp4 v[12:13], v96, 1.0 op_sel:[0,1,0]
	v_cvt_scalef32_pk_f32_fp4 v[14:15], v96, 1.0 op_sel:[1,1,0]
	v_cvt_scalef32_pk_f32_fp4 v[16:17], v97, 1.0
	v_cvt_scalef32_pk_f32_fp4 v[18:19], v97, 1.0 op_sel:[1,0,0]
	v_cvt_scalef32_pk_f32_fp4 v[64:65], v97, 1.0 op_sel:[0,1,0]
	v_cvt_scalef32_pk_f32_fp4 v[66:67], v97, 1.0 op_sel:[1,1,0]
	v_pk_fma_f32 v[200:201], v[8:9], v[242:243], v[200:201] op_sel_hi:[1,0,1]
	v_pk_fma_f32 v[202:203], v[10:11], v[242:243], v[202:203] op_sel_hi:[1,0,1]
	v_pk_fma_f32 v[204:205], v[12:13], v[242:243], v[204:205] op_sel_hi:[1,0,1]
	v_pk_fma_f32 v[206:207], v[14:15], v[242:243], v[206:207] op_sel_hi:[1,0,1]
	v_cvt_scalef32_pk_f32_fp4 v[68:69], v98, 1.0
	v_cvt_scalef32_pk_f32_fp4 v[70:71], v98, 1.0 op_sel:[1,0,0]
	v_cvt_scalef32_pk_f32_fp4 v[72:73], v98, 1.0 op_sel:[0,1,0]
	v_cvt_scalef32_pk_f32_fp4 v[74:75], v98, 1.0 op_sel:[1,1,0]
	v_pk_fma_f32 v[208:209], v[16:17], v[242:243], v[208:209] op_sel_hi:[1,0,1]
	v_pk_fma_f32 v[210:211], v[18:19], v[242:243], v[210:211] op_sel_hi:[1,0,1]
	v_pk_fma_f32 v[212:213], v[64:65], v[242:243], v[212:213] op_sel_hi:[1,0,1]
	v_pk_fma_f32 v[214:215], v[66:67], v[242:243], v[214:215] op_sel_hi:[1,0,1]
	v_cvt_scalef32_pk_f32_fp4 v[8:9], v99, 1.0
	v_cvt_scalef32_pk_f32_fp4 v[10:11], v99, 1.0 op_sel:[1,0,0]
	v_cvt_scalef32_pk_f32_fp4 v[12:13], v99, 1.0 op_sel:[0,1,0]
	v_cvt_scalef32_pk_f32_fp4 v[14:15], v99, 1.0 op_sel:[1,1,0]
	v_pk_fma_f32 v[218:219], v[68:69], v[242:243], v[218:219] op_sel_hi:[1,0,1]
	v_pk_fma_f32 v[220:221], v[70:71], v[242:243], v[220:221] op_sel_hi:[1,0,1]
	v_pk_fma_f32 v[222:223], v[72:73], v[242:243], v[222:223] op_sel_hi:[1,0,1]
	v_pk_fma_f32 v[224:225], v[74:75], v[242:243], v[224:225] op_sel_hi:[1,0,1]
	v_pk_fma_f32 v[226:227], v[8:9], v[242:243], v[226:227] op_sel_hi:[1,0,1]
	v_pk_fma_f32 v[228:229], v[10:11], v[242:243], v[228:229] op_sel_hi:[1,0,1]
	v_pk_fma_f32 v[230:231], v[12:13], v[242:243], v[230:231] op_sel_hi:[1,0,1]
	v_pk_fma_f32 v[232:233], v[14:15], v[242:243], v[232:233] op_sel_hi:[1,0,1]
	s_add_i32 s45, s66, 6
	v_readlane_b32 s44, v154, s45
	s_lshl_b32 s44, s44, 10
	s_add_u32 s46, s92, s44
	s_addc_u32 s47, s93, 0
	global_load_dwordx4 v[96:99], v216, s[46:47]
	s_waitcnt vmcnt(15)
	v_cvt_scalef32_pk_f32_fp4 v[8:9], v100, 1.0
	v_cvt_scalef32_pk_f32_fp4 v[10:11], v100, 1.0 op_sel:[1,0,0]
	v_cvt_scalef32_pk_f32_fp4 v[12:13], v100, 1.0 op_sel:[0,1,0]
	v_cvt_scalef32_pk_f32_fp4 v[14:15], v100, 1.0 op_sel:[1,1,0]
	v_cvt_scalef32_pk_f32_fp4 v[16:17], v101, 1.0
	v_cvt_scalef32_pk_f32_fp4 v[18:19], v101, 1.0 op_sel:[1,0,0]
	v_cvt_scalef32_pk_f32_fp4 v[64:65], v101, 1.0 op_sel:[0,1,0]
	v_cvt_scalef32_pk_f32_fp4 v[66:67], v101, 1.0 op_sel:[1,1,0]
	v_pk_fma_f32 v[200:201], v[8:9], v[242:243], v[200:201] op_sel:[0,1,0]
	v_pk_fma_f32 v[202:203], v[10:11], v[242:243], v[202:203] op_sel:[0,1,0]
	v_pk_fma_f32 v[204:205], v[12:13], v[242:243], v[204:205] op_sel:[0,1,0]
	v_pk_fma_f32 v[206:207], v[14:15], v[242:243], v[206:207] op_sel:[0,1,0]
	v_cvt_scalef32_pk_f32_fp4 v[68:69], v102, 1.0
	v_cvt_scalef32_pk_f32_fp4 v[70:71], v102, 1.0 op_sel:[1,0,0]
	v_cvt_scalef32_pk_f32_fp4 v[72:73], v102, 1.0 op_sel:[0,1,0]
	v_cvt_scalef32_pk_f32_fp4 v[74:75], v102, 1.0 op_sel:[1,1,0]
	v_pk_fma_f32 v[208:209], v[16:17], v[242:243], v[208:209] op_sel:[0,1,0]
	v_pk_fma_f32 v[210:211], v[18:19], v[242:243], v[210:211] op_sel:[0,1,0]
	v_pk_fma_f32 v[212:213], v[64:65], v[242:243], v[212:213] op_sel:[0,1,0]
	v_pk_fma_f32 v[214:215], v[66:67], v[242:243], v[214:215] op_sel:[0,1,0]
	v_cvt_scalef32_pk_f32_fp4 v[8:9], v103, 1.0
	v_cvt_scalef32_pk_f32_fp4 v[10:11], v103, 1.0 op_sel:[1,0,0]
	v_cvt_scalef32_pk_f32_fp4 v[12:13], v103, 1.0 op_sel:[0,1,0]
	v_cvt_scalef32_pk_f32_fp4 v[14:15], v103, 1.0 op_sel:[1,1,0]
	v_pk_fma_f32 v[218:219], v[68:69], v[242:243], v[218:219] op_sel:[0,1,0]
	v_pk_fma_f32 v[220:221], v[70:71], v[242:243], v[220:221] op_sel:[0,1,0]
	v_pk_fma_f32 v[222:223], v[72:73], v[242:243], v[222:223] op_sel:[0,1,0]
	v_pk_fma_f32 v[224:225], v[74:75], v[242:243], v[224:225] op_sel:[0,1,0]
	v_pk_fma_f32 v[226:227], v[8:9], v[242:243], v[226:227] op_sel:[0,1,0]
	v_pk_fma_f32 v[228:229], v[10:11], v[242:243], v[228:229] op_sel:[0,1,0]
	v_pk_fma_f32 v[230:231], v[12:13], v[242:243], v[230:231] op_sel:[0,1,0]
	v_pk_fma_f32 v[232:233], v[14:15], v[242:243], v[232:233] op_sel:[0,1,0]
	v_readlane_b32 s44, v155, s45
	s_lshl_b32 s44, s44, 10
	s_add_u32 s46, s92, s44
	s_addc_u32 s47, s93, 0
	global_load_dwordx4 v[100:103], v216, s[46:47]
	ds_read_b128 v[240:243], v131 offset:96
	s_waitcnt vmcnt(15) lgkmcnt(3)
	v_cvt_scalef32_pk_f32_fp4 v[8:9], v172, 1.0
	v_cvt_scalef32_pk_f32_fp4 v[10:11], v172, 1.0 op_sel:[1,0,0]
	v_cvt_scalef32_pk_f32_fp4 v[12:13], v172, 1.0 op_sel:[0,1,0]
	v_cvt_scalef32_pk_f32_fp4 v[14:15], v172, 1.0 op_sel:[1,1,0]
	v_cvt_scalef32_pk_f32_fp4 v[16:17], v173, 1.0
	v_cvt_scalef32_pk_f32_fp4 v[18:19], v173, 1.0 op_sel:[1,0,0]
	v_cvt_scalef32_pk_f32_fp4 v[64:65], v173, 1.0 op_sel:[0,1,0]
	v_cvt_scalef32_pk_f32_fp4 v[66:67], v173, 1.0 op_sel:[1,1,0]
	v_pk_fma_f32 v[200:201], v[8:9], v[244:245], v[200:201] op_sel_hi:[1,0,1]
	v_pk_fma_f32 v[202:203], v[10:11], v[244:245], v[202:203] op_sel_hi:[1,0,1]
	v_pk_fma_f32 v[204:205], v[12:13], v[244:245], v[204:205] op_sel_hi:[1,0,1]
	v_pk_fma_f32 v[206:207], v[14:15], v[244:245], v[206:207] op_sel_hi:[1,0,1]
	v_cvt_scalef32_pk_f32_fp4 v[68:69], v174, 1.0
	v_cvt_scalef32_pk_f32_fp4 v[70:71], v174, 1.0 op_sel:[1,0,0]
	v_cvt_scalef32_pk_f32_fp4 v[72:73], v174, 1.0 op_sel:[0,1,0]
	v_cvt_scalef32_pk_f32_fp4 v[74:75], v174, 1.0 op_sel:[1,1,0]
	v_pk_fma_f32 v[208:209], v[16:17], v[244:245], v[208:209] op_sel_hi:[1,0,1]
	v_pk_fma_f32 v[210:211], v[18:19], v[244:245], v[210:211] op_sel_hi:[1,0,1]
	v_pk_fma_f32 v[212:213], v[64:65], v[244:245], v[212:213] op_sel_hi:[1,0,1]
	v_pk_fma_f32 v[214:215], v[66:67], v[244:245], v[214:215] op_sel_hi:[1,0,1]
	v_cvt_scalef32_pk_f32_fp4 v[8:9], v175, 1.0
	v_cvt_scalef32_pk_f32_fp4 v[10:11], v175, 1.0 op_sel:[1,0,0]
	v_cvt_scalef32_pk_f32_fp4 v[12:13], v175, 1.0 op_sel:[0,1,0]
	v_cvt_scalef32_pk_f32_fp4 v[14:15], v175, 1.0 op_sel:[1,1,0]
	v_pk_fma_f32 v[218:219], v[68:69], v[244:245], v[218:219] op_sel_hi:[1,0,1]
	v_pk_fma_f32 v[220:221], v[70:71], v[244:245], v[220:221] op_sel_hi:[1,0,1]
	v_pk_fma_f32 v[222:223], v[72:73], v[244:245], v[222:223] op_sel_hi:[1,0,1]
	v_pk_fma_f32 v[224:225], v[74:75], v[244:245], v[224:225] op_sel_hi:[1,0,1]
	v_pk_fma_f32 v[226:227], v[8:9], v[244:245], v[226:227] op_sel_hi:[1,0,1]
	v_pk_fma_f32 v[228:229], v[10:11], v[244:245], v[228:229] op_sel_hi:[1,0,1]
	v_pk_fma_f32 v[230:231], v[12:13], v[244:245], v[230:231] op_sel_hi:[1,0,1]
	v_pk_fma_f32 v[232:233], v[14:15], v[244:245], v[232:233] op_sel_hi:[1,0,1]
	s_add_i32 s45, s66, 7
	v_readlane_b32 s44, v154, s45
	s_lshl_b32 s44, s44, 10
	s_add_u32 s46, s92, s44
	s_addc_u32 s47, s93, 0
	global_load_dwordx4 v[172:175], v216, s[46:47]
	s_waitcnt vmcnt(15)
	v_cvt_scalef32_pk_f32_fp4 v[8:9], v176, 1.0
	v_cvt_scalef32_pk_f32_fp4 v[10:11], v176, 1.0 op_sel:[1,0,0]
	v_cvt_scalef32_pk_f32_fp4 v[12:13], v176, 1.0 op_sel:[0,1,0]
	v_cvt_scalef32_pk_f32_fp4 v[14:15], v176, 1.0 op_sel:[1,1,0]
	v_cvt_scalef32_pk_f32_fp4 v[16:17], v177, 1.0
	v_cvt_scalef32_pk_f32_fp4 v[18:19], v177, 1.0 op_sel:[1,0,0]
	v_cvt_scalef32_pk_f32_fp4 v[64:65], v177, 1.0 op_sel:[0,1,0]
	v_cvt_scalef32_pk_f32_fp4 v[66:67], v177, 1.0 op_sel:[1,1,0]
	v_pk_fma_f32 v[200:201], v[8:9], v[244:245], v[200:201] op_sel:[0,1,0]
	v_pk_fma_f32 v[202:203], v[10:11], v[244:245], v[202:203] op_sel:[0,1,0]
	v_pk_fma_f32 v[204:205], v[12:13], v[244:245], v[204:205] op_sel:[0,1,0]
	v_pk_fma_f32 v[206:207], v[14:15], v[244:245], v[206:207] op_sel:[0,1,0]
	v_cvt_scalef32_pk_f32_fp4 v[68:69], v178, 1.0
	v_cvt_scalef32_pk_f32_fp4 v[70:71], v178, 1.0 op_sel:[1,0,0]
	v_cvt_scalef32_pk_f32_fp4 v[72:73], v178, 1.0 op_sel:[0,1,0]
	v_cvt_scalef32_pk_f32_fp4 v[74:75], v178, 1.0 op_sel:[1,1,0]
	v_pk_fma_f32 v[208:209], v[16:17], v[244:245], v[208:209] op_sel:[0,1,0]
	v_pk_fma_f32 v[210:211], v[18:19], v[244:245], v[210:211] op_sel:[0,1,0]
	v_pk_fma_f32 v[212:213], v[64:65], v[244:245], v[212:213] op_sel:[0,1,0]
	v_pk_fma_f32 v[214:215], v[66:67], v[244:245], v[214:215] op_sel:[0,1,0]
	v_cvt_scalef32_pk_f32_fp4 v[8:9], v179, 1.0
	v_cvt_scalef32_pk_f32_fp4 v[10:11], v179, 1.0 op_sel:[1,0,0]
	v_cvt_scalef32_pk_f32_fp4 v[12:13], v179, 1.0 op_sel:[0,1,0]
	v_cvt_scalef32_pk_f32_fp4 v[14:15], v179, 1.0 op_sel:[1,1,0]
	v_pk_fma_f32 v[218:219], v[68:69], v[244:245], v[218:219] op_sel:[0,1,0]
	v_pk_fma_f32 v[220:221], v[70:71], v[244:245], v[220:221] op_sel:[0,1,0]
	v_pk_fma_f32 v[222:223], v[72:73], v[244:245], v[222:223] op_sel:[0,1,0]
	v_pk_fma_f32 v[224:225], v[74:75], v[244:245], v[224:225] op_sel:[0,1,0]
	v_pk_fma_f32 v[226:227], v[8:9], v[244:245], v[226:227] op_sel:[0,1,0]
	v_pk_fma_f32 v[228:229], v[10:11], v[244:245], v[228:229] op_sel:[0,1,0]
	v_pk_fma_f32 v[230:231], v[12:13], v[244:245], v[230:231] op_sel:[0,1,0]
	v_pk_fma_f32 v[232:233], v[14:15], v[244:245], v[232:233] op_sel:[0,1,0]
	v_readlane_b32 s44, v155, s45
	s_lshl_b32 s44, s44, 10
	s_add_u32 s46, s92, s44
	s_addc_u32 s47, s93, 0
	global_load_dwordx4 v[176:179], v216, s[46:47]
	s_waitcnt vmcnt(15)
	v_cvt_scalef32_pk_f32_fp4 v[8:9], v180, 1.0
	v_cvt_scalef32_pk_f32_fp4 v[10:11], v180, 1.0 op_sel:[1,0,0]
	v_cvt_scalef32_pk_f32_fp4 v[12:13], v180, 1.0 op_sel:[0,1,0]
	v_cvt_scalef32_pk_f32_fp4 v[14:15], v180, 1.0 op_sel:[1,1,0]
	v_cvt_scalef32_pk_f32_fp4 v[16:17], v181, 1.0
	v_cvt_scalef32_pk_f32_fp4 v[18:19], v181, 1.0 op_sel:[1,0,0]
	v_cvt_scalef32_pk_f32_fp4 v[64:65], v181, 1.0 op_sel:[0,1,0]
	v_cvt_scalef32_pk_f32_fp4 v[66:67], v181, 1.0 op_sel:[1,1,0]
	v_pk_fma_f32 v[200:201], v[8:9], v[246:247], v[200:201] op_sel_hi:[1,0,1]
	v_pk_fma_f32 v[202:203], v[10:11], v[246:247], v[202:203] op_sel_hi:[1,0,1]
	v_pk_fma_f32 v[204:205], v[12:13], v[246:247], v[204:205] op_sel_hi:[1,0,1]
	v_pk_fma_f32 v[206:207], v[14:15], v[246:247], v[206:207] op_sel_hi:[1,0,1]
	v_cvt_scalef32_pk_f32_fp4 v[68:69], v182, 1.0
	v_cvt_scalef32_pk_f32_fp4 v[70:71], v182, 1.0 op_sel:[1,0,0]
	v_cvt_scalef32_pk_f32_fp4 v[72:73], v182, 1.0 op_sel:[0,1,0]
	v_cvt_scalef32_pk_f32_fp4 v[74:75], v182, 1.0 op_sel:[1,1,0]
	v_pk_fma_f32 v[208:209], v[16:17], v[246:247], v[208:209] op_sel_hi:[1,0,1]
	v_pk_fma_f32 v[210:211], v[18:19], v[246:247], v[210:211] op_sel_hi:[1,0,1]
	v_pk_fma_f32 v[212:213], v[64:65], v[246:247], v[212:213] op_sel_hi:[1,0,1]
	v_pk_fma_f32 v[214:215], v[66:67], v[246:247], v[214:215] op_sel_hi:[1,0,1]
	v_cvt_scalef32_pk_f32_fp4 v[8:9], v183, 1.0
	v_cvt_scalef32_pk_f32_fp4 v[10:11], v183, 1.0 op_sel:[1,0,0]
	v_cvt_scalef32_pk_f32_fp4 v[12:13], v183, 1.0 op_sel:[0,1,0]
	v_cvt_scalef32_pk_f32_fp4 v[14:15], v183, 1.0 op_sel:[1,1,0]
	v_pk_fma_f32 v[218:219], v[68:69], v[246:247], v[218:219] op_sel_hi:[1,0,1]
	v_pk_fma_f32 v[220:221], v[70:71], v[246:247], v[220:221] op_sel_hi:[1,0,1]
	v_pk_fma_f32 v[222:223], v[72:73], v[246:247], v[222:223] op_sel_hi:[1,0,1]
	v_pk_fma_f32 v[224:225], v[74:75], v[246:247], v[224:225] op_sel_hi:[1,0,1]
	v_pk_fma_f32 v[226:227], v[8:9], v[246:247], v[226:227] op_sel_hi:[1,0,1]
	v_pk_fma_f32 v[228:229], v[10:11], v[246:247], v[228:229] op_sel_hi:[1,0,1]
	v_pk_fma_f32 v[230:231], v[12:13], v[246:247], v[230:231] op_sel_hi:[1,0,1]
	v_pk_fma_f32 v[232:233], v[14:15], v[246:247], v[232:233] op_sel_hi:[1,0,1]
	s_add_i32 s45, s66, 8
	v_readlane_b32 s44, v154, s45
	s_lshl_b32 s44, s44, 10
	s_add_u32 s46, s92, s44
	s_addc_u32 s47, s93, 0
	global_load_dwordx4 v[180:183], v216, s[46:47]
	s_waitcnt vmcnt(15)
	v_cvt_scalef32_pk_f32_fp4 v[8:9], v184, 1.0
	v_cvt_scalef32_pk_f32_fp4 v[10:11], v184, 1.0 op_sel:[1,0,0]
	v_cvt_scalef32_pk_f32_fp4 v[12:13], v184, 1.0 op_sel:[0,1,0]
	v_cvt_scalef32_pk_f32_fp4 v[14:15], v184, 1.0 op_sel:[1,1,0]
	v_cvt_scalef32_pk_f32_fp4 v[16:17], v185, 1.0
	v_cvt_scalef32_pk_f32_fp4 v[18:19], v185, 1.0 op_sel:[1,0,0]
	v_cvt_scalef32_pk_f32_fp4 v[64:65], v185, 1.0 op_sel:[0,1,0]
	v_cvt_scalef32_pk_f32_fp4 v[66:67], v185, 1.0 op_sel:[1,1,0]
	v_pk_fma_f32 v[200:201], v[8:9], v[246:247], v[200:201] op_sel:[0,1,0]
	v_pk_fma_f32 v[202:203], v[10:11], v[246:247], v[202:203] op_sel:[0,1,0]
	v_pk_fma_f32 v[204:205], v[12:13], v[246:247], v[204:205] op_sel:[0,1,0]
	v_pk_fma_f32 v[206:207], v[14:15], v[246:247], v[206:207] op_sel:[0,1,0]
	v_cvt_scalef32_pk_f32_fp4 v[68:69], v186, 1.0
	v_cvt_scalef32_pk_f32_fp4 v[70:71], v186, 1.0 op_sel:[1,0,0]
	v_cvt_scalef32_pk_f32_fp4 v[72:73], v186, 1.0 op_sel:[0,1,0]
	v_cvt_scalef32_pk_f32_fp4 v[74:75], v186, 1.0 op_sel:[1,1,0]
	v_pk_fma_f32 v[208:209], v[16:17], v[246:247], v[208:209] op_sel:[0,1,0]
	v_pk_fma_f32 v[210:211], v[18:19], v[246:247], v[210:211] op_sel:[0,1,0]
	v_pk_fma_f32 v[212:213], v[64:65], v[246:247], v[212:213] op_sel:[0,1,0]
	v_pk_fma_f32 v[214:215], v[66:67], v[246:247], v[214:215] op_sel:[0,1,0]
	v_cvt_scalef32_pk_f32_fp4 v[8:9], v187, 1.0
	v_cvt_scalef32_pk_f32_fp4 v[10:11], v187, 1.0 op_sel:[1,0,0]
	v_cvt_scalef32_pk_f32_fp4 v[12:13], v187, 1.0 op_sel:[0,1,0]
	v_cvt_scalef32_pk_f32_fp4 v[14:15], v187, 1.0 op_sel:[1,1,0]
	v_pk_fma_f32 v[218:219], v[68:69], v[246:247], v[218:219] op_sel:[0,1,0]
	v_pk_fma_f32 v[220:221], v[70:71], v[246:247], v[220:221] op_sel:[0,1,0]
	v_pk_fma_f32 v[222:223], v[72:73], v[246:247], v[222:223] op_sel:[0,1,0]
	v_pk_fma_f32 v[224:225], v[74:75], v[246:247], v[224:225] op_sel:[0,1,0]
	v_pk_fma_f32 v[226:227], v[8:9], v[246:247], v[226:227] op_sel:[0,1,0]
	v_pk_fma_f32 v[228:229], v[10:11], v[246:247], v[228:229] op_sel:[0,1,0]
	v_pk_fma_f32 v[230:231], v[12:13], v[246:247], v[230:231] op_sel:[0,1,0]
	v_pk_fma_f32 v[232:233], v[14:15], v[246:247], v[232:233] op_sel:[0,1,0]
	v_readlane_b32 s44, v155, s45
	s_lshl_b32 s44, s44, 10
	s_add_u32 s46, s92, s44
	s_addc_u32 s47, s93, 0
	global_load_dwordx4 v[184:187], v216, s[46:47]
	ds_read_b128 v[244:247], v131 offset:112
	s_add_i32 s65, s65, 16
	s_add_i32 s66, s66, 8
	v_add_u32_e32 v131, 64, v131
	v_add_u32_e32 v198, 64, v198
	s_cmpk_lt_u32 s65, 0x70
	s_cbranch_scc1 .Lp10vp_loop
	s_waitcnt vmcnt(0) lgkmcnt(0)
	s_branch .Lp10v_epi
.Lp10v_odd:
	v_mov_b32_e32 v24, v200
	v_mov_b32_e32 v25, v201
	v_mov_b32_e32 v26, v202
	v_mov_b32_e32 v27, v203
	v_mov_b32_e32 v40, v204
	v_mov_b32_e32 v41, v205
	v_mov_b32_e32 v42, v206
	v_mov_b32_e32 v43, v207
	v_mov_b32_e32 v36, v208
	v_mov_b32_e32 v37, v209
	v_mov_b32_e32 v38, v210
	v_mov_b32_e32 v39, v211
	v_mov_b32_e32 v4, v212
	v_mov_b32_e32 v5, v213
	v_mov_b32_e32 v6, v214
	v_mov_b32_e32 v7, v215
	v_mov_b32_e32 v32, v218
	v_mov_b32_e32 v33, v219
	v_mov_b32_e32 v34, v220
	v_mov_b32_e32 v35, v221
	v_mov_b32_e32 v28, v222
	v_mov_b32_e32 v29, v223
	v_mov_b32_e32 v30, v224
	v_mov_b32_e32 v31, v225
	v_mov_b32_e32 v20, v226
	v_mov_b32_e32 v21, v227
	v_mov_b32_e32 v22, v228
	v_mov_b32_e32 v23, v229
	v_mov_b32_e32 v0, v230
	v_mov_b32_e32 v1, v231
	v_mov_b32_e32 v2, v232
	v_mov_b32_e32 v3, v233
.Lp10v_epi:
	s_waitcnt lgkmcnt(0)
	ds_write_b128 v166, v[24:27]
	ds_write_b128 v166, v[40:43] offset:16
	ds_write_b128 v166, v[36:39] offset:32
	ds_write_b128 v166, v[4:7] offset:48
	ds_write_b128 v166, v[32:35] offset:64
	ds_write_b128 v166, v[28:31] offset:80
	ds_write_b128 v166, v[20:23] offset:96
	ds_write_b128 v166, v[0:3] offset:112
	v_add_u32_e32 v1, 0xffffc000, v152
	v_lshrrev_b32_e32 v1, 3, v1
	v_ashrrev_i32_e32 v0, 11, v152
	v_add_u32_e32 v1, 8, v1
	v_cmp_gt_i32_e32 vcc, s61, v152
	v_ashrrev_i32_e32 v153, 31, v152
	s_waitcnt lgkmcnt(0)
	v_mov_b32_e32 v137, v107
	v_cndmask_b32_e32 v2, v1, v0, vcc
	v_mov_b64_e32 v[0:1], s[92:93]
	v_mad_i64_i32 v[0:1], s[44:45], v2, s62, v[0:1]
	v_lshlrev_b64 v[2:3], 12, v[152:153]
	v_lshl_add_u64 v[12:13], v[126:127], 0, v[2:3]
	v_lshl_add_u64 v[16:17], v[0:1], 0, s[40:41]
	v_lshlrev_b64 v[4:5], 13, v[152:153]
	v_lshl_add_u64 v[18:19], s[90:91], 0, v[4:5]
	v_mov_b32_e32 v139, v107
	v_mov_b32_e32 v141, v107
	v_mov_b32_e32 v143, v107
	v_mov_b32_e32 v145, v107
	v_mov_b32_e32 v147, v107
	v_mov_b32_e32 v149, v107
	v_mov_b32_e32 v151, v107
	global_load_dwordx2 v[44:45], v[12:13], off
	v_lshl_add_u64 v[0:1], v[16:17], 0, v[136:137]
	global_load_dwordx4 v[60:63], v[0:1], off
	global_load_dwordx2 v[46:47], v[12:13], off offset:512
	v_lshl_add_u64 v[0:1], v[16:17], 0, v[138:139]
	global_load_dwordx4 v[76:79], v[0:1], off
	global_load_dwordx2 v[48:49], v[12:13], off offset:1024
	v_lshl_add_u64 v[0:1], v[16:17], 0, v[140:141]
	global_load_dwordx4 v[80:83], v[0:1], off
	global_load_dwordx2 v[50:51], v[12:13], off offset:1536
	v_lshl_add_u64 v[0:1], v[16:17], 0, v[142:143]
	global_load_dwordx4 v[84:87], v[0:1], off
	global_load_dwordx2 v[52:53], v[12:13], off offset:2048
	v_lshl_add_u64 v[0:1], v[16:17], 0, v[144:145]
	global_load_dwordx4 v[88:91], v[0:1], off
	global_load_dwordx2 v[54:55], v[12:13], off offset:2560
	v_lshl_add_u64 v[0:1], v[16:17], 0, v[146:147]
	global_load_dwordx4 v[92:95], v[0:1], off
	global_load_dwordx2 v[56:57], v[12:13], off offset:3072
	v_lshl_add_u64 v[0:1], v[16:17], 0, v[148:149]
	global_load_dwordx4 v[96:99], v[0:1], off
	global_load_dwordx2 v[58:59], v[12:13], off offset:3584
	v_lshl_add_u64 v[0:1], v[16:17], 0, v[150:151]
	global_load_dwordx4 v[100:103], v[0:1], off
	ds_read_b128 v[172:175], v167
	ds_read_b128 v[176:179], v167 offset:1152
	ds_read_b128 v[180:183], v167 offset:2304
	ds_read_b128 v[184:187], v167 offset:3456
	ds_read_b128 v[188:191], v167 offset:4608
	ds_read_b128 v[192:195], v167 offset:5760
	ds_read_b128 v[240:243], v167 offset:6912
	ds_read_b128 v[244:247], v167 offset:8064
	v_lshl_add_u64 v[20:21], v[18:19], 0, v[136:137]
	v_lshl_add_u64 v[22:23], v[18:19], 0, v[144:145]
	s_waitcnt vmcnt(14) lgkmcnt(7)
	v_lshlrev_b32_e32 v0, 16, v44
	v_and_b32_e32 v1, 0xffff0000, v44
	v_lshlrev_b32_e32 v2, 16, v45
	v_and_b32_e32 v3, 0xffff0000, v45
	v_pk_fma_f32 v[60:61], v[172:173], v[60:61], v[0:1]
	v_pk_fma_f32 v[62:63], v[174:175], v[62:63], v[2:3]
	global_store_dwordx4 v[20:21], v[60:63], off
	s_waitcnt vmcnt(13) lgkmcnt(6)
	v_lshlrev_b32_e32 v0, 16, v46
	v_and_b32_e32 v1, 0xffff0000, v46
	v_lshlrev_b32_e32 v2, 16, v47
	v_and_b32_e32 v3, 0xffff0000, v47
	v_pk_fma_f32 v[76:77], v[176:177], v[76:77], v[0:1]
	v_pk_fma_f32 v[78:79], v[178:179], v[78:79], v[2:3]
	global_store_dwordx4 v[20:21], v[76:79], off offset:1024
	s_waitcnt vmcnt(12) lgkmcnt(5)
	v_lshlrev_b32_e32 v0, 16, v48
	v_and_b32_e32 v1, 0xffff0000, v48
	v_lshlrev_b32_e32 v2, 16, v49
	v_and_b32_e32 v3, 0xffff0000, v49
	v_pk_fma_f32 v[80:81], v[180:181], v[80:81], v[0:1]
	v_pk_fma_f32 v[82:83], v[182:183], v[82:83], v[2:3]
	global_store_dwordx4 v[20:21], v[80:83], off offset:2048
	s_waitcnt vmcnt(11) lgkmcnt(4)
	v_lshlrev_b32_e32 v0, 16, v50
	v_and_b32_e32 v1, 0xffff0000, v50
	v_lshlrev_b32_e32 v2, 16, v51
	v_and_b32_e32 v3, 0xffff0000, v51
	v_pk_fma_f32 v[84:85], v[184:185], v[84:85], v[0:1]
	v_pk_fma_f32 v[86:87], v[186:187], v[86:87], v[2:3]
	global_store_dwordx4 v[20:21], v[84:87], off offset:3072
	s_waitcnt vmcnt(10) lgkmcnt(3)
	v_lshlrev_b32_e32 v0, 16, v52
	v_and_b32_e32 v1, 0xffff0000, v52
	v_lshlrev_b32_e32 v2, 16, v53
	v_and_b32_e32 v3, 0xffff0000, v53
	v_pk_fma_f32 v[88:89], v[188:189], v[88:89], v[0:1]
	v_pk_fma_f32 v[90:91], v[190:191], v[90:91], v[2:3]
	global_store_dwordx4 v[22:23], v[88:91], off
	s_waitcnt vmcnt(9) lgkmcnt(2)
	v_lshlrev_b32_e32 v0, 16, v54
	v_and_b32_e32 v1, 0xffff0000, v54
	v_lshlrev_b32_e32 v2, 16, v55
	v_and_b32_e32 v3, 0xffff0000, v55
	v_pk_fma_f32 v[92:93], v[192:193], v[92:93], v[0:1]
	v_pk_fma_f32 v[94:95], v[194:195], v[94:95], v[2:3]
	global_store_dwordx4 v[22:23], v[92:95], off offset:1024
	s_waitcnt vmcnt(8) lgkmcnt(1)
	v_lshlrev_b32_e32 v0, 16, v56
	v_and_b32_e32 v1, 0xffff0000, v56
	v_lshlrev_b32_e32 v2, 16, v57
	v_and_b32_e32 v3, 0xffff0000, v57
	v_pk_fma_f32 v[96:97], v[240:241], v[96:97], v[0:1]
	v_pk_fma_f32 v[98:99], v[242:243], v[98:99], v[2:3]
	global_store_dwordx4 v[22:23], v[96:99], off offset:2048
	s_waitcnt vmcnt(7) lgkmcnt(0)
	v_lshlrev_b32_e32 v0, 16, v58
	v_and_b32_e32 v1, 0xffff0000, v58
	v_lshlrev_b32_e32 v2, 16, v59
	v_and_b32_e32 v3, 0xffff0000, v59
	v_pk_fma_f32 v[100:101], v[244:245], v[100:101], v[0:1]
	v_pk_fma_f32 v[102:103], v[246:247], v[102:103], v[2:3]
	global_store_dwordx4 v[22:23], v[100:103], off offset:3072
	s_waitcnt lgkmcnt(0)
	s_branch .LBB0_2054
